# v20 + L2 prefetch: one plain load per wave per K-tile touching this workgroup's share (12 lines) of the A/B tiles two K-tiles ahead of the LDS-DMA stream; counted waits re-derived
# baseline (speedup 1.0000x reference)
; #define PG8_STAGE(bufoff, gbase, voff) do { _Pragma("unroll") for (int _i = 0; _i < 2; ++_i) \
;         __builtin_amdgcn_global_load_lds((const unsigned*)((const char*)(gbase) + (voff)[_i]), (PG8_LAS unsigned*)(lds + (bufoff) + ldsw + _i * 8192), 16, 0, 0); } while (0)
; #define PG8_LDA(dst, b, h) do { _Pragma("unroll") for (int m = 0; m < 4; ++m) _Pragma("unroll") for (int k = 0; k < 2; ++k) dst[m][k] = *(const PG8_LAS bf16x8*)(lds + PG8_SA(b, h) + aoff + m * 2048 + k * 1024); } while (0)
; #define PG8_LDB(dst, b, h) do { _Pragma("unroll") for (int n = 0; n < 2; ++n) _Pragma("unroll") for (int k = 0; k < 2; ++k) dst[n][k] = *(const PG8_LAS bf16x8*)(lds + PG8_SB(b, h) + boff + n * 2048 + k * 1024); } while (0)
; #define PG8_MMA(ai, bj, At, Bt) do { __builtin_amdgcn_s_setprio(1); _Pragma("unroll") for (int m = 0; m < 4; ++m) _Pragma("unroll") for (int n = 0; n < 2; ++n) _Pragma("unroll") for (int k = 0; k < 2; ++k) \
;         acc[ai][bj][m][n] = __builtin_amdgcn_mfma_f32_16x16x32_bf16(Bt[n][k], At[m][k], acc[ai][bj][m][n], 0, 0, 0); __builtin_amdgcn_s_setprio(0); } while (0)
; #define PG8_WAIT_V(n) asm volatile("s_waitcnt vmcnt(" #n ")" ::: "memory")
; #define PG8_BAR __builtin_amdgcn_s_barrier()
; template <class Epi, class Sched, bool ALIGN_EPI = false, bool SP2 = false>
; __device__ __forceinline__ void gemm_phase(PG8_LAS unsigned char* lds, const Gemm g, const Sched& S, const Epi& E) {
;     ...
;     for (;;) {
;         const bool has_next = S.next(ui + 1, nxt);
;         const char* nA = has_next ? (const char*)g.A + (size_t)nxt.pm * tA + (size_t)nxt.pn * pnA : cA; const char* nB = has_next ? (const char*)g.Bt + (size_t)nxt.pn * tB : cB;
; #pragma nounroll
;         for (int t = 0; t < nt; t += 2) {
;             const bool last = (t == nt - 2);
;             const char* a1 = cA + (size_t)(t + 1) * kstep;
;             const char* a2 = last ? nA : cA + (size_t)(t + 2) * kstep; const char* b2 = last ? nB : cB + (size_t)(t + 2) * kstep;
;             const char* a3 = a2 + kstep; const char* b3 = b2 + kstep;
;             if (last && has_next) S.a_ready(nxt);
;             if constexpr (SP2) {
;             PG8_LDB(B0, 0, 0); PG8_LDB(B1, 0, 1); PG8_SCHED; PG8_LDA(At, 0, 0); PG8_STAGE(PG8_SA(1, 1), a1 + hA, voffA);
;             PG8_WAIT_V(8); PG8_WAIT_L(0); PG8_BAR; PG8_MMA(0, 0, At, B0); PG8_MMA(0, 1, At, B1); PG8_BAR; PG8_SCHED;
.LBB0_189:
	s_ashr_i32 s55, s54, 31
	s_lshl_b64 s[56:57], s[54:55], 20
	s_add_u32 s56, s69, s56
	s_addc_u32 s57, s70, s57
	s_and_b64 s[58:59], s[8:9], exec
	s_cselect_b32 s11, s57, s63
	s_cselect_b32 s33, s56, s62
	s_ashr_i32 s53, s52, 31
	s_lshl_b64 s[58:59], s[52:53], 20
	s_add_u32 s58, s71, s58
	s_addc_u32 s59, s72, s59
	s_and_b64 s[66:67], s[8:9], exec
	s_cselect_b32 s53, s59, s65
	s_cselect_b32 s55, s58, s64
	s_add_u32 s62, s62, 0x80080
	s_addc_u32 s63, s63, 0
	s_add_u32 s61, s64, 0x100
	v_mov_b32_e32 v2, 0
	s_addc_u32 s96, s65, 0
	s_mov_b32 s97, -2
	v_mov_b32_e32 v3, v2
	s_add_u32 s100, s62, 0xfff80180
	s_addc_u32 s101, s63, -1
	v_mov_b32_e32 v248, s100
	v_mov_b32_e32 v249, s101
	s_add_u32 s100, s61, 0x100
	s_addc_u32 s101, s96, 0
	v_mov_b32_e32 v250, s100
	v_mov_b32_e32 v251, s101
	s_mov_b64 s[100:101], 0xff0
	v_cndmask_b32_e64 v248, v248, v250, s[100:101]
	v_cndmask_b32_e64 v249, v249, v251, s[100:101]
	v_and_b32_e32 v247, 63, v0
	v_lshrrev_b32_e32 v250, 6, v0
	v_and_b32_e32 v251, 3, v247
	v_lshl_add_u32 v251, v250, 2, v251
	v_add_u32_e32 v247, 4, v247
	v_and_b32_e32 v247, 7, v247
	v_lshl_add_u32 v247, v250, 3, v247
	s_and_b32 s100, s2, 0xe0
	s_and_b32 s101, s2, 0x18
	s_lshl_b32 s101, s101, 3
	v_add_u32_e32 v251, s100, v251
	v_add_u32_e32 v247, s101, v247
	s_mov_b64 s[100:101], 0xff0
	v_cndmask_b32_e64 v247, v251, v247, s[100:101]
	v_mul_u32_u24_e32 v250, 0x1000, v247
	v_mov_b32_e32 v251, 0
	s_nop 0
	v_lshl_add_u64 v[248:249], v[250:251], 0, v[248:249]
	s_mov_b32 s101, 0
	s_mov_b32 s100, 0x80
	ds_read_b128 v[130:133], v229
	ds_read_b128 v[134:137], v229 offset:1024
	ds_read_b128 v[138:141], v229 offset:2048
	ds_read_b128 v[142:145], v229 offset:3072
	ds_read_b128 v[146:149], v230
	ds_read_b128 v[150:153], v230 offset:1024
	ds_read_b128 v[154:157], v230 offset:2048
	ds_read_b128 v[158:161], v230 offset:3072
	s_add_u32 s64, s62, 0xfff80080
	s_addc_u32 s65, s63, -1
	s_cmp_eq_u32 s97, 28
	s_cselect_b32 s67, s11, s65
	s_cselect_b32 s66, s33, s64
	s_cselect_b32 s65, s53, s96
	s_cselect_b32 s64, s55, s61
	s_cmp_lt_i32 s97, 23
	s_cselect_b32 s100, 0x80, 0
	s_add_i32 m0, s74, 0xc000
	ds_read_b128 v[162:165], v231
	ds_read_b128 v[166:169], v231 offset:1024
	ds_read_b128 v[170:173], v231 offset:2048
	ds_read_b128 v[174:177], v231 offset:3072
	ds_read_b128 v[178:181], v231 offset:4096
	ds_read_b128 v[182:185], v231 offset:5120
	ds_read_b128 v[186:189], v231 offset:6144
	ds_read_b128 v[190:193], v231 offset:7168
	global_load_lds_dwordx4 v212, s[62:63]
	s_add_i32 m0, s74, 0xe000
	s_nop 0
	global_load_lds_dwordx4 v214, s[62:63]
	s_waitcnt vmcnt(9)
	s_waitcnt lgkmcnt(0)
	s_barrier
	s_waitcnt lgkmcnt(0)
	v_mfma_f32_16x16x32_bf16 v[126:129], v[130:133], v[162:165], 0
	v_mfma_f32_16x16x32_bf16 v[122:125], v[138:141], v[162:165], 0
	v_mfma_f32_16x16x32_bf16 v[110:113], v[130:133], v[170:173], 0
	v_mfma_f32_16x16x32_bf16 v[106:109], v[138:141], v[170:173], 0
	v_mfma_f32_16x16x32_bf16 v[94:97], v[130:133], v[178:181], 0
	v_mfma_f32_16x16x32_bf16 v[90:93], v[138:141], v[178:181], 0
	v_mfma_f32_16x16x32_bf16 v[78:81], v[130:133], v[186:189], 0
	v_mfma_f32_16x16x32_bf16 v[74:77], v[138:141], v[186:189], 0
	v_mfma_f32_16x16x32_bf16 v[126:129], v[134:137], v[166:169], v[126:129]
	v_mfma_f32_16x16x32_bf16 v[122:125], v[142:145], v[166:169], v[122:125]
	v_mfma_f32_16x16x32_bf16 v[110:113], v[134:137], v[174:177], v[110:113]
	v_mfma_f32_16x16x32_bf16 v[106:109], v[142:145], v[174:177], v[106:109]
	v_mfma_f32_16x16x32_bf16 v[94:97], v[134:137], v[182:185], v[94:97]
	v_mfma_f32_16x16x32_bf16 v[90:93], v[142:145], v[182:185], v[90:93]
	v_mfma_f32_16x16x32_bf16 v[78:81], v[134:137], v[190:193], v[78:81]
	v_mfma_f32_16x16x32_bf16 v[74:77], v[142:145], v[190:193], v[74:77]
	v_mfma_f32_16x16x32_bf16 v[118:121], v[146:149], v[162:165], 0
	v_mfma_f32_16x16x32_bf16 v[114:117], v[154:157], v[162:165], 0
	v_mfma_f32_16x16x32_bf16 v[102:105], v[146:149], v[170:173], 0
	v_mfma_f32_16x16x32_bf16 v[98:101], v[154:157], v[170:173], 0
	v_mfma_f32_16x16x32_bf16 v[86:89], v[146:149], v[178:181], 0
	v_mfma_f32_16x16x32_bf16 v[82:85], v[154:157], v[178:181], 0
	v_mfma_f32_16x16x32_bf16 v[70:73], v[146:149], v[186:189], 0
	v_mfma_f32_16x16x32_bf16 v[66:69], v[154:157], v[186:189], 0
	v_mfma_f32_16x16x32_bf16 v[118:121], v[150:153], v[166:169], v[118:121]
	v_mfma_f32_16x16x32_bf16 v[114:117], v[158:161], v[166:169], v[114:117]
	v_mfma_f32_16x16x32_bf16 v[102:105], v[150:153], v[174:177], v[102:105]
	v_mfma_f32_16x16x32_bf16 v[98:101], v[158:161], v[174:177], v[98:101]
	v_mfma_f32_16x16x32_bf16 v[86:89], v[150:153], v[182:185], v[86:89]
	v_mfma_f32_16x16x32_bf16 v[82:85], v[158:161], v[182:185], v[82:85]
	v_mfma_f32_16x16x32_bf16 v[70:73], v[150:153], v[190:193], v[70:73]
	v_mfma_f32_16x16x32_bf16 v[66:69], v[158:161], v[190:193], v[66:69]
	s_barrier
	s_add_i32 vcc_lo, s84, s73
	s_add_u32 s34, s64, s38
	s_addc_u32 s35, s65, s39
	s_mov_b32 m0, vcc_lo
	ds_read_b128 v[162:165], v231 offset:16384
	ds_read_b128 v[166:169], v231 offset:17408
	ds_read_b128 v[170:173], v231 offset:18432
	ds_read_b128 v[174:177], v231 offset:19456
	ds_read_b128 v[178:181], v231 offset:20480
	ds_read_b128 v[182:185], v231 offset:21504
	ds_read_b128 v[186:189], v231 offset:22528
	ds_read_b128 v[190:193], v231 offset:23552
	global_load_lds_dwordx4 v196, s[64:65]
	s_add_i32 m0, vcc_lo, 0x2000
	s_add_u32 vcc_lo, s64, 0x80000
	s_addc_u32 vcc_hi, s65, 0
	s_add_i32 s86, s85, s73
	global_load_lds_dwordx4 v200, s[64:65]
	s_mov_b32 m0, s86
	s_nop 0
	global_load_lds_dwordx4 v196, vcc
	s_add_i32 m0, s86, 0x2000
	s_nop 0
	global_load_lds_dwordx4 v200, vcc
	s_add_u32 s98, s66, s38
	s_addc_u32 s99, s67, s39
	s_mov_b32 m0, s74
	s_nop 0
	global_load_lds_dwordx4 v194, s[66:67]
	s_mov_b32 m0, s75
	s_nop 0
	global_load_lds_dwordx4 v198, s[66:67]
	global_load_dword v247, v[248:249], off
	v_lshl_add_u64 v[248:249], v[248:249], 0, s[100:101]
	s_waitcnt vmcnt(9)
	s_waitcnt lgkmcnt(0)
	s_barrier
; #define PG8_STAGE(bufoff, gbase, voff) do { _Pragma("unroll") for (int _i = 0; _i < 2; ++_i) \
;         __builtin_amdgcn_global_load_lds((const unsigned*)((const char*)(gbase) + (voff)[_i]), (PG8_LAS unsigned*)(lds + (bufoff) + ldsw + _i * 8192), 16, 0, 0); } while (0)
; #define PG8_LDA(dst, b, h) do { _Pragma("unroll") for (int m = 0; m < 4; ++m) _Pragma("unroll") for (int k = 0; k < 2; ++k) dst[m][k] = *(const PG8_LAS bf16x8*)(lds + PG8_SA(b, h) + aoff + m * 2048 + k * 1024); } while (0)
; #define PG8_LDB(dst, b, h) do { _Pragma("unroll") for (int n = 0; n < 2; ++n) _Pragma("unroll") for (int k = 0; k < 2; ++k) dst[n][k] = *(const PG8_LAS bf16x8*)(lds + PG8_SB(b, h) + boff + n * 2048 + k * 1024); } while (0)
; #define PG8_MMA(ai, bj, At, Bt) do { __builtin_amdgcn_s_setprio(1); _Pragma("unroll") for (int m = 0; m < 4; ++m) _Pragma("unroll") for (int n = 0; n < 2; ++n) _Pragma("unroll") for (int k = 0; k < 2; ++k) \
;         acc[ai][bj][m][n] = __builtin_amdgcn_mfma_f32_16x16x32_bf16(Bt[n][k], At[m][k], acc[ai][bj][m][n], 0, 0, 0); __builtin_amdgcn_s_setprio(0); } while (0)
; #define PG8_WAIT_V(n) asm volatile("s_waitcnt vmcnt(" #n ")" ::: "memory")
; #define PG8_WAIT_L(n) asm volatile("s_waitcnt lgkmcnt(" #n ")" ::: "memory")
; #define PG8_BAR __builtin_amdgcn_s_barrier()
; #define PG8_SCHED __builtin_amdgcn_sched_barrier(0)
; template <class Epi, class Sched, bool ALIGN_EPI = false, bool SP2 = false>
; __device__ __forceinline__ void gemm_phase(PG8_LAS unsigned char* lds, const Gemm g, const Sched& S, const Epi& E) {
;     ...
;             PG8_WAIT_V(8); PG8_WAIT_L(0); PG8_BAR; PG8_MMA(0, 0, At, B0); PG8_MMA(0, 1, At, B1); PG8_BAR; PG8_SCHED;
;             PG8_LDA(At, 0, 1); PG8_STAGE(PG8_SB(0, 0), b2, voffB); PG8_STAGE(PG8_SB(0, 1), b2 + hB, voffB); PG8_STAGE(PG8_SA(0, 0), a2, voffA);
;             PG8_WAIT_V(8); PG8_WAIT_L(0); PG8_BAR; PG8_MMA(1, 0, At, B0); PG8_MMA(1, 1, At, B1); PG8_BAR; PG8_SCHED;
;             PG8_LDB(B0, 1, 0); PG8_LDB(B1, 1, 1); PG8_SCHED; PG8_LDA(At, 1, 0); PG8_STAGE(PG8_SA(0, 1), a2 + hA, voffA);
;             PG8_WAIT_V(8); PG8_WAIT_L(0); PG8_BAR; PG8_MMA(0, 0, At, B0); PG8_MMA(0, 1, At, B1); PG8_BAR; PG8_SCHED;
	s_waitcnt lgkmcnt(0)
	v_mfma_f32_16x16x32_bf16 v[62:65], v[130:133], v[162:165], 0
	v_mfma_f32_16x16x32_bf16 v[58:61], v[138:141], v[162:165], 0
	v_mfma_f32_16x16x32_bf16 v[46:49], v[130:133], v[170:173], 0
	v_mfma_f32_16x16x32_bf16 v[42:45], v[138:141], v[170:173], 0
	v_mfma_f32_16x16x32_bf16 v[30:33], v[130:133], v[178:181], 0
	v_mfma_f32_16x16x32_bf16 v[26:29], v[138:141], v[178:181], 0
	v_mfma_f32_16x16x32_bf16 v[14:17], v[130:133], v[186:189], 0
	v_mfma_f32_16x16x32_bf16 v[10:13], v[138:141], v[186:189], 0
	v_mfma_f32_16x16x32_bf16 v[62:65], v[134:137], v[166:169], v[62:65]
	v_mfma_f32_16x16x32_bf16 v[58:61], v[142:145], v[166:169], v[58:61]
	v_mfma_f32_16x16x32_bf16 v[46:49], v[134:137], v[174:177], v[46:49]
	v_mfma_f32_16x16x32_bf16 v[42:45], v[142:145], v[174:177], v[42:45]
	v_mfma_f32_16x16x32_bf16 v[30:33], v[134:137], v[182:185], v[30:33]
	v_mfma_f32_16x16x32_bf16 v[26:29], v[142:145], v[182:185], v[26:29]
	v_mfma_f32_16x16x32_bf16 v[14:17], v[134:137], v[190:193], v[14:17]
	v_mfma_f32_16x16x32_bf16 v[10:13], v[142:145], v[190:193], v[10:13]
	v_mfma_f32_16x16x32_bf16 v[54:57], v[146:149], v[162:165], 0
	v_mfma_f32_16x16x32_bf16 v[50:53], v[154:157], v[162:165], 0
	v_mfma_f32_16x16x32_bf16 v[38:41], v[146:149], v[170:173], 0
	v_mfma_f32_16x16x32_bf16 v[34:37], v[154:157], v[170:173], 0
	v_mfma_f32_16x16x32_bf16 v[22:25], v[146:149], v[178:181], 0
	v_mfma_f32_16x16x32_bf16 v[18:21], v[154:157], v[178:181], 0
	v_mfma_f32_16x16x32_bf16 v[6:9], v[146:149], v[186:189], 0
	v_mfma_f32_16x16x32_bf16 v[2:5], v[154:157], v[186:189], 0
	v_mfma_f32_16x16x32_bf16 v[54:57], v[150:153], v[166:169], v[54:57]
	v_mfma_f32_16x16x32_bf16 v[50:53], v[158:161], v[166:169], v[50:53]
	v_mfma_f32_16x16x32_bf16 v[38:41], v[150:153], v[174:177], v[38:41]
	v_mfma_f32_16x16x32_bf16 v[34:37], v[158:161], v[174:177], v[34:37]
	v_mfma_f32_16x16x32_bf16 v[22:25], v[150:153], v[182:185], v[22:25]
	v_mfma_f32_16x16x32_bf16 v[18:21], v[158:161], v[182:185], v[18:21]
	v_mfma_f32_16x16x32_bf16 v[6:9], v[150:153], v[190:193], v[6:9]
	v_mfma_f32_16x16x32_bf16 v[2:5], v[158:161], v[190:193], v[2:5]
	s_barrier
	s_add_i32 s86, 0, 0x18000
	s_add_i32 vcc_lo, 0, 0x1c000
	v_add_u32_e32 v142, s86, v223
	v_add_u32_e32 v158, vcc_lo, v223
	ds_read_b128 v[130:133], v142
	ds_read_b128 v[134:137], v142 offset:1024
	ds_read_b128 v[138:141], v142 offset:2048
	ds_read_b128 v[142:145], v142 offset:3072
	ds_read_b128 v[146:149], v158
	ds_read_b128 v[150:153], v158 offset:1024
	ds_read_b128 v[154:157], v158 offset:2048
	ds_read_b128 v[158:161], v158 offset:3072
	s_add_u32 s66, s66, 0x80000
	s_addc_u32 s67, s67, 0
	s_mov_b32 m0, s76
	ds_read_b128 v[162:165], v231 offset:32768
	ds_read_b128 v[166:169], v231 offset:33792
	ds_read_b128 v[170:173], v231 offset:34816
	ds_read_b128 v[174:177], v231 offset:35840
	ds_read_b128 v[178:181], v231 offset:36864
	ds_read_b128 v[182:185], v231 offset:37888
	ds_read_b128 v[186:189], v231 offset:38912
	ds_read_b128 v[190:193], v231 offset:39936
	global_load_lds_dwordx4 v194, s[66:67]
	s_mov_b32 m0, s77
	s_nop 0
	global_load_lds_dwordx4 v198, s[66:67]
	s_waitcnt vmcnt(9)
	s_waitcnt lgkmcnt(0)
	s_barrier
	s_waitcnt lgkmcnt(0)
	v_mfma_f32_16x16x32_bf16 v[126:129], v[130:133], v[162:165], v[126:129]
	v_mfma_f32_16x16x32_bf16 v[122:125], v[138:141], v[162:165], v[122:125]
	v_mfma_f32_16x16x32_bf16 v[110:113], v[130:133], v[170:173], v[110:113]
	v_mfma_f32_16x16x32_bf16 v[106:109], v[138:141], v[170:173], v[106:109]
	v_mfma_f32_16x16x32_bf16 v[94:97], v[130:133], v[178:181], v[94:97]
	v_mfma_f32_16x16x32_bf16 v[90:93], v[138:141], v[178:181], v[90:93]
	v_mfma_f32_16x16x32_bf16 v[78:81], v[130:133], v[186:189], v[78:81]
	v_mfma_f32_16x16x32_bf16 v[74:77], v[138:141], v[186:189], v[74:77]
	v_mfma_f32_16x16x32_bf16 v[126:129], v[134:137], v[166:169], v[126:129]
	v_mfma_f32_16x16x32_bf16 v[122:125], v[142:145], v[166:169], v[122:125]
	v_mfma_f32_16x16x32_bf16 v[110:113], v[134:137], v[174:177], v[110:113]
	v_mfma_f32_16x16x32_bf16 v[106:109], v[142:145], v[174:177], v[106:109]
	v_mfma_f32_16x16x32_bf16 v[94:97], v[134:137], v[182:185], v[94:97]
	v_mfma_f32_16x16x32_bf16 v[90:93], v[142:145], v[182:185], v[90:93]
	v_mfma_f32_16x16x32_bf16 v[78:81], v[134:137], v[190:193], v[78:81]
	v_mfma_f32_16x16x32_bf16 v[74:77], v[142:145], v[190:193], v[74:77]
	v_mfma_f32_16x16x32_bf16 v[118:121], v[146:149], v[162:165], v[118:121]
	v_mfma_f32_16x16x32_bf16 v[114:117], v[154:157], v[162:165], v[114:117]
	v_mfma_f32_16x16x32_bf16 v[102:105], v[146:149], v[170:173], v[102:105]
	v_mfma_f32_16x16x32_bf16 v[98:101], v[154:157], v[170:173], v[98:101]
	v_mfma_f32_16x16x32_bf16 v[86:89], v[146:149], v[178:181], v[86:89]
	v_mfma_f32_16x16x32_bf16 v[82:85], v[154:157], v[178:181], v[82:85]
	v_mfma_f32_16x16x32_bf16 v[70:73], v[146:149], v[186:189], v[70:73]
	v_mfma_f32_16x16x32_bf16 v[66:69], v[154:157], v[186:189], v[66:69]
	v_mfma_f32_16x16x32_bf16 v[118:121], v[150:153], v[166:169], v[118:121]
	v_mfma_f32_16x16x32_bf16 v[114:117], v[158:161], v[166:169], v[114:117]
	v_mfma_f32_16x16x32_bf16 v[102:105], v[150:153], v[174:177], v[102:105]
	v_mfma_f32_16x16x32_bf16 v[98:101], v[158:161], v[174:177], v[98:101]
	v_mfma_f32_16x16x32_bf16 v[86:89], v[150:153], v[182:185], v[86:89]
	v_mfma_f32_16x16x32_bf16 v[82:85], v[158:161], v[182:185], v[82:85]
	v_mfma_f32_16x16x32_bf16 v[70:73], v[150:153], v[190:193], v[70:73]
	v_mfma_f32_16x16x32_bf16 v[66:69], v[158:161], v[190:193], v[66:69]
	s_barrier
; #define PG8_STAGE(bufoff, gbase, voff) do { _Pragma("unroll") for (int _i = 0; _i < 2; ++_i) \
;         __builtin_amdgcn_global_load_lds((const unsigned*)((const char*)(gbase) + (voff)[_i]), (PG8_LAS unsigned*)(lds + (bufoff) + ldsw + _i * 8192), 16, 0, 0); } while (0)
; #define PG8_LDA(dst, b, h) do { _Pragma("unroll") for (int m = 0; m < 4; ++m) _Pragma("unroll") for (int k = 0; k < 2; ++k) dst[m][k] = *(const PG8_LAS bf16x8*)(lds + PG8_SA(b, h) + aoff + m * 2048 + k * 1024); } while (0)
; #define PG8_LDB(dst, b, h) do { _Pragma("unroll") for (int n = 0; n < 2; ++n) _Pragma("unroll") for (int k = 0; k < 2; ++k) dst[n][k] = *(const PG8_LAS bf16x8*)(lds + PG8_SB(b, h) + boff + n * 2048 + k * 1024); } while (0)
; #define PG8_MMA(ai, bj, At, Bt) do { __builtin_amdgcn_s_setprio(1); _Pragma("unroll") for (int m = 0; m < 4; ++m) _Pragma("unroll") for (int n = 0; n < 2; ++n) _Pragma("unroll") for (int k = 0; k < 2; ++k) \
;         acc[ai][bj][m][n] = __builtin_amdgcn_mfma_f32_16x16x32_bf16(Bt[n][k], At[m][k], acc[ai][bj][m][n], 0, 0, 0); __builtin_amdgcn_s_setprio(0); } while (0)
; #define PG8_WAIT_V(n) asm volatile("s_waitcnt vmcnt(" #n ")" ::: "memory")
; #define PG8_WAIT_L(n) asm volatile("s_waitcnt lgkmcnt(" #n ")" ::: "memory")
; #define PG8_BAR __builtin_amdgcn_s_barrier()
; #define PG8_SCHED __builtin_amdgcn_sched_barrier(0)
; template <class Epi, class Sched, bool ALIGN_EPI = false, bool SP2 = false>
; __device__ __forceinline__ void gemm_phase(PG8_LAS unsigned char* lds, const Gemm g, const Sched& S, const Epi& E) {
;     ...
;         for (int t = 0; t < nt; t += 2) {
;             const bool last = (t == nt - 2);
;             const char* a1 = cA + (size_t)(t + 1) * kstep;
;             const char* a2 = last ? nA : cA + (size_t)(t + 2) * kstep; const char* b2 = last ? nB : cB + (size_t)(t + 2) * kstep;
;             const char* a3 = a2 + kstep; const char* b3 = b2 + kstep;
;             if (last && has_next) S.a_ready(nxt);
;             if constexpr (SP2) {
;             PG8_LDB(B0, 0, 0); PG8_LDB(B1, 0, 1); PG8_SCHED; PG8_LDA(At, 0, 0); PG8_STAGE(PG8_SA(1, 1), a1 + hA, voffA);
;     ...
;             PG8_LDA(At, 1, 1); PG8_STAGE(PG8_SB(1, 0), b3, voffB); PG8_STAGE(PG8_SB(1, 1), b3 + hB, voffB); PG8_STAGE(PG8_SA(1, 0), a3, voffA);
;             PG8_WAIT_V(8); PG8_WAIT_L(0); PG8_BAR; PG8_MMA(1, 0, At, B0); PG8_MMA(1, 1, At, B1); PG8_BAR; PG8_SCHED;
	s_add_i32 s66, s86, s73
	s_mov_b32 m0, s66
	ds_read_b128 v[162:165], v231 offset:49152
	ds_read_b128 v[166:169], v231 offset:50176
	ds_read_b128 v[170:173], v231 offset:51200
	ds_read_b128 v[174:177], v231 offset:52224
	ds_read_b128 v[178:181], v231 offset:53248
	ds_read_b128 v[182:185], v231 offset:54272
	ds_read_b128 v[186:189], v231 offset:55296
	ds_read_b128 v[190:193], v231 offset:56320
	global_load_lds_dwordx4 v196, s[34:35]
	s_add_i32 m0, s66, 0x2000
	s_add_u32 s64, s64, 0x80080
	s_addc_u32 s65, s65, 0
	s_add_i32 s66, vcc_lo, s73
	global_load_lds_dwordx4 v200, s[34:35]
	s_mov_b32 m0, s66
	s_nop 0
	global_load_lds_dwordx4 v196, s[64:65]
	s_add_i32 m0, s66, 0x2000
	s_nop 0
	global_load_lds_dwordx4 v200, s[64:65]
	s_mov_b32 m0, s81
	s_nop 0
	global_load_lds_dwordx4 v194, s[98:99]
	s_mov_b32 m0, s82
	s_nop 0
	global_load_lds_dwordx4 v198, s[98:99]
	global_load_dword v247, v[248:249], off
	v_lshl_add_u64 v[248:249], v[248:249], 0, s[100:101]
	s_waitcnt vmcnt(10)
	s_waitcnt lgkmcnt(0)
	s_barrier
	s_waitcnt lgkmcnt(0)
	v_mfma_f32_16x16x32_bf16 v[62:65], v[130:133], v[162:165], v[62:65]
	v_mfma_f32_16x16x32_bf16 v[58:61], v[138:141], v[162:165], v[58:61]
	v_mfma_f32_16x16x32_bf16 v[46:49], v[130:133], v[170:173], v[46:49]
	v_mfma_f32_16x16x32_bf16 v[42:45], v[138:141], v[170:173], v[42:45]
	v_mfma_f32_16x16x32_bf16 v[30:33], v[130:133], v[178:181], v[30:33]
	v_mfma_f32_16x16x32_bf16 v[26:29], v[138:141], v[178:181], v[26:29]
	v_mfma_f32_16x16x32_bf16 v[14:17], v[130:133], v[186:189], v[14:17]
	v_mfma_f32_16x16x32_bf16 v[10:13], v[138:141], v[186:189], v[10:13]
	v_mfma_f32_16x16x32_bf16 v[62:65], v[134:137], v[166:169], v[62:65]
	v_mfma_f32_16x16x32_bf16 v[58:61], v[142:145], v[166:169], v[58:61]
	v_mfma_f32_16x16x32_bf16 v[46:49], v[134:137], v[174:177], v[46:49]
	v_mfma_f32_16x16x32_bf16 v[42:45], v[142:145], v[174:177], v[42:45]
	v_mfma_f32_16x16x32_bf16 v[30:33], v[134:137], v[182:185], v[30:33]
	v_mfma_f32_16x16x32_bf16 v[26:29], v[142:145], v[182:185], v[26:29]
	v_mfma_f32_16x16x32_bf16 v[14:17], v[134:137], v[190:193], v[14:17]
	v_mfma_f32_16x16x32_bf16 v[10:13], v[142:145], v[190:193], v[10:13]
	v_mfma_f32_16x16x32_bf16 v[54:57], v[146:149], v[162:165], v[54:57]
	v_mfma_f32_16x16x32_bf16 v[50:53], v[154:157], v[162:165], v[50:53]
	v_mfma_f32_16x16x32_bf16 v[38:41], v[146:149], v[170:173], v[38:41]
	v_mfma_f32_16x16x32_bf16 v[34:37], v[154:157], v[170:173], v[34:37]
	v_mfma_f32_16x16x32_bf16 v[22:25], v[146:149], v[178:181], v[22:25]
	v_mfma_f32_16x16x32_bf16 v[18:21], v[154:157], v[178:181], v[18:21]
	v_mfma_f32_16x16x32_bf16 v[6:9], v[146:149], v[186:189], v[6:9]
	v_mfma_f32_16x16x32_bf16 v[2:5], v[154:157], v[186:189], v[2:5]
	v_mfma_f32_16x16x32_bf16 v[54:57], v[150:153], v[166:169], v[54:57]
	v_mfma_f32_16x16x32_bf16 v[50:53], v[158:161], v[166:169], v[50:53]
	v_mfma_f32_16x16x32_bf16 v[38:41], v[150:153], v[174:177], v[38:41]
	v_mfma_f32_16x16x32_bf16 v[34:37], v[158:161], v[174:177], v[34:37]
	v_mfma_f32_16x16x32_bf16 v[22:25], v[150:153], v[182:185], v[22:25]
	v_mfma_f32_16x16x32_bf16 v[18:21], v[158:161], v[182:185], v[18:21]
	v_mfma_f32_16x16x32_bf16 v[6:9], v[150:153], v[190:193], v[6:9]
	v_mfma_f32_16x16x32_bf16 v[2:5], v[158:161], v[190:193], v[2:5]
	s_barrier
	s_add_i32 s97, s97, 2
	s_add_u32 s62, s62, 0x100
	s_addc_u32 s63, s63, 0
	s_add_u32 s61, s61, 0x100
	s_addc_u32 s96, s96, 0
	s_cmp_gt_u32 s97, 29
.LBB0_190:
	ds_read_b128 v[130:133], v229
	ds_read_b128 v[134:137], v229 offset:1024
	ds_read_b128 v[138:141], v229 offset:2048
	ds_read_b128 v[142:145], v229 offset:3072
	ds_read_b128 v[146:149], v230
	ds_read_b128 v[150:153], v230 offset:1024
	ds_read_b128 v[154:157], v230 offset:2048
	ds_read_b128 v[158:161], v230 offset:3072
	s_add_u32 s64, s62, 0xfff80080
	s_addc_u32 s65, s63, -1
	s_cmp_eq_u32 s97, 28
	s_cselect_b32 s67, s11, s65
	s_cselect_b32 s66, s33, s64
	s_cselect_b32 s65, s53, s96
	s_cselect_b32 s64, s55, s61
	s_cmp_lt_i32 s97, 23
	s_cselect_b32 s100, 0x80, 0
	s_add_i32 m0, s74, 0xc000
	ds_read_b128 v[162:165], v231
	ds_read_b128 v[166:169], v231 offset:1024
	ds_read_b128 v[170:173], v231 offset:2048
	ds_read_b128 v[174:177], v231 offset:3072
	ds_read_b128 v[178:181], v231 offset:4096
	ds_read_b128 v[182:185], v231 offset:5120
	ds_read_b128 v[186:189], v231 offset:6144
	ds_read_b128 v[190:193], v231 offset:7168
	global_load_lds_dwordx4 v212, s[62:63]
	s_add_i32 m0, s74, 0xe000
	s_nop 0
	global_load_lds_dwordx4 v214, s[62:63]
	s_waitcnt vmcnt(9)
	s_waitcnt lgkmcnt(0)
	s_barrier
; #define PG8_STAGE(bufoff, gbase, voff) do { _Pragma("unroll") for (int _i = 0; _i < 2; ++_i) \
;         __builtin_amdgcn_global_load_lds((const unsigned*)((const char*)(gbase) + (voff)[_i]), (PG8_LAS unsigned*)(lds + (bufoff) + ldsw + _i * 8192), 16, 0, 0); } while (0)
; #define PG8_LDA(dst, b, h) do { _Pragma("unroll") for (int m = 0; m < 4; ++m) _Pragma("unroll") for (int k = 0; k < 2; ++k) dst[m][k] = *(const PG8_LAS bf16x8*)(lds + PG8_SA(b, h) + aoff + m * 2048 + k * 1024); } while (0)
; #define PG8_MMA(ai, bj, At, Bt) do { __builtin_amdgcn_s_setprio(1); _Pragma("unroll") for (int m = 0; m < 4; ++m) _Pragma("unroll") for (int n = 0; n < 2; ++n) _Pragma("unroll") for (int k = 0; k < 2; ++k) \
;         acc[ai][bj][m][n] = __builtin_amdgcn_mfma_f32_16x16x32_bf16(Bt[n][k], At[m][k], acc[ai][bj][m][n], 0, 0, 0); __builtin_amdgcn_s_setprio(0); } while (0)
; #define PG8_WAIT_V(n) asm volatile("s_waitcnt vmcnt(" #n ")" ::: "memory")
; #define PG8_WAIT_L(n) asm volatile("s_waitcnt lgkmcnt(" #n ")" ::: "memory")
; #define PG8_BAR __builtin_amdgcn_s_barrier()
; #define PG8_SCHED __builtin_amdgcn_sched_barrier(0)
; template <class Epi, class Sched, bool ALIGN_EPI = false, bool SP2 = false>
; __device__ __forceinline__ void gemm_phase(PG8_LAS unsigned char* lds, const Gemm g, const Sched& S, const Epi& E) {
;     ...
;             PG8_WAIT_V(8); PG8_WAIT_L(0); PG8_BAR; PG8_MMA(0, 0, At, B0); PG8_MMA(0, 1, At, B1); PG8_BAR; PG8_SCHED;
;             PG8_LDA(At, 0, 1); PG8_STAGE(PG8_SB(0, 0), b2, voffB); PG8_STAGE(PG8_SB(0, 1), b2 + hB, voffB); PG8_STAGE(PG8_SA(0, 0), a2, voffA);
;             PG8_WAIT_V(8); PG8_WAIT_L(0); PG8_BAR; PG8_MMA(1, 0, At, B0); PG8_MMA(1, 1, At, B1); PG8_BAR; PG8_SCHED;
	s_waitcnt lgkmcnt(0)
	v_mfma_f32_16x16x32_bf16 v[126:129], v[130:133], v[162:165], v[126:129]
	v_mfma_f32_16x16x32_bf16 v[122:125], v[138:141], v[162:165], v[122:125]
	v_mfma_f32_16x16x32_bf16 v[110:113], v[130:133], v[170:173], v[110:113]
	v_mfma_f32_16x16x32_bf16 v[106:109], v[138:141], v[170:173], v[106:109]
	v_mfma_f32_16x16x32_bf16 v[94:97], v[130:133], v[178:181], v[94:97]
	v_mfma_f32_16x16x32_bf16 v[90:93], v[138:141], v[178:181], v[90:93]
	v_mfma_f32_16x16x32_bf16 v[78:81], v[130:133], v[186:189], v[78:81]
	v_mfma_f32_16x16x32_bf16 v[74:77], v[138:141], v[186:189], v[74:77]
	v_mfma_f32_16x16x32_bf16 v[126:129], v[134:137], v[166:169], v[126:129]
	v_mfma_f32_16x16x32_bf16 v[122:125], v[142:145], v[166:169], v[122:125]
	v_mfma_f32_16x16x32_bf16 v[110:113], v[134:137], v[174:177], v[110:113]
	v_mfma_f32_16x16x32_bf16 v[106:109], v[142:145], v[174:177], v[106:109]
	v_mfma_f32_16x16x32_bf16 v[94:97], v[134:137], v[182:185], v[94:97]
	v_mfma_f32_16x16x32_bf16 v[90:93], v[142:145], v[182:185], v[90:93]
	v_mfma_f32_16x16x32_bf16 v[78:81], v[134:137], v[190:193], v[78:81]
	v_mfma_f32_16x16x32_bf16 v[74:77], v[142:145], v[190:193], v[74:77]
	v_mfma_f32_16x16x32_bf16 v[118:121], v[146:149], v[162:165], v[118:121]
	v_mfma_f32_16x16x32_bf16 v[114:117], v[154:157], v[162:165], v[114:117]
	v_mfma_f32_16x16x32_bf16 v[102:105], v[146:149], v[170:173], v[102:105]
	v_mfma_f32_16x16x32_bf16 v[98:101], v[154:157], v[170:173], v[98:101]
	v_mfma_f32_16x16x32_bf16 v[86:89], v[146:149], v[178:181], v[86:89]
	v_mfma_f32_16x16x32_bf16 v[82:85], v[154:157], v[178:181], v[82:85]
	v_mfma_f32_16x16x32_bf16 v[70:73], v[146:149], v[186:189], v[70:73]
	v_mfma_f32_16x16x32_bf16 v[66:69], v[154:157], v[186:189], v[66:69]
	v_mfma_f32_16x16x32_bf16 v[118:121], v[150:153], v[166:169], v[118:121]
	v_mfma_f32_16x16x32_bf16 v[114:117], v[158:161], v[166:169], v[114:117]
	v_mfma_f32_16x16x32_bf16 v[102:105], v[150:153], v[174:177], v[102:105]
	v_mfma_f32_16x16x32_bf16 v[98:101], v[158:161], v[174:177], v[98:101]
	v_mfma_f32_16x16x32_bf16 v[86:89], v[150:153], v[182:185], v[86:89]
	v_mfma_f32_16x16x32_bf16 v[82:85], v[158:161], v[182:185], v[82:85]
	v_mfma_f32_16x16x32_bf16 v[70:73], v[150:153], v[190:193], v[70:73]
	v_mfma_f32_16x16x32_bf16 v[66:69], v[158:161], v[190:193], v[66:69]
	s_barrier
	s_add_i32 vcc_lo, s84, s73
	s_add_u32 s34, s64, s38
	s_addc_u32 s35, s65, s39
	s_mov_b32 m0, vcc_lo
	ds_read_b128 v[162:165], v231 offset:16384
	ds_read_b128 v[166:169], v231 offset:17408
	ds_read_b128 v[170:173], v231 offset:18432
	ds_read_b128 v[174:177], v231 offset:19456
	ds_read_b128 v[178:181], v231 offset:20480
	ds_read_b128 v[182:185], v231 offset:21504
	ds_read_b128 v[186:189], v231 offset:22528
	ds_read_b128 v[190:193], v231 offset:23552
	global_load_lds_dwordx4 v196, s[64:65]
	s_add_i32 m0, vcc_lo, 0x2000
	s_add_u32 vcc_lo, s64, 0x80000
	s_addc_u32 vcc_hi, s65, 0
	s_add_i32 s86, s85, s73
	global_load_lds_dwordx4 v200, s[64:65]
	s_mov_b32 m0, s86
	s_nop 0
	global_load_lds_dwordx4 v196, vcc
	s_add_i32 m0, s86, 0x2000
	s_nop 0
	global_load_lds_dwordx4 v200, vcc
	s_add_u32 s98, s66, s38
	s_addc_u32 s99, s67, s39
	s_mov_b32 m0, s74
	s_nop 0
	global_load_lds_dwordx4 v194, s[66:67]
	s_mov_b32 m0, s75
	s_nop 0
	global_load_lds_dwordx4 v198, s[66:67]
	global_load_dword v247, v[248:249], off
	v_lshl_add_u64 v[248:249], v[248:249], 0, s[100:101]
	s_waitcnt vmcnt(10)
	s_waitcnt lgkmcnt(0)
	s_barrier
	s_waitcnt lgkmcnt(0)
	v_mfma_f32_16x16x32_bf16 v[62:65], v[130:133], v[162:165], v[62:65]
	v_mfma_f32_16x16x32_bf16 v[58:61], v[138:141], v[162:165], v[58:61]
	v_mfma_f32_16x16x32_bf16 v[46:49], v[130:133], v[170:173], v[46:49]
	v_mfma_f32_16x16x32_bf16 v[42:45], v[138:141], v[170:173], v[42:45]
	v_mfma_f32_16x16x32_bf16 v[30:33], v[130:133], v[178:181], v[30:33]
	v_mfma_f32_16x16x32_bf16 v[26:29], v[138:141], v[178:181], v[26:29]
	v_mfma_f32_16x16x32_bf16 v[14:17], v[130:133], v[186:189], v[14:17]
	v_mfma_f32_16x16x32_bf16 v[10:13], v[138:141], v[186:189], v[10:13]
	v_mfma_f32_16x16x32_bf16 v[62:65], v[134:137], v[166:169], v[62:65]
	v_mfma_f32_16x16x32_bf16 v[58:61], v[142:145], v[166:169], v[58:61]
	v_mfma_f32_16x16x32_bf16 v[46:49], v[134:137], v[174:177], v[46:49]
	v_mfma_f32_16x16x32_bf16 v[42:45], v[142:145], v[174:177], v[42:45]
	v_mfma_f32_16x16x32_bf16 v[30:33], v[134:137], v[182:185], v[30:33]
	v_mfma_f32_16x16x32_bf16 v[26:29], v[142:145], v[182:185], v[26:29]
	v_mfma_f32_16x16x32_bf16 v[14:17], v[134:137], v[190:193], v[14:17]
	v_mfma_f32_16x16x32_bf16 v[10:13], v[142:145], v[190:193], v[10:13]
	v_mfma_f32_16x16x32_bf16 v[54:57], v[146:149], v[162:165], v[54:57]
	v_mfma_f32_16x16x32_bf16 v[50:53], v[154:157], v[162:165], v[50:53]
	v_mfma_f32_16x16x32_bf16 v[38:41], v[146:149], v[170:173], v[38:41]
	v_mfma_f32_16x16x32_bf16 v[34:37], v[154:157], v[170:173], v[34:37]
	v_mfma_f32_16x16x32_bf16 v[22:25], v[146:149], v[178:181], v[22:25]
	v_mfma_f32_16x16x32_bf16 v[18:21], v[154:157], v[178:181], v[18:21]
	v_mfma_f32_16x16x32_bf16 v[6:9], v[146:149], v[186:189], v[6:9]
	v_mfma_f32_16x16x32_bf16 v[2:5], v[154:157], v[186:189], v[2:5]
	v_mfma_f32_16x16x32_bf16 v[54:57], v[150:153], v[166:169], v[54:57]
	v_mfma_f32_16x16x32_bf16 v[50:53], v[158:161], v[166:169], v[50:53]
	v_mfma_f32_16x16x32_bf16 v[38:41], v[150:153], v[174:177], v[38:41]
	v_mfma_f32_16x16x32_bf16 v[34:37], v[158:161], v[174:177], v[34:37]
	v_mfma_f32_16x16x32_bf16 v[22:25], v[150:153], v[182:185], v[22:25]
	v_mfma_f32_16x16x32_bf16 v[18:21], v[158:161], v[182:185], v[18:21]
	v_mfma_f32_16x16x32_bf16 v[6:9], v[150:153], v[190:193], v[6:9]
	v_mfma_f32_16x16x32_bf16 v[2:5], v[158:161], v[190:193], v[2:5]
	s_barrier
; #define PG8_STAGE(bufoff, gbase, voff) do { _Pragma("unroll") for (int _i = 0; _i < 2; ++_i) \
;         __builtin_amdgcn_global_load_lds((const unsigned*)((const char*)(gbase) + (voff)[_i]), (PG8_LAS unsigned*)(lds + (bufoff) + ldsw + _i * 8192), 16, 0, 0); } while (0)
; #define PG8_LDA(dst, b, h) do { _Pragma("unroll") for (int m = 0; m < 4; ++m) _Pragma("unroll") for (int k = 0; k < 2; ++k) dst[m][k] = *(const PG8_LAS bf16x8*)(lds + PG8_SA(b, h) + aoff + m * 2048 + k * 1024); } while (0)
; #define PG8_LDB(dst, b, h) do { _Pragma("unroll") for (int n = 0; n < 2; ++n) _Pragma("unroll") for (int k = 0; k < 2; ++k) dst[n][k] = *(const PG8_LAS bf16x8*)(lds + PG8_SB(b, h) + boff + n * 2048 + k * 1024); } while (0)
; #define PG8_MMA(ai, bj, At, Bt) do { __builtin_amdgcn_s_setprio(1); _Pragma("unroll") for (int m = 0; m < 4; ++m) _Pragma("unroll") for (int n = 0; n < 2; ++n) _Pragma("unroll") for (int k = 0; k < 2; ++k) \
;         acc[ai][bj][m][n] = __builtin_amdgcn_mfma_f32_16x16x32_bf16(Bt[n][k], At[m][k], acc[ai][bj][m][n], 0, 0, 0); __builtin_amdgcn_s_setprio(0); } while (0)
; #define PG8_WAIT_V(n) asm volatile("s_waitcnt vmcnt(" #n ")" ::: "memory")
; #define PG8_WAIT_L(n) asm volatile("s_waitcnt lgkmcnt(" #n ")" ::: "memory")
; #define PG8_BAR __builtin_amdgcn_s_barrier()
; #define PG8_SCHED __builtin_amdgcn_sched_barrier(0)
; template <class Epi, class Sched, bool ALIGN_EPI = false, bool SP2 = false>
; __device__ __forceinline__ void gemm_phase(PG8_LAS unsigned char* lds, const Gemm g, const Sched& S, const Epi& E) {
;     ...
;             PG8_LDB(B0, 1, 0); PG8_LDB(B1, 1, 1); PG8_SCHED; PG8_LDA(At, 1, 0); PG8_STAGE(PG8_SA(0, 1), a2 + hA, voffA);
;             PG8_WAIT_V(8); PG8_WAIT_L(0); PG8_BAR; PG8_MMA(0, 0, At, B0); PG8_MMA(0, 1, At, B1); PG8_BAR; PG8_SCHED;
;             PG8_LDA(At, 1, 1); PG8_STAGE(PG8_SB(1, 0), b3, voffB); PG8_STAGE(PG8_SB(1, 1), b3 + hB, voffB); PG8_STAGE(PG8_SA(1, 0), a3, voffA);
;             PG8_WAIT_V(8); PG8_WAIT_L(0); PG8_BAR; PG8_MMA(1, 0, At, B0); PG8_MMA(1, 1, At, B1); PG8_BAR; PG8_SCHED;
;     ...
;         if constexpr (ALIGN_EPI) { if (wr == 0) PG8_BAR; }
;         if constexpr (!Epi::AFTER_DRAIN) { E(acc, cur, wr, wc, fr, fq); S.done(cur); }
;         if (!has_next) break;
	s_add_i32 s86, 0, 0x18000
	s_add_i32 vcc_lo, 0, 0x1c000
	v_add_u32_e32 v142, s86, v223
	v_add_u32_e32 v158, vcc_lo, v223
	ds_read_b128 v[130:133], v142
	ds_read_b128 v[134:137], v142 offset:1024
	ds_read_b128 v[138:141], v142 offset:2048
	ds_read_b128 v[142:145], v142 offset:3072
	ds_read_b128 v[146:149], v158
	ds_read_b128 v[150:153], v158 offset:1024
	ds_read_b128 v[154:157], v158 offset:2048
	ds_read_b128 v[158:161], v158 offset:3072
	s_add_u32 s66, s66, 0x80000
	s_addc_u32 s67, s67, 0
	s_mov_b32 m0, s76
	ds_read_b128 v[162:165], v231 offset:32768
	ds_read_b128 v[166:169], v231 offset:33792
	ds_read_b128 v[170:173], v231 offset:34816
	ds_read_b128 v[174:177], v231 offset:35840
	ds_read_b128 v[178:181], v231 offset:36864
	ds_read_b128 v[182:185], v231 offset:37888
	ds_read_b128 v[186:189], v231 offset:38912
	ds_read_b128 v[190:193], v231 offset:39936
	global_load_lds_dwordx4 v194, s[66:67]
	s_mov_b32 m0, s77
	s_nop 0
	global_load_lds_dwordx4 v198, s[66:67]
	s_waitcnt vmcnt(9)
	s_waitcnt lgkmcnt(0)
	s_barrier
	s_waitcnt lgkmcnt(0)
	v_mfma_f32_16x16x32_bf16 v[126:129], v[130:133], v[162:165], v[126:129]
	v_mfma_f32_16x16x32_bf16 v[122:125], v[138:141], v[162:165], v[122:125]
	v_mfma_f32_16x16x32_bf16 v[110:113], v[130:133], v[170:173], v[110:113]
	v_mfma_f32_16x16x32_bf16 v[106:109], v[138:141], v[170:173], v[106:109]
	v_mfma_f32_16x16x32_bf16 v[94:97], v[130:133], v[178:181], v[94:97]
	v_mfma_f32_16x16x32_bf16 v[90:93], v[138:141], v[178:181], v[90:93]
	v_mfma_f32_16x16x32_bf16 v[78:81], v[130:133], v[186:189], v[78:81]
	v_mfma_f32_16x16x32_bf16 v[74:77], v[138:141], v[186:189], v[74:77]
	v_mfma_f32_16x16x32_bf16 v[126:129], v[134:137], v[166:169], v[126:129]
	v_mfma_f32_16x16x32_bf16 v[122:125], v[142:145], v[166:169], v[122:125]
	v_mfma_f32_16x16x32_bf16 v[110:113], v[134:137], v[174:177], v[110:113]
	v_mfma_f32_16x16x32_bf16 v[106:109], v[142:145], v[174:177], v[106:109]
	v_mfma_f32_16x16x32_bf16 v[94:97], v[134:137], v[182:185], v[94:97]
	v_mfma_f32_16x16x32_bf16 v[90:93], v[142:145], v[182:185], v[90:93]
	v_mfma_f32_16x16x32_bf16 v[78:81], v[134:137], v[190:193], v[78:81]
	v_mfma_f32_16x16x32_bf16 v[74:77], v[142:145], v[190:193], v[74:77]
	v_mfma_f32_16x16x32_bf16 v[118:121], v[146:149], v[162:165], v[118:121]
	v_mfma_f32_16x16x32_bf16 v[114:117], v[154:157], v[162:165], v[114:117]
	v_mfma_f32_16x16x32_bf16 v[102:105], v[146:149], v[170:173], v[102:105]
	v_mfma_f32_16x16x32_bf16 v[98:101], v[154:157], v[170:173], v[98:101]
	v_mfma_f32_16x16x32_bf16 v[86:89], v[146:149], v[178:181], v[86:89]
	v_mfma_f32_16x16x32_bf16 v[82:85], v[154:157], v[178:181], v[82:85]
	v_mfma_f32_16x16x32_bf16 v[70:73], v[146:149], v[186:189], v[70:73]
	v_mfma_f32_16x16x32_bf16 v[66:69], v[154:157], v[186:189], v[66:69]
	v_mfma_f32_16x16x32_bf16 v[118:121], v[150:153], v[166:169], v[118:121]
	v_mfma_f32_16x16x32_bf16 v[114:117], v[158:161], v[166:169], v[114:117]
	v_mfma_f32_16x16x32_bf16 v[102:105], v[150:153], v[174:177], v[102:105]
	v_mfma_f32_16x16x32_bf16 v[98:101], v[158:161], v[174:177], v[98:101]
	v_mfma_f32_16x16x32_bf16 v[86:89], v[150:153], v[182:185], v[86:89]
	v_mfma_f32_16x16x32_bf16 v[82:85], v[158:161], v[182:185], v[82:85]
	v_mfma_f32_16x16x32_bf16 v[70:73], v[150:153], v[190:193], v[70:73]
	v_mfma_f32_16x16x32_bf16 v[66:69], v[158:161], v[190:193], v[66:69]
	s_barrier
	s_add_i32 s66, s86, s73
	s_mov_b32 m0, s66
	ds_read_b128 v[162:165], v231 offset:49152
	ds_read_b128 v[166:169], v231 offset:50176
	ds_read_b128 v[170:173], v231 offset:51200
	ds_read_b128 v[174:177], v231 offset:52224
	ds_read_b128 v[178:181], v231 offset:53248
	ds_read_b128 v[182:185], v231 offset:54272
	ds_read_b128 v[186:189], v231 offset:55296
	ds_read_b128 v[190:193], v231 offset:56320
	global_load_lds_dwordx4 v196, s[34:35]
	s_add_i32 m0, s66, 0x2000
	s_add_u32 s64, s64, 0x80080
	s_addc_u32 s65, s65, 0
	s_add_i32 s66, vcc_lo, s73
	global_load_lds_dwordx4 v200, s[34:35]
	s_mov_b32 m0, s66
	s_nop 0
	global_load_lds_dwordx4 v196, s[64:65]
	s_add_i32 m0, s66, 0x2000
	s_nop 0
	global_load_lds_dwordx4 v200, s[64:65]
	s_mov_b32 m0, s81
	s_nop 0
	global_load_lds_dwordx4 v194, s[98:99]
	s_mov_b32 m0, s82
	s_nop 0
	global_load_lds_dwordx4 v198, s[98:99]
	global_load_dword v247, v[248:249], off
	v_lshl_add_u64 v[248:249], v[248:249], 0, s[100:101]
	s_waitcnt vmcnt(10)
	s_waitcnt lgkmcnt(0)
	s_barrier
	s_waitcnt lgkmcnt(0)
	v_mfma_f32_16x16x32_bf16 v[62:65], v[130:133], v[162:165], v[62:65]
	v_mfma_f32_16x16x32_bf16 v[58:61], v[138:141], v[162:165], v[58:61]
	v_mfma_f32_16x16x32_bf16 v[46:49], v[130:133], v[170:173], v[46:49]
	v_mfma_f32_16x16x32_bf16 v[42:45], v[138:141], v[170:173], v[42:45]
	v_mfma_f32_16x16x32_bf16 v[30:33], v[130:133], v[178:181], v[30:33]
	v_mfma_f32_16x16x32_bf16 v[26:29], v[138:141], v[178:181], v[26:29]
	v_mfma_f32_16x16x32_bf16 v[14:17], v[130:133], v[186:189], v[14:17]
	v_mfma_f32_16x16x32_bf16 v[10:13], v[138:141], v[186:189], v[10:13]
	v_mfma_f32_16x16x32_bf16 v[62:65], v[134:137], v[166:169], v[62:65]
	v_mfma_f32_16x16x32_bf16 v[58:61], v[142:145], v[166:169], v[58:61]
	v_mfma_f32_16x16x32_bf16 v[46:49], v[134:137], v[174:177], v[46:49]
	v_mfma_f32_16x16x32_bf16 v[42:45], v[142:145], v[174:177], v[42:45]
	v_mfma_f32_16x16x32_bf16 v[30:33], v[134:137], v[182:185], v[30:33]
	v_mfma_f32_16x16x32_bf16 v[26:29], v[142:145], v[182:185], v[26:29]
	v_mfma_f32_16x16x32_bf16 v[14:17], v[134:137], v[190:193], v[14:17]
	v_mfma_f32_16x16x32_bf16 v[10:13], v[142:145], v[190:193], v[10:13]
	v_mfma_f32_16x16x32_bf16 v[54:57], v[146:149], v[162:165], v[54:57]
	v_mfma_f32_16x16x32_bf16 v[50:53], v[154:157], v[162:165], v[50:53]
	v_mfma_f32_16x16x32_bf16 v[38:41], v[146:149], v[170:173], v[38:41]
	v_mfma_f32_16x16x32_bf16 v[34:37], v[154:157], v[170:173], v[34:37]
	v_mfma_f32_16x16x32_bf16 v[22:25], v[146:149], v[178:181], v[22:25]
	v_mfma_f32_16x16x32_bf16 v[18:21], v[154:157], v[178:181], v[18:21]
	v_mfma_f32_16x16x32_bf16 v[6:9], v[146:149], v[186:189], v[6:9]
	v_mfma_f32_16x16x32_bf16 v[2:5], v[154:157], v[186:189], v[2:5]
	v_mfma_f32_16x16x32_bf16 v[54:57], v[150:153], v[166:169], v[54:57]
	v_mfma_f32_16x16x32_bf16 v[50:53], v[158:161], v[166:169], v[50:53]
	v_mfma_f32_16x16x32_bf16 v[38:41], v[150:153], v[174:177], v[38:41]
	v_mfma_f32_16x16x32_bf16 v[34:37], v[158:161], v[174:177], v[34:37]
	v_mfma_f32_16x16x32_bf16 v[22:25], v[150:153], v[182:185], v[22:25]
	v_mfma_f32_16x16x32_bf16 v[18:21], v[158:161], v[182:185], v[18:21]
	v_mfma_f32_16x16x32_bf16 v[6:9], v[150:153], v[190:193], v[6:9]
	v_mfma_f32_16x16x32_bf16 v[2:5], v[158:161], v[190:193], v[2:5]
	s_barrier
	s_add_i32 s97, s97, 2
	s_add_u32 s62, s62, 0x100
	s_addc_u32 s63, s63, 0
	s_add_u32 s61, s61, 0x100
	s_addc_u32 s96, s96, 0
	s_cmp_gt_u32 s97, 29
	s_cbranch_scc0 .LBB0_190
	s_and_b64 vcc, exec, s[40:41]
	s_cbranch_vccz .LBB0_211
	s_barrier
	v_lshl_add_u32 v220, s60, 8, v1
	s_cmp_gt_i32 s10, 15
	s_mov_b64 s[60:61], -1
	s_cbranch_scc1 .LBB0_212

; #define PG8_STAGE(bufoff, gbase, voff) do { _Pragma("unroll") for (int _i = 0; _i < 2; ++_i) \
;         __builtin_amdgcn_global_load_lds((const unsigned*)((const char*)(gbase) + (voff)[_i]), (PG8_LAS unsigned*)(lds + (bufoff) + ldsw + _i * 8192), 16, 0, 0); } while (0)
; #define PG8_LDA(dst, b, h) do { _Pragma("unroll") for (int m = 0; m < 4; ++m) _Pragma("unroll") for (int k = 0; k < 2; ++k) dst[m][k] = *(const PG8_LAS bf16x8*)(lds + PG8_SA(b, h) + aoff + m * 2048 + k * 1024); } while (0)
; #define PG8_LDB(dst, b, h) do { _Pragma("unroll") for (int n = 0; n < 2; ++n) _Pragma("unroll") for (int k = 0; k < 2; ++k) dst[n][k] = *(const PG8_LAS bf16x8*)(lds + PG8_SB(b, h) + boff + n * 2048 + k * 1024); } while (0)
; #define PG8_MMA(ai, bj, At, Bt) do { __builtin_amdgcn_s_setprio(1); _Pragma("unroll") for (int m = 0; m < 4; ++m) _Pragma("unroll") for (int n = 0; n < 2; ++n) _Pragma("unroll") for (int k = 0; k < 2; ++k) \
;         acc[ai][bj][m][n] = __builtin_amdgcn_mfma_f32_16x16x32_bf16(Bt[n][k], At[m][k], acc[ai][bj][m][n], 0, 0, 0); __builtin_amdgcn_s_setprio(0); } while (0)
; #define PG8_WAIT_V(n) asm volatile("s_waitcnt vmcnt(" #n ")" ::: "memory")
; #define PG8_BAR __builtin_amdgcn_s_barrier()
; template <class Epi, class Sched, bool ALIGN_EPI = false, bool SP2 = false>
; __device__ __forceinline__ void gemm_phase(PG8_LAS unsigned char* lds, const Gemm g, const Sched& S, const Epi& E) {
;     ...
;     for (;;) {
;         const bool has_next = S.next(ui + 1, nxt);
;         const char* nA = has_next ? (const char*)g.A + (size_t)nxt.pm * tA + (size_t)nxt.pn * pnA : cA; const char* nB = has_next ? (const char*)g.Bt + (size_t)nxt.pn * tB : cB;
; #pragma nounroll
;         for (int t = 0; t < nt; t += 2) {
;             const bool last = (t == nt - 2);
;             const char* a1 = cA + (size_t)(t + 1) * kstep;
;             const char* a2 = last ? nA : cA + (size_t)(t + 2) * kstep; const char* b2 = last ? nB : cB + (size_t)(t + 2) * kstep;
;             const char* a3 = a2 + kstep; const char* b3 = b2 + kstep;
;             if (last && has_next) S.a_ready(nxt);
;             if constexpr (SP2) {
;             PG8_LDB(B0, 0, 0); PG8_LDB(B1, 0, 1); PG8_SCHED; PG8_LDA(At, 0, 0); PG8_STAGE(PG8_SA(1, 1), a1 + hA, voffA);
;             PG8_WAIT_V(8); PG8_WAIT_L(0); PG8_BAR; PG8_MMA(0, 0, At, B0); PG8_MMA(0, 1, At, B1); PG8_BAR; PG8_SCHED;
.LBB0_867:
	s_ashr_i32 s23, s22, 31
	s_lshl_b64 s[24:25], s[22:23], 19
	s_add_u32 s24, s33, s24
	s_addc_u32 s25, s48, s25
	s_and_b64 s[38:39], s[4:5], exec
	s_cselect_b32 s23, s25, s43
	s_cselect_b32 s67, s24, s42
	s_ashr_i32 s21, s20, 31
	s_lshl_b64 s[38:39], s[20:21], 19
	s_add_u32 s38, s49, s38
	s_addc_u32 s39, s51, s39
	s_and_b64 s[46:47], s[4:5], exec
	s_cselect_b32 s21, s39, s45
	s_cselect_b32 s69, s38, s44
	s_add_u32 s42, s42, 0x40080
	s_addc_u32 s43, s43, 0
	s_add_u32 s70, s44, 0x100
	v_mov_b32_e32 v2, 0
	s_addc_u32 s71, s45, 0
	s_mov_b32 s72, -2
	v_mov_b32_e32 v3, v2
	s_add_u32 s90, s42, 0xfffc0180
	s_addc_u32 s91, s43, -1
	v_mov_b32_e32 v248, s90
	v_mov_b32_e32 v249, s91
	s_add_u32 s90, s70, 0x100
	s_addc_u32 s91, s71, 0
	v_mov_b32_e32 v250, s90
	v_mov_b32_e32 v251, s91
	s_mov_b64 s[90:91], 0xff0
	v_cndmask_b32_e64 v248, v248, v250, s[90:91]
	v_cndmask_b32_e64 v249, v249, v251, s[90:91]
	v_and_b32_e32 v247, 63, v0
	v_lshrrev_b32_e32 v250, 6, v0
	v_and_b32_e32 v251, 3, v247
	v_lshl_add_u32 v251, v250, 2, v251
	v_add_u32_e32 v247, 4, v247
	v_and_b32_e32 v247, 7, v247
	v_lshl_add_u32 v247, v250, 3, v247
	s_and_b32 s90, s2, 0xe0
	s_and_b32 s91, s2, 0x18
	s_lshl_b32 s91, s91, 3
	v_add_u32_e32 v251, s90, v251
	v_add_u32_e32 v247, s91, v247
	s_mov_b64 s[90:91], 0xff0
	v_cndmask_b32_e64 v247, v251, v247, s[90:91]
	v_mul_u32_u24_e32 v250, 0x800, v247
	v_mov_b32_e32 v251, 0
	s_nop 0
	v_lshl_add_u64 v[248:249], v[250:251], 0, v[248:249]
	s_mov_b32 s91, 0
	s_mov_b32 s90, 0x80
	ds_read_b128 v[146:149], v156
	ds_read_b128 v[150:153], v156 offset:1024
	ds_read_b128 v[160:163], v156 offset:2048
	ds_read_b128 v[164:167], v156 offset:3072
	ds_read_b128 v[168:171], v157
	ds_read_b128 v[172:175], v157 offset:1024
	ds_read_b128 v[176:179], v157 offset:2048
	ds_read_b128 v[180:183], v157 offset:3072
	s_add_u32 s18, s42, 0xfffc0080
	s_addc_u32 s19, s43, -1
	s_cmp_eq_u32 s72, 12
	s_cselect_b32 s47, s23, s19
	s_cselect_b32 s46, s67, s18
	s_cselect_b32 s45, s21, s71
	s_cselect_b32 s44, s69, s70
	s_cmp_lt_i32 s72, 7
	s_cselect_b32 s90, 0x80, 0
	s_add_i32 m0, s41, 0xc000
	ds_read_b128 v[184:187], v158
	ds_read_b128 v[188:191], v158 offset:1024
	ds_read_b128 v[192:195], v158 offset:2048
	ds_read_b128 v[196:199], v158 offset:3072
	ds_read_b128 v[200:203], v158 offset:4096
	ds_read_b128 v[204:207], v158 offset:5120
	ds_read_b128 v[208:211], v158 offset:6144
	ds_read_b128 v[212:215], v158 offset:7168
	global_load_lds_dwordx4 v138, s[42:43]
	s_add_i32 m0, s41, 0xe000
	s_nop 0
	global_load_lds_dwordx4 v140, s[42:43]
	s_waitcnt vmcnt(9)
	s_waitcnt lgkmcnt(0)
	s_barrier
	s_waitcnt lgkmcnt(0)
	v_mfma_f32_16x16x32_bf16 v[126:129], v[146:149], v[184:187], 0
	v_mfma_f32_16x16x32_bf16 v[122:125], v[160:163], v[184:187], 0
	v_mfma_f32_16x16x32_bf16 v[114:117], v[146:149], v[192:195], 0
	v_mfma_f32_16x16x32_bf16 v[106:109], v[160:163], v[192:195], 0
	v_mfma_f32_16x16x32_bf16 v[98:101], v[146:149], v[200:203], 0
	v_mfma_f32_16x16x32_bf16 v[90:93], v[160:163], v[200:203], 0
	v_mfma_f32_16x16x32_bf16 v[82:85], v[146:149], v[208:211], 0
	v_mfma_f32_16x16x32_bf16 v[74:77], v[160:163], v[208:211], 0
	v_mfma_f32_16x16x32_bf16 v[126:129], v[150:153], v[188:191], v[126:129]
	v_mfma_f32_16x16x32_bf16 v[122:125], v[164:167], v[188:191], v[122:125]
	v_mfma_f32_16x16x32_bf16 v[114:117], v[150:153], v[196:199], v[114:117]
	v_mfma_f32_16x16x32_bf16 v[106:109], v[164:167], v[196:199], v[106:109]
	v_mfma_f32_16x16x32_bf16 v[98:101], v[150:153], v[204:207], v[98:101]
	v_mfma_f32_16x16x32_bf16 v[90:93], v[164:167], v[204:207], v[90:93]
	v_mfma_f32_16x16x32_bf16 v[82:85], v[150:153], v[212:215], v[82:85]
	v_mfma_f32_16x16x32_bf16 v[74:77], v[164:167], v[212:215], v[74:77]
	v_mfma_f32_16x16x32_bf16 v[118:121], v[168:171], v[184:187], 0
	v_mfma_f32_16x16x32_bf16 v[110:113], v[176:179], v[184:187], 0
	v_mfma_f32_16x16x32_bf16 v[102:105], v[168:171], v[192:195], 0
	v_mfma_f32_16x16x32_bf16 v[94:97], v[176:179], v[192:195], 0
	v_mfma_f32_16x16x32_bf16 v[86:89], v[168:171], v[200:203], 0
	v_mfma_f32_16x16x32_bf16 v[78:81], v[176:179], v[200:203], 0
	v_mfma_f32_16x16x32_bf16 v[70:73], v[168:171], v[208:211], 0
	v_mfma_f32_16x16x32_bf16 v[66:69], v[176:179], v[208:211], 0
	v_mfma_f32_16x16x32_bf16 v[118:121], v[172:175], v[188:191], v[118:121]
	v_mfma_f32_16x16x32_bf16 v[110:113], v[180:183], v[188:191], v[110:113]
	v_mfma_f32_16x16x32_bf16 v[102:105], v[172:175], v[196:199], v[102:105]
	v_mfma_f32_16x16x32_bf16 v[94:97], v[180:183], v[196:199], v[94:97]
	v_mfma_f32_16x16x32_bf16 v[86:89], v[172:175], v[204:207], v[86:89]
	v_mfma_f32_16x16x32_bf16 v[78:81], v[180:183], v[204:207], v[78:81]
	v_mfma_f32_16x16x32_bf16 v[70:73], v[172:175], v[212:215], v[70:73]
	v_mfma_f32_16x16x32_bf16 v[66:69], v[180:183], v[212:215], v[66:69]
	s_barrier
	s_add_i32 s18, s64, s52
	s_add_u32 s78, s44, s8
	s_addc_u32 s79, s45, s9
	s_mov_b32 m0, s18
	ds_read_b128 v[184:187], v158 offset:16384
	ds_read_b128 v[188:191], v158 offset:17408
	ds_read_b128 v[192:195], v158 offset:18432
	ds_read_b128 v[196:199], v158 offset:19456
	ds_read_b128 v[200:203], v158 offset:20480
	ds_read_b128 v[204:207], v158 offset:21504
	ds_read_b128 v[208:211], v158 offset:22528
	ds_read_b128 v[212:215], v158 offset:23552
	global_load_lds_dwordx4 v134, s[44:45]
	s_add_i32 m0, s18, 0x2000
	s_add_u32 s74, s44, 0x40000
	s_addc_u32 s75, s45, 0
	s_add_i32 s18, s65, s52
	global_load_lds_dwordx4 v130, s[44:45]
	s_mov_b32 m0, s18
	s_nop 0
	global_load_lds_dwordx4 v134, s[74:75]
	s_add_i32 m0, s18, 0x2000
	s_nop 0
	global_load_lds_dwordx4 v130, s[74:75]
	s_add_u32 s80, s46, s8
	s_addc_u32 s81, s47, s9
	s_mov_b32 m0, s41
	s_nop 0
	global_load_lds_dwordx4 v136, s[46:47]
	s_mov_b32 m0, s53
	s_nop 0
	global_load_lds_dwordx4 v132, s[46:47]
	global_load_dword v247, v[248:249], off
	v_lshl_add_u64 v[248:249], v[248:249], 0, s[90:91]
	s_waitcnt vmcnt(9)
	s_waitcnt lgkmcnt(0)
	s_barrier
; #define PG8_STAGE(bufoff, gbase, voff) do { _Pragma("unroll") for (int _i = 0; _i < 2; ++_i) \
;         __builtin_amdgcn_global_load_lds((const unsigned*)((const char*)(gbase) + (voff)[_i]), (PG8_LAS unsigned*)(lds + (bufoff) + ldsw + _i * 8192), 16, 0, 0); } while (0)
; #define PG8_LDA(dst, b, h) do { _Pragma("unroll") for (int m = 0; m < 4; ++m) _Pragma("unroll") for (int k = 0; k < 2; ++k) dst[m][k] = *(const PG8_LAS bf16x8*)(lds + PG8_SA(b, h) + aoff + m * 2048 + k * 1024); } while (0)
; #define PG8_LDB(dst, b, h) do { _Pragma("unroll") for (int n = 0; n < 2; ++n) _Pragma("unroll") for (int k = 0; k < 2; ++k) dst[n][k] = *(const PG8_LAS bf16x8*)(lds + PG8_SB(b, h) + boff + n * 2048 + k * 1024); } while (0)
; #define PG8_MMA(ai, bj, At, Bt) do { __builtin_amdgcn_s_setprio(1); _Pragma("unroll") for (int m = 0; m < 4; ++m) _Pragma("unroll") for (int n = 0; n < 2; ++n) _Pragma("unroll") for (int k = 0; k < 2; ++k) \
;         acc[ai][bj][m][n] = __builtin_amdgcn_mfma_f32_16x16x32_bf16(Bt[n][k], At[m][k], acc[ai][bj][m][n], 0, 0, 0); __builtin_amdgcn_s_setprio(0); } while (0)
; #define PG8_WAIT_V(n) asm volatile("s_waitcnt vmcnt(" #n ")" ::: "memory")
; #define PG8_WAIT_L(n) asm volatile("s_waitcnt lgkmcnt(" #n ")" ::: "memory")
; #define PG8_BAR __builtin_amdgcn_s_barrier()
; #define PG8_SCHED __builtin_amdgcn_sched_barrier(0)
; template <class Epi, class Sched, bool ALIGN_EPI = false, bool SP2 = false>
; __device__ __forceinline__ void gemm_phase(PG8_LAS unsigned char* lds, const Gemm g, const Sched& S, const Epi& E) {
;     ...
;             PG8_WAIT_V(8); PG8_WAIT_L(0); PG8_BAR; PG8_MMA(0, 0, At, B0); PG8_MMA(0, 1, At, B1); PG8_BAR; PG8_SCHED;
;             PG8_LDA(At, 0, 1); PG8_STAGE(PG8_SB(0, 0), b2, voffB); PG8_STAGE(PG8_SB(0, 1), b2 + hB, voffB); PG8_STAGE(PG8_SA(0, 0), a2, voffA);
;             PG8_WAIT_V(8); PG8_WAIT_L(0); PG8_BAR; PG8_MMA(1, 0, At, B0); PG8_MMA(1, 1, At, B1); PG8_BAR; PG8_SCHED;
;             PG8_LDB(B0, 1, 0); PG8_LDB(B1, 1, 1); PG8_SCHED; PG8_LDA(At, 1, 0); PG8_STAGE(PG8_SA(0, 1), a2 + hA, voffA);
;             PG8_WAIT_V(8); PG8_WAIT_L(0); PG8_BAR; PG8_MMA(0, 0, At, B0); PG8_MMA(0, 1, At, B1); PG8_BAR; PG8_SCHED;
	s_waitcnt lgkmcnt(0)
	v_mfma_f32_16x16x32_bf16 v[62:65], v[146:149], v[184:187], 0
	v_mfma_f32_16x16x32_bf16 v[58:61], v[160:163], v[184:187], 0
	v_mfma_f32_16x16x32_bf16 v[50:53], v[146:149], v[192:195], 0
	v_mfma_f32_16x16x32_bf16 v[42:45], v[160:163], v[192:195], 0
	v_mfma_f32_16x16x32_bf16 v[34:37], v[146:149], v[200:203], 0
	v_mfma_f32_16x16x32_bf16 v[26:29], v[160:163], v[200:203], 0
	v_mfma_f32_16x16x32_bf16 v[18:21], v[146:149], v[208:211], 0
	v_mfma_f32_16x16x32_bf16 v[10:13], v[160:163], v[208:211], 0
	v_mfma_f32_16x16x32_bf16 v[62:65], v[150:153], v[188:191], v[62:65]
	v_mfma_f32_16x16x32_bf16 v[58:61], v[164:167], v[188:191], v[58:61]
	v_mfma_f32_16x16x32_bf16 v[50:53], v[150:153], v[196:199], v[50:53]
	v_mfma_f32_16x16x32_bf16 v[42:45], v[164:167], v[196:199], v[42:45]
	v_mfma_f32_16x16x32_bf16 v[34:37], v[150:153], v[204:207], v[34:37]
	v_mfma_f32_16x16x32_bf16 v[26:29], v[164:167], v[204:207], v[26:29]
	v_mfma_f32_16x16x32_bf16 v[18:21], v[150:153], v[212:215], v[18:21]
	v_mfma_f32_16x16x32_bf16 v[10:13], v[164:167], v[212:215], v[10:13]
	v_mfma_f32_16x16x32_bf16 v[54:57], v[168:171], v[184:187], 0
	v_mfma_f32_16x16x32_bf16 v[46:49], v[176:179], v[184:187], 0
	v_mfma_f32_16x16x32_bf16 v[38:41], v[168:171], v[192:195], 0
	v_mfma_f32_16x16x32_bf16 v[30:33], v[176:179], v[192:195], 0
	v_mfma_f32_16x16x32_bf16 v[22:25], v[168:171], v[200:203], 0
	v_mfma_f32_16x16x32_bf16 v[14:17], v[176:179], v[200:203], 0
	v_mfma_f32_16x16x32_bf16 v[6:9], v[168:171], v[208:211], 0
	v_mfma_f32_16x16x32_bf16 v[2:5], v[176:179], v[208:211], 0
	v_mfma_f32_16x16x32_bf16 v[54:57], v[172:175], v[188:191], v[54:57]
	v_mfma_f32_16x16x32_bf16 v[46:49], v[180:183], v[188:191], v[46:49]
	v_mfma_f32_16x16x32_bf16 v[38:41], v[172:175], v[196:199], v[38:41]
	v_mfma_f32_16x16x32_bf16 v[30:33], v[180:183], v[196:199], v[30:33]
	v_mfma_f32_16x16x32_bf16 v[22:25], v[172:175], v[204:207], v[22:25]
	v_mfma_f32_16x16x32_bf16 v[14:17], v[180:183], v[204:207], v[14:17]
	v_mfma_f32_16x16x32_bf16 v[6:9], v[172:175], v[212:215], v[6:9]
	v_mfma_f32_16x16x32_bf16 v[2:5], v[180:183], v[212:215], v[2:5]
	s_barrier
	s_add_i32 s18, 0, 0x18000
	v_add_u32_e32 v159, s18, v154
	s_add_i32 s19, 0, 0x1c000
	ds_read_b128 v[146:149], v159
	ds_read_b128 v[150:153], v159 offset:1024
	ds_read_b128 v[160:163], v159 offset:2048
	ds_read_b128 v[164:167], v159 offset:3072
	v_add_u32_e32 v159, s19, v154
	ds_read_b128 v[168:171], v159
	ds_read_b128 v[172:175], v159 offset:1024
	ds_read_b128 v[176:179], v159 offset:2048
	ds_read_b128 v[180:183], v159 offset:3072
	s_add_u32 s46, s46, 0x40000
	s_addc_u32 s47, s47, 0
	s_mov_b32 m0, s58
	ds_read_b128 v[184:187], v158 offset:32768
	ds_read_b128 v[188:191], v158 offset:33792
	ds_read_b128 v[192:195], v158 offset:34816
	ds_read_b128 v[196:199], v158 offset:35840
	ds_read_b128 v[200:203], v158 offset:36864
	ds_read_b128 v[204:207], v158 offset:37888
	ds_read_b128 v[208:211], v158 offset:38912
	ds_read_b128 v[212:215], v158 offset:39936
	global_load_lds_dwordx4 v136, s[46:47]
	s_mov_b32 m0, s59
	s_nop 0
	global_load_lds_dwordx4 v132, s[46:47]
	s_waitcnt vmcnt(9)
	s_waitcnt lgkmcnt(0)
	s_barrier
	s_waitcnt lgkmcnt(0)
	v_mfma_f32_16x16x32_bf16 v[126:129], v[146:149], v[184:187], v[126:129]
	v_mfma_f32_16x16x32_bf16 v[122:125], v[160:163], v[184:187], v[122:125]
	v_mfma_f32_16x16x32_bf16 v[114:117], v[146:149], v[192:195], v[114:117]
	v_mfma_f32_16x16x32_bf16 v[106:109], v[160:163], v[192:195], v[106:109]
	v_mfma_f32_16x16x32_bf16 v[98:101], v[146:149], v[200:203], v[98:101]
	v_mfma_f32_16x16x32_bf16 v[90:93], v[160:163], v[200:203], v[90:93]
	v_mfma_f32_16x16x32_bf16 v[82:85], v[146:149], v[208:211], v[82:85]
	v_mfma_f32_16x16x32_bf16 v[74:77], v[160:163], v[208:211], v[74:77]
	v_mfma_f32_16x16x32_bf16 v[126:129], v[150:153], v[188:191], v[126:129]
	v_mfma_f32_16x16x32_bf16 v[122:125], v[164:167], v[188:191], v[122:125]
	v_mfma_f32_16x16x32_bf16 v[114:117], v[150:153], v[196:199], v[114:117]
	v_mfma_f32_16x16x32_bf16 v[106:109], v[164:167], v[196:199], v[106:109]
	v_mfma_f32_16x16x32_bf16 v[98:101], v[150:153], v[204:207], v[98:101]
	v_mfma_f32_16x16x32_bf16 v[90:93], v[164:167], v[204:207], v[90:93]
	v_mfma_f32_16x16x32_bf16 v[82:85], v[150:153], v[212:215], v[82:85]
	v_mfma_f32_16x16x32_bf16 v[74:77], v[164:167], v[212:215], v[74:77]
	v_mfma_f32_16x16x32_bf16 v[118:121], v[168:171], v[184:187], v[118:121]
	v_mfma_f32_16x16x32_bf16 v[110:113], v[176:179], v[184:187], v[110:113]
	v_mfma_f32_16x16x32_bf16 v[102:105], v[168:171], v[192:195], v[102:105]
	v_mfma_f32_16x16x32_bf16 v[94:97], v[176:179], v[192:195], v[94:97]
	v_mfma_f32_16x16x32_bf16 v[86:89], v[168:171], v[200:203], v[86:89]
	v_mfma_f32_16x16x32_bf16 v[78:81], v[176:179], v[200:203], v[78:81]
	v_mfma_f32_16x16x32_bf16 v[70:73], v[168:171], v[208:211], v[70:73]
	v_mfma_f32_16x16x32_bf16 v[66:69], v[176:179], v[208:211], v[66:69]
	v_mfma_f32_16x16x32_bf16 v[118:121], v[172:175], v[188:191], v[118:121]
	v_mfma_f32_16x16x32_bf16 v[110:113], v[180:183], v[188:191], v[110:113]
	v_mfma_f32_16x16x32_bf16 v[102:105], v[172:175], v[196:199], v[102:105]
	v_mfma_f32_16x16x32_bf16 v[94:97], v[180:183], v[196:199], v[94:97]
	v_mfma_f32_16x16x32_bf16 v[86:89], v[172:175], v[204:207], v[86:89]
	v_mfma_f32_16x16x32_bf16 v[78:81], v[180:183], v[204:207], v[78:81]
	v_mfma_f32_16x16x32_bf16 v[70:73], v[172:175], v[212:215], v[70:73]
	v_mfma_f32_16x16x32_bf16 v[66:69], v[180:183], v[212:215], v[66:69]
	s_barrier
; #define PG8_STAGE(bufoff, gbase, voff) do { _Pragma("unroll") for (int _i = 0; _i < 2; ++_i) \
;         __builtin_amdgcn_global_load_lds((const unsigned*)((const char*)(gbase) + (voff)[_i]), (PG8_LAS unsigned*)(lds + (bufoff) + ldsw + _i * 8192), 16, 0, 0); } while (0)
; #define PG8_LDA(dst, b, h) do { _Pragma("unroll") for (int m = 0; m < 4; ++m) _Pragma("unroll") for (int k = 0; k < 2; ++k) dst[m][k] = *(const PG8_LAS bf16x8*)(lds + PG8_SA(b, h) + aoff + m * 2048 + k * 1024); } while (0)
; #define PG8_LDB(dst, b, h) do { _Pragma("unroll") for (int n = 0; n < 2; ++n) _Pragma("unroll") for (int k = 0; k < 2; ++k) dst[n][k] = *(const PG8_LAS bf16x8*)(lds + PG8_SB(b, h) + boff + n * 2048 + k * 1024); } while (0)
; #define PG8_MMA(ai, bj, At, Bt) do { __builtin_amdgcn_s_setprio(1); _Pragma("unroll") for (int m = 0; m < 4; ++m) _Pragma("unroll") for (int n = 0; n < 2; ++n) _Pragma("unroll") for (int k = 0; k < 2; ++k) \
;         acc[ai][bj][m][n] = __builtin_amdgcn_mfma_f32_16x16x32_bf16(Bt[n][k], At[m][k], acc[ai][bj][m][n], 0, 0, 0); __builtin_amdgcn_s_setprio(0); } while (0)
; #define PG8_WAIT_V(n) asm volatile("s_waitcnt vmcnt(" #n ")" ::: "memory")
; #define PG8_WAIT_L(n) asm volatile("s_waitcnt lgkmcnt(" #n ")" ::: "memory")
; #define PG8_BAR __builtin_amdgcn_s_barrier()
; #define PG8_SCHED __builtin_amdgcn_sched_barrier(0)
; template <class Epi, class Sched, bool ALIGN_EPI = false, bool SP2 = false>
; __device__ __forceinline__ void gemm_phase(PG8_LAS unsigned char* lds, const Gemm g, const Sched& S, const Epi& E) {
;     ...
;         for (int t = 0; t < nt; t += 2) {
;             const bool last = (t == nt - 2);
;             const char* a1 = cA + (size_t)(t + 1) * kstep;
;             const char* a2 = last ? nA : cA + (size_t)(t + 2) * kstep; const char* b2 = last ? nB : cB + (size_t)(t + 2) * kstep;
;             const char* a3 = a2 + kstep; const char* b3 = b2 + kstep;
;             if (last && has_next) S.a_ready(nxt);
;             if constexpr (SP2) {
;             PG8_LDB(B0, 0, 0); PG8_LDB(B1, 0, 1); PG8_SCHED; PG8_LDA(At, 0, 0); PG8_STAGE(PG8_SA(1, 1), a1 + hA, voffA);
;     ...
;             PG8_LDA(At, 1, 1); PG8_STAGE(PG8_SB(1, 0), b3, voffB); PG8_STAGE(PG8_SB(1, 1), b3 + hB, voffB); PG8_STAGE(PG8_SA(1, 0), a3, voffA);
;             PG8_WAIT_V(8); PG8_WAIT_L(0); PG8_BAR; PG8_MMA(1, 0, At, B0); PG8_MMA(1, 1, At, B1); PG8_BAR; PG8_SCHED;
	s_add_i32 s18, s18, s52
	s_mov_b32 m0, s18
	ds_read_b128 v[184:187], v158 offset:49152
	ds_read_b128 v[188:191], v158 offset:50176
	ds_read_b128 v[192:195], v158 offset:51200
	ds_read_b128 v[196:199], v158 offset:52224
	ds_read_b128 v[200:203], v158 offset:53248
	ds_read_b128 v[204:207], v158 offset:54272
	ds_read_b128 v[208:211], v158 offset:55296
	ds_read_b128 v[212:215], v158 offset:56320
	global_load_lds_dwordx4 v134, s[78:79]
	s_add_i32 m0, s18, 0x2000
	s_add_u32 s44, s44, 0x40080
	s_addc_u32 s45, s45, 0
	s_add_i32 s18, s19, s52
	global_load_lds_dwordx4 v130, s[78:79]
	s_mov_b32 m0, s18
	s_nop 0
	global_load_lds_dwordx4 v134, s[44:45]
	s_add_i32 m0, s18, 0x2000
	s_nop 0
	global_load_lds_dwordx4 v130, s[44:45]
	s_mov_b32 m0, s60
	s_nop 0
	global_load_lds_dwordx4 v136, s[80:81]
	s_mov_b32 m0, s61
	s_nop 0
	global_load_lds_dwordx4 v132, s[80:81]
	global_load_dword v247, v[248:249], off
	v_lshl_add_u64 v[248:249], v[248:249], 0, s[90:91]
	s_waitcnt vmcnt(10)
	s_waitcnt lgkmcnt(0)
	s_barrier
	s_waitcnt lgkmcnt(0)
	v_mfma_f32_16x16x32_bf16 v[62:65], v[146:149], v[184:187], v[62:65]
	v_mfma_f32_16x16x32_bf16 v[58:61], v[160:163], v[184:187], v[58:61]
	v_mfma_f32_16x16x32_bf16 v[50:53], v[146:149], v[192:195], v[50:53]
	v_mfma_f32_16x16x32_bf16 v[42:45], v[160:163], v[192:195], v[42:45]
	v_mfma_f32_16x16x32_bf16 v[34:37], v[146:149], v[200:203], v[34:37]
	v_mfma_f32_16x16x32_bf16 v[26:29], v[160:163], v[200:203], v[26:29]
	v_mfma_f32_16x16x32_bf16 v[18:21], v[146:149], v[208:211], v[18:21]
	v_mfma_f32_16x16x32_bf16 v[10:13], v[160:163], v[208:211], v[10:13]
	v_mfma_f32_16x16x32_bf16 v[62:65], v[150:153], v[188:191], v[62:65]
	v_mfma_f32_16x16x32_bf16 v[58:61], v[164:167], v[188:191], v[58:61]
	v_mfma_f32_16x16x32_bf16 v[50:53], v[150:153], v[196:199], v[50:53]
	v_mfma_f32_16x16x32_bf16 v[42:45], v[164:167], v[196:199], v[42:45]
	v_mfma_f32_16x16x32_bf16 v[34:37], v[150:153], v[204:207], v[34:37]
	v_mfma_f32_16x16x32_bf16 v[26:29], v[164:167], v[204:207], v[26:29]
	v_mfma_f32_16x16x32_bf16 v[18:21], v[150:153], v[212:215], v[18:21]
	v_mfma_f32_16x16x32_bf16 v[10:13], v[164:167], v[212:215], v[10:13]
	v_mfma_f32_16x16x32_bf16 v[54:57], v[168:171], v[184:187], v[54:57]
	v_mfma_f32_16x16x32_bf16 v[46:49], v[176:179], v[184:187], v[46:49]
	v_mfma_f32_16x16x32_bf16 v[38:41], v[168:171], v[192:195], v[38:41]
	v_mfma_f32_16x16x32_bf16 v[30:33], v[176:179], v[192:195], v[30:33]
	v_mfma_f32_16x16x32_bf16 v[22:25], v[168:171], v[200:203], v[22:25]
	v_mfma_f32_16x16x32_bf16 v[14:17], v[176:179], v[200:203], v[14:17]
	v_mfma_f32_16x16x32_bf16 v[6:9], v[168:171], v[208:211], v[6:9]
	v_mfma_f32_16x16x32_bf16 v[2:5], v[176:179], v[208:211], v[2:5]
	v_mfma_f32_16x16x32_bf16 v[54:57], v[172:175], v[188:191], v[54:57]
	v_mfma_f32_16x16x32_bf16 v[46:49], v[180:183], v[188:191], v[46:49]
	v_mfma_f32_16x16x32_bf16 v[38:41], v[172:175], v[196:199], v[38:41]
	v_mfma_f32_16x16x32_bf16 v[30:33], v[180:183], v[196:199], v[30:33]
	v_mfma_f32_16x16x32_bf16 v[22:25], v[172:175], v[204:207], v[22:25]
	v_mfma_f32_16x16x32_bf16 v[14:17], v[180:183], v[204:207], v[14:17]
	v_mfma_f32_16x16x32_bf16 v[6:9], v[172:175], v[212:215], v[6:9]
	v_mfma_f32_16x16x32_bf16 v[2:5], v[180:183], v[212:215], v[2:5]
	s_barrier
	s_add_i32 s72, s72, 2
	s_add_u32 s42, s42, 0x100
	s_addc_u32 s43, s43, 0
	s_add_u32 s70, s70, 0x100
	s_addc_u32 s71, s71, 0
	s_cmp_gt_u32 s72, 13
.LBB0_868:
	ds_read_b128 v[146:149], v156
	ds_read_b128 v[150:153], v156 offset:1024
	ds_read_b128 v[160:163], v156 offset:2048
	ds_read_b128 v[164:167], v156 offset:3072
	ds_read_b128 v[168:171], v157
	ds_read_b128 v[172:175], v157 offset:1024
	ds_read_b128 v[176:179], v157 offset:2048
	ds_read_b128 v[180:183], v157 offset:3072
	s_add_u32 s18, s42, 0xfffc0080
	s_addc_u32 s19, s43, -1
	s_cmp_eq_u32 s72, 12
	s_cselect_b32 s47, s23, s19
	s_cselect_b32 s46, s67, s18
	s_cselect_b32 s45, s21, s71
	s_cselect_b32 s44, s69, s70
	s_cmp_lt_i32 s72, 7
	s_cselect_b32 s90, 0x80, 0
	s_add_i32 m0, s41, 0xc000
	ds_read_b128 v[184:187], v158
	ds_read_b128 v[188:191], v158 offset:1024
	ds_read_b128 v[192:195], v158 offset:2048
	ds_read_b128 v[196:199], v158 offset:3072
	ds_read_b128 v[200:203], v158 offset:4096
	ds_read_b128 v[204:207], v158 offset:5120
	ds_read_b128 v[208:211], v158 offset:6144
	ds_read_b128 v[212:215], v158 offset:7168
	global_load_lds_dwordx4 v138, s[42:43]
	s_add_i32 m0, s41, 0xe000
	s_nop 0
	global_load_lds_dwordx4 v140, s[42:43]
	s_waitcnt vmcnt(9)
	s_waitcnt lgkmcnt(0)
	s_barrier
	s_waitcnt lgkmcnt(0)
	v_mfma_f32_16x16x32_bf16 v[126:129], v[146:149], v[184:187], v[126:129]
	v_mfma_f32_16x16x32_bf16 v[122:125], v[160:163], v[184:187], v[122:125]
	v_mfma_f32_16x16x32_bf16 v[114:117], v[146:149], v[192:195], v[114:117]
	v_mfma_f32_16x16x32_bf16 v[106:109], v[160:163], v[192:195], v[106:109]
	v_mfma_f32_16x16x32_bf16 v[98:101], v[146:149], v[200:203], v[98:101]
	v_mfma_f32_16x16x32_bf16 v[90:93], v[160:163], v[200:203], v[90:93]
	v_mfma_f32_16x16x32_bf16 v[82:85], v[146:149], v[208:211], v[82:85]
	v_mfma_f32_16x16x32_bf16 v[74:77], v[160:163], v[208:211], v[74:77]
	v_mfma_f32_16x16x32_bf16 v[126:129], v[150:153], v[188:191], v[126:129]
	v_mfma_f32_16x16x32_bf16 v[122:125], v[164:167], v[188:191], v[122:125]
	v_mfma_f32_16x16x32_bf16 v[114:117], v[150:153], v[196:199], v[114:117]
	v_mfma_f32_16x16x32_bf16 v[106:109], v[164:167], v[196:199], v[106:109]
	v_mfma_f32_16x16x32_bf16 v[98:101], v[150:153], v[204:207], v[98:101]
	v_mfma_f32_16x16x32_bf16 v[90:93], v[164:167], v[204:207], v[90:93]
	v_mfma_f32_16x16x32_bf16 v[82:85], v[150:153], v[212:215], v[82:85]
	v_mfma_f32_16x16x32_bf16 v[74:77], v[164:167], v[212:215], v[74:77]
	v_mfma_f32_16x16x32_bf16 v[118:121], v[168:171], v[184:187], v[118:121]
	v_mfma_f32_16x16x32_bf16 v[110:113], v[176:179], v[184:187], v[110:113]
	v_mfma_f32_16x16x32_bf16 v[102:105], v[168:171], v[192:195], v[102:105]
	v_mfma_f32_16x16x32_bf16 v[94:97], v[176:179], v[192:195], v[94:97]
	v_mfma_f32_16x16x32_bf16 v[86:89], v[168:171], v[200:203], v[86:89]
	v_mfma_f32_16x16x32_bf16 v[78:81], v[176:179], v[200:203], v[78:81]
	v_mfma_f32_16x16x32_bf16 v[70:73], v[168:171], v[208:211], v[70:73]
	v_mfma_f32_16x16x32_bf16 v[66:69], v[176:179], v[208:211], v[66:69]
	v_mfma_f32_16x16x32_bf16 v[118:121], v[172:175], v[188:191], v[118:121]
	v_mfma_f32_16x16x32_bf16 v[110:113], v[180:183], v[188:191], v[110:113]
	v_mfma_f32_16x16x32_bf16 v[102:105], v[172:175], v[196:199], v[102:105]
	v_mfma_f32_16x16x32_bf16 v[94:97], v[180:183], v[196:199], v[94:97]
	v_mfma_f32_16x16x32_bf16 v[86:89], v[172:175], v[204:207], v[86:89]
	v_mfma_f32_16x16x32_bf16 v[78:81], v[180:183], v[204:207], v[78:81]
	v_mfma_f32_16x16x32_bf16 v[70:73], v[172:175], v[212:215], v[70:73]
	v_mfma_f32_16x16x32_bf16 v[66:69], v[180:183], v[212:215], v[66:69]
	s_barrier
; #define PG8_STAGE(bufoff, gbase, voff) do { _Pragma("unroll") for (int _i = 0; _i < 2; ++_i) \
;         __builtin_amdgcn_global_load_lds((const unsigned*)((const char*)(gbase) + (voff)[_i]), (PG8_LAS unsigned*)(lds + (bufoff) + ldsw + _i * 8192), 16, 0, 0); } while (0)
; #define PG8_LDA(dst, b, h) do { _Pragma("unroll") for (int m = 0; m < 4; ++m) _Pragma("unroll") for (int k = 0; k < 2; ++k) dst[m][k] = *(const PG8_LAS bf16x8*)(lds + PG8_SA(b, h) + aoff + m * 2048 + k * 1024); } while (0)
; #define PG8_LDB(dst, b, h) do { _Pragma("unroll") for (int n = 0; n < 2; ++n) _Pragma("unroll") for (int k = 0; k < 2; ++k) dst[n][k] = *(const PG8_LAS bf16x8*)(lds + PG8_SB(b, h) + boff + n * 2048 + k * 1024); } while (0)
; #define PG8_MMA(ai, bj, At, Bt) do { __builtin_amdgcn_s_setprio(1); _Pragma("unroll") for (int m = 0; m < 4; ++m) _Pragma("unroll") for (int n = 0; n < 2; ++n) _Pragma("unroll") for (int k = 0; k < 2; ++k) \
;         acc[ai][bj][m][n] = __builtin_amdgcn_mfma_f32_16x16x32_bf16(Bt[n][k], At[m][k], acc[ai][bj][m][n], 0, 0, 0); __builtin_amdgcn_s_setprio(0); } while (0)
; #define PG8_WAIT_V(n) asm volatile("s_waitcnt vmcnt(" #n ")" ::: "memory")
; #define PG8_WAIT_L(n) asm volatile("s_waitcnt lgkmcnt(" #n ")" ::: "memory")
; #define PG8_BAR __builtin_amdgcn_s_barrier()
; #define PG8_SCHED __builtin_amdgcn_sched_barrier(0)
; template <class Epi, class Sched, bool ALIGN_EPI = false, bool SP2 = false>
; __device__ __forceinline__ void gemm_phase(PG8_LAS unsigned char* lds, const Gemm g, const Sched& S, const Epi& E) {
;     ...
;             PG8_WAIT_V(8); PG8_WAIT_L(0); PG8_BAR; PG8_MMA(0, 0, At, B0); PG8_MMA(0, 1, At, B1); PG8_BAR; PG8_SCHED;
;             PG8_LDA(At, 0, 1); PG8_STAGE(PG8_SB(0, 0), b2, voffB); PG8_STAGE(PG8_SB(0, 1), b2 + hB, voffB); PG8_STAGE(PG8_SA(0, 0), a2, voffA);
;             PG8_WAIT_V(8); PG8_WAIT_L(0); PG8_BAR; PG8_MMA(1, 0, At, B0); PG8_MMA(1, 1, At, B1); PG8_BAR; PG8_SCHED;
;             PG8_LDB(B0, 1, 0); PG8_LDB(B1, 1, 1); PG8_SCHED; PG8_LDA(At, 1, 0); PG8_STAGE(PG8_SA(0, 1), a2 + hA, voffA);
;             PG8_WAIT_V(8); PG8_WAIT_L(0); PG8_BAR; PG8_MMA(0, 0, At, B0); PG8_MMA(0, 1, At, B1); PG8_BAR; PG8_SCHED;
;             PG8_LDA(At, 1, 1); PG8_STAGE(PG8_SB(1, 0), b3, voffB); PG8_STAGE(PG8_SB(1, 1), b3 + hB, voffB); PG8_STAGE(PG8_SA(1, 0), a3, voffA);
	s_add_i32 s18, s64, s52
	s_add_u32 s78, s44, s8
	s_addc_u32 s79, s45, s9
	s_mov_b32 m0, s18
	ds_read_b128 v[184:187], v158 offset:16384
	ds_read_b128 v[188:191], v158 offset:17408
	ds_read_b128 v[192:195], v158 offset:18432
	ds_read_b128 v[196:199], v158 offset:19456
	ds_read_b128 v[200:203], v158 offset:20480
	ds_read_b128 v[204:207], v158 offset:21504
	ds_read_b128 v[208:211], v158 offset:22528
	ds_read_b128 v[212:215], v158 offset:23552
	global_load_lds_dwordx4 v134, s[44:45]
	s_add_i32 m0, s18, 0x2000
	s_add_u32 s74, s44, 0x40000
	s_addc_u32 s75, s45, 0
	s_add_i32 s18, s65, s52
	global_load_lds_dwordx4 v130, s[44:45]
	s_mov_b32 m0, s18
	s_nop 0
	global_load_lds_dwordx4 v134, s[74:75]
	s_add_i32 m0, s18, 0x2000
	s_nop 0
	global_load_lds_dwordx4 v130, s[74:75]
	s_add_u32 s80, s46, s8
	s_addc_u32 s81, s47, s9
	s_mov_b32 m0, s41
	s_nop 0
	global_load_lds_dwordx4 v136, s[46:47]
	s_mov_b32 m0, s53
	s_nop 0
	global_load_lds_dwordx4 v132, s[46:47]
	global_load_dword v247, v[248:249], off
	v_lshl_add_u64 v[248:249], v[248:249], 0, s[90:91]
	s_waitcnt vmcnt(10)
	s_waitcnt lgkmcnt(0)
	s_barrier
	s_waitcnt lgkmcnt(0)
	v_mfma_f32_16x16x32_bf16 v[62:65], v[146:149], v[184:187], v[62:65]
	v_mfma_f32_16x16x32_bf16 v[58:61], v[160:163], v[184:187], v[58:61]
	v_mfma_f32_16x16x32_bf16 v[50:53], v[146:149], v[192:195], v[50:53]
	v_mfma_f32_16x16x32_bf16 v[42:45], v[160:163], v[192:195], v[42:45]
	v_mfma_f32_16x16x32_bf16 v[34:37], v[146:149], v[200:203], v[34:37]
	v_mfma_f32_16x16x32_bf16 v[26:29], v[160:163], v[200:203], v[26:29]
	v_mfma_f32_16x16x32_bf16 v[18:21], v[146:149], v[208:211], v[18:21]
	v_mfma_f32_16x16x32_bf16 v[10:13], v[160:163], v[208:211], v[10:13]
	v_mfma_f32_16x16x32_bf16 v[62:65], v[150:153], v[188:191], v[62:65]
	v_mfma_f32_16x16x32_bf16 v[58:61], v[164:167], v[188:191], v[58:61]
	v_mfma_f32_16x16x32_bf16 v[50:53], v[150:153], v[196:199], v[50:53]
	v_mfma_f32_16x16x32_bf16 v[42:45], v[164:167], v[196:199], v[42:45]
	v_mfma_f32_16x16x32_bf16 v[34:37], v[150:153], v[204:207], v[34:37]
	v_mfma_f32_16x16x32_bf16 v[26:29], v[164:167], v[204:207], v[26:29]
	v_mfma_f32_16x16x32_bf16 v[18:21], v[150:153], v[212:215], v[18:21]
	v_mfma_f32_16x16x32_bf16 v[10:13], v[164:167], v[212:215], v[10:13]
	v_mfma_f32_16x16x32_bf16 v[54:57], v[168:171], v[184:187], v[54:57]
	v_mfma_f32_16x16x32_bf16 v[46:49], v[176:179], v[184:187], v[46:49]
	v_mfma_f32_16x16x32_bf16 v[38:41], v[168:171], v[192:195], v[38:41]
	v_mfma_f32_16x16x32_bf16 v[30:33], v[176:179], v[192:195], v[30:33]
	v_mfma_f32_16x16x32_bf16 v[22:25], v[168:171], v[200:203], v[22:25]
	v_mfma_f32_16x16x32_bf16 v[14:17], v[176:179], v[200:203], v[14:17]
	v_mfma_f32_16x16x32_bf16 v[6:9], v[168:171], v[208:211], v[6:9]
	v_mfma_f32_16x16x32_bf16 v[2:5], v[176:179], v[208:211], v[2:5]
	v_mfma_f32_16x16x32_bf16 v[54:57], v[172:175], v[188:191], v[54:57]
	v_mfma_f32_16x16x32_bf16 v[46:49], v[180:183], v[188:191], v[46:49]
	v_mfma_f32_16x16x32_bf16 v[38:41], v[172:175], v[196:199], v[38:41]
	v_mfma_f32_16x16x32_bf16 v[30:33], v[180:183], v[196:199], v[30:33]
	v_mfma_f32_16x16x32_bf16 v[22:25], v[172:175], v[204:207], v[22:25]
	v_mfma_f32_16x16x32_bf16 v[14:17], v[180:183], v[204:207], v[14:17]
	v_mfma_f32_16x16x32_bf16 v[6:9], v[172:175], v[212:215], v[6:9]
	v_mfma_f32_16x16x32_bf16 v[2:5], v[180:183], v[212:215], v[2:5]
	s_barrier
	s_add_i32 s18, 0, 0x18000
	v_add_u32_e32 v159, s18, v154
	s_add_i32 s19, 0, 0x1c000
	ds_read_b128 v[146:149], v159
	ds_read_b128 v[150:153], v159 offset:1024
	ds_read_b128 v[160:163], v159 offset:2048
	ds_read_b128 v[164:167], v159 offset:3072
	v_add_u32_e32 v159, s19, v154
	ds_read_b128 v[168:171], v159
	ds_read_b128 v[172:175], v159 offset:1024
	ds_read_b128 v[176:179], v159 offset:2048
	ds_read_b128 v[180:183], v159 offset:3072
	s_add_u32 s46, s46, 0x40000
	s_addc_u32 s47, s47, 0
	s_mov_b32 m0, s58
	ds_read_b128 v[184:187], v158 offset:32768
	ds_read_b128 v[188:191], v158 offset:33792
	ds_read_b128 v[192:195], v158 offset:34816
	ds_read_b128 v[196:199], v158 offset:35840
	ds_read_b128 v[200:203], v158 offset:36864
	ds_read_b128 v[204:207], v158 offset:37888
	ds_read_b128 v[208:211], v158 offset:38912
	ds_read_b128 v[212:215], v158 offset:39936
	global_load_lds_dwordx4 v136, s[46:47]
	s_mov_b32 m0, s59
	s_nop 0
	global_load_lds_dwordx4 v132, s[46:47]
	s_waitcnt vmcnt(9)
	s_waitcnt lgkmcnt(0)
	s_barrier
; #define PG8_STAGE(bufoff, gbase, voff) do { _Pragma("unroll") for (int _i = 0; _i < 2; ++_i) \
;         __builtin_amdgcn_global_load_lds((const unsigned*)((const char*)(gbase) + (voff)[_i]), (PG8_LAS unsigned*)(lds + (bufoff) + ldsw + _i * 8192), 16, 0, 0); } while (0)
; #define PG8_LDA(dst, b, h) do { _Pragma("unroll") for (int m = 0; m < 4; ++m) _Pragma("unroll") for (int k = 0; k < 2; ++k) dst[m][k] = *(const PG8_LAS bf16x8*)(lds + PG8_SA(b, h) + aoff + m * 2048 + k * 1024); } while (0)
; #define PG8_MMA(ai, bj, At, Bt) do { __builtin_amdgcn_s_setprio(1); _Pragma("unroll") for (int m = 0; m < 4; ++m) _Pragma("unroll") for (int n = 0; n < 2; ++n) _Pragma("unroll") for (int k = 0; k < 2; ++k) \
;         acc[ai][bj][m][n] = __builtin_amdgcn_mfma_f32_16x16x32_bf16(Bt[n][k], At[m][k], acc[ai][bj][m][n], 0, 0, 0); __builtin_amdgcn_s_setprio(0); } while (0)
; #define PG8_WAIT_V(n) asm volatile("s_waitcnt vmcnt(" #n ")" ::: "memory")
; #define PG8_WAIT_L(n) asm volatile("s_waitcnt lgkmcnt(" #n ")" ::: "memory")
; #define PG8_BAR __builtin_amdgcn_s_barrier()
; #define PG8_SCHED __builtin_amdgcn_sched_barrier(0)
; template <class Epi, class Sched, bool ALIGN_EPI = false, bool SP2 = false>
; __device__ __forceinline__ void gemm_phase(PG8_LAS unsigned char* lds, const Gemm g, const Sched& S, const Epi& E) {
;     ...
;             PG8_WAIT_V(8); PG8_WAIT_L(0); PG8_BAR; PG8_MMA(0, 0, At, B0); PG8_MMA(0, 1, At, B1); PG8_BAR; PG8_SCHED;
;             PG8_LDA(At, 1, 1); PG8_STAGE(PG8_SB(1, 0), b3, voffB); PG8_STAGE(PG8_SB(1, 1), b3 + hB, voffB); PG8_STAGE(PG8_SA(1, 0), a3, voffA);
;             PG8_WAIT_V(8); PG8_WAIT_L(0); PG8_BAR; PG8_MMA(1, 0, At, B0); PG8_MMA(1, 1, At, B1); PG8_BAR; PG8_SCHED;
;     ...
;         if constexpr (ALIGN_EPI) { if (wr == 0) PG8_BAR; }
;         if constexpr (!Epi::AFTER_DRAIN) { E(acc, cur, wr, wc, fr, fq); S.done(cur); }
;         if (!has_next) break;
	s_waitcnt lgkmcnt(0)
	v_mfma_f32_16x16x32_bf16 v[126:129], v[146:149], v[184:187], v[126:129]
	v_mfma_f32_16x16x32_bf16 v[122:125], v[160:163], v[184:187], v[122:125]
	v_mfma_f32_16x16x32_bf16 v[114:117], v[146:149], v[192:195], v[114:117]
	v_mfma_f32_16x16x32_bf16 v[106:109], v[160:163], v[192:195], v[106:109]
	v_mfma_f32_16x16x32_bf16 v[98:101], v[146:149], v[200:203], v[98:101]
	v_mfma_f32_16x16x32_bf16 v[90:93], v[160:163], v[200:203], v[90:93]
	v_mfma_f32_16x16x32_bf16 v[82:85], v[146:149], v[208:211], v[82:85]
	v_mfma_f32_16x16x32_bf16 v[74:77], v[160:163], v[208:211], v[74:77]
	v_mfma_f32_16x16x32_bf16 v[126:129], v[150:153], v[188:191], v[126:129]
	v_mfma_f32_16x16x32_bf16 v[122:125], v[164:167], v[188:191], v[122:125]
	v_mfma_f32_16x16x32_bf16 v[114:117], v[150:153], v[196:199], v[114:117]
	v_mfma_f32_16x16x32_bf16 v[106:109], v[164:167], v[196:199], v[106:109]
	v_mfma_f32_16x16x32_bf16 v[98:101], v[150:153], v[204:207], v[98:101]
	v_mfma_f32_16x16x32_bf16 v[90:93], v[164:167], v[204:207], v[90:93]
	v_mfma_f32_16x16x32_bf16 v[82:85], v[150:153], v[212:215], v[82:85]
	v_mfma_f32_16x16x32_bf16 v[74:77], v[164:167], v[212:215], v[74:77]
	v_mfma_f32_16x16x32_bf16 v[118:121], v[168:171], v[184:187], v[118:121]
	v_mfma_f32_16x16x32_bf16 v[110:113], v[176:179], v[184:187], v[110:113]
	v_mfma_f32_16x16x32_bf16 v[102:105], v[168:171], v[192:195], v[102:105]
	v_mfma_f32_16x16x32_bf16 v[94:97], v[176:179], v[192:195], v[94:97]
	v_mfma_f32_16x16x32_bf16 v[86:89], v[168:171], v[200:203], v[86:89]
	v_mfma_f32_16x16x32_bf16 v[78:81], v[176:179], v[200:203], v[78:81]
	v_mfma_f32_16x16x32_bf16 v[70:73], v[168:171], v[208:211], v[70:73]
	v_mfma_f32_16x16x32_bf16 v[66:69], v[176:179], v[208:211], v[66:69]
	v_mfma_f32_16x16x32_bf16 v[118:121], v[172:175], v[188:191], v[118:121]
	v_mfma_f32_16x16x32_bf16 v[110:113], v[180:183], v[188:191], v[110:113]
	v_mfma_f32_16x16x32_bf16 v[102:105], v[172:175], v[196:199], v[102:105]
	v_mfma_f32_16x16x32_bf16 v[94:97], v[180:183], v[196:199], v[94:97]
	v_mfma_f32_16x16x32_bf16 v[86:89], v[172:175], v[204:207], v[86:89]
	v_mfma_f32_16x16x32_bf16 v[78:81], v[180:183], v[204:207], v[78:81]
	v_mfma_f32_16x16x32_bf16 v[70:73], v[172:175], v[212:215], v[70:73]
	v_mfma_f32_16x16x32_bf16 v[66:69], v[180:183], v[212:215], v[66:69]
	s_barrier
	s_add_i32 s18, s18, s52
	s_mov_b32 m0, s18
	ds_read_b128 v[184:187], v158 offset:49152
	ds_read_b128 v[188:191], v158 offset:50176
	ds_read_b128 v[192:195], v158 offset:51200
	ds_read_b128 v[196:199], v158 offset:52224
	ds_read_b128 v[200:203], v158 offset:53248
	ds_read_b128 v[204:207], v158 offset:54272
	ds_read_b128 v[208:211], v158 offset:55296
	ds_read_b128 v[212:215], v158 offset:56320
	global_load_lds_dwordx4 v134, s[78:79]
	s_add_i32 m0, s18, 0x2000
	s_add_u32 s44, s44, 0x40080
	s_addc_u32 s45, s45, 0
	s_add_i32 s18, s19, s52
	global_load_lds_dwordx4 v130, s[78:79]
	s_mov_b32 m0, s18
	s_nop 0
	global_load_lds_dwordx4 v134, s[44:45]
	s_add_i32 m0, s18, 0x2000
	s_nop 0
	global_load_lds_dwordx4 v130, s[44:45]
	s_mov_b32 m0, s60
	s_nop 0
	global_load_lds_dwordx4 v136, s[80:81]
	s_mov_b32 m0, s61
	s_nop 0
	global_load_lds_dwordx4 v132, s[80:81]
	global_load_dword v247, v[248:249], off
	v_lshl_add_u64 v[248:249], v[248:249], 0, s[90:91]
	s_waitcnt vmcnt(10)
	s_waitcnt lgkmcnt(0)
	s_barrier
	s_waitcnt lgkmcnt(0)
	v_mfma_f32_16x16x32_bf16 v[62:65], v[146:149], v[184:187], v[62:65]
	v_mfma_f32_16x16x32_bf16 v[58:61], v[160:163], v[184:187], v[58:61]
	v_mfma_f32_16x16x32_bf16 v[50:53], v[146:149], v[192:195], v[50:53]
	v_mfma_f32_16x16x32_bf16 v[42:45], v[160:163], v[192:195], v[42:45]
	v_mfma_f32_16x16x32_bf16 v[34:37], v[146:149], v[200:203], v[34:37]
	v_mfma_f32_16x16x32_bf16 v[26:29], v[160:163], v[200:203], v[26:29]
	v_mfma_f32_16x16x32_bf16 v[18:21], v[146:149], v[208:211], v[18:21]
	v_mfma_f32_16x16x32_bf16 v[10:13], v[160:163], v[208:211], v[10:13]
	v_mfma_f32_16x16x32_bf16 v[62:65], v[150:153], v[188:191], v[62:65]
	v_mfma_f32_16x16x32_bf16 v[58:61], v[164:167], v[188:191], v[58:61]
	v_mfma_f32_16x16x32_bf16 v[50:53], v[150:153], v[196:199], v[50:53]
	v_mfma_f32_16x16x32_bf16 v[42:45], v[164:167], v[196:199], v[42:45]
	v_mfma_f32_16x16x32_bf16 v[34:37], v[150:153], v[204:207], v[34:37]
	v_mfma_f32_16x16x32_bf16 v[26:29], v[164:167], v[204:207], v[26:29]
	v_mfma_f32_16x16x32_bf16 v[18:21], v[150:153], v[212:215], v[18:21]
	v_mfma_f32_16x16x32_bf16 v[10:13], v[164:167], v[212:215], v[10:13]
	v_mfma_f32_16x16x32_bf16 v[54:57], v[168:171], v[184:187], v[54:57]
	v_mfma_f32_16x16x32_bf16 v[46:49], v[176:179], v[184:187], v[46:49]
	v_mfma_f32_16x16x32_bf16 v[38:41], v[168:171], v[192:195], v[38:41]
	v_mfma_f32_16x16x32_bf16 v[30:33], v[176:179], v[192:195], v[30:33]
	v_mfma_f32_16x16x32_bf16 v[22:25], v[168:171], v[200:203], v[22:25]
	v_mfma_f32_16x16x32_bf16 v[14:17], v[176:179], v[200:203], v[14:17]
	v_mfma_f32_16x16x32_bf16 v[6:9], v[168:171], v[208:211], v[6:9]
	v_mfma_f32_16x16x32_bf16 v[2:5], v[176:179], v[208:211], v[2:5]
	v_mfma_f32_16x16x32_bf16 v[54:57], v[172:175], v[188:191], v[54:57]
	v_mfma_f32_16x16x32_bf16 v[46:49], v[180:183], v[188:191], v[46:49]
	v_mfma_f32_16x16x32_bf16 v[38:41], v[172:175], v[196:199], v[38:41]
	v_mfma_f32_16x16x32_bf16 v[30:33], v[180:183], v[196:199], v[30:33]
	v_mfma_f32_16x16x32_bf16 v[22:25], v[172:175], v[204:207], v[22:25]
	v_mfma_f32_16x16x32_bf16 v[14:17], v[180:183], v[204:207], v[14:17]
	v_mfma_f32_16x16x32_bf16 v[6:9], v[172:175], v[212:215], v[6:9]
	v_mfma_f32_16x16x32_bf16 v[2:5], v[180:183], v[212:215], v[2:5]
	s_barrier
	s_add_i32 s72, s72, 2
	s_add_u32 s42, s42, 0x100
	s_addc_u32 s43, s43, 0
	s_add_u32 s70, s70, 0x100
	s_addc_u32 s71, s71, 0
	s_cmp_gt_u32 s72, 13
	s_cbranch_scc0 .LBB0_868
	s_and_b64 vcc, exec, s[14:15]
	s_cbranch_vccz .LBB0_871
	s_barrier

; #define PG8_STAGE(bufoff, gbase, voff) do { _Pragma("unroll") for (int _i = 0; _i < 2; ++_i) \
;         __builtin_amdgcn_global_load_lds((const unsigned*)((const char*)(gbase) + (voff)[_i]), (PG8_LAS unsigned*)(lds + (bufoff) + ldsw + _i * 8192), 16, 0, 0); } while (0)
; #define PG8_LDA(dst, b, h) do { _Pragma("unroll") for (int m = 0; m < 4; ++m) _Pragma("unroll") for (int k = 0; k < 2; ++k) dst[m][k] = *(const PG8_LAS bf16x8*)(lds + PG8_SA(b, h) + aoff + m * 2048 + k * 1024); } while (0)
; #define PG8_LDB(dst, b, h) do { _Pragma("unroll") for (int n = 0; n < 2; ++n) _Pragma("unroll") for (int k = 0; k < 2; ++k) dst[n][k] = *(const PG8_LAS bf16x8*)(lds + PG8_SB(b, h) + boff + n * 2048 + k * 1024); } while (0)
; #define PG8_MMA(ai, bj, At, Bt) do { __builtin_amdgcn_s_setprio(1); _Pragma("unroll") for (int m = 0; m < 4; ++m) _Pragma("unroll") for (int n = 0; n < 2; ++n) _Pragma("unroll") for (int k = 0; k < 2; ++k) \
;         acc[ai][bj][m][n] = __builtin_amdgcn_mfma_f32_16x16x32_bf16(Bt[n][k], At[m][k], acc[ai][bj][m][n], 0, 0, 0); __builtin_amdgcn_s_setprio(0); } while (0)
; #define PG8_WAIT_V(n) asm volatile("s_waitcnt vmcnt(" #n ")" ::: "memory")
; #define PG8_BAR __builtin_amdgcn_s_barrier()
; template <class Epi, class Sched, bool ALIGN_EPI = false, bool SP2 = false>
; __device__ __forceinline__ void gemm_phase(PG8_LAS unsigned char* lds, const Gemm g, const Sched& S, const Epi& E) {
;     ...
;     for (;;) {
;         const bool has_next = S.next(ui + 1, nxt);
;         const char* nA = has_next ? (const char*)g.A + (size_t)nxt.pm * tA + (size_t)nxt.pn * pnA : cA; const char* nB = has_next ? (const char*)g.Bt + (size_t)nxt.pn * tB : cB;
; #pragma nounroll
;         for (int t = 0; t < nt; t += 2) {
;             const bool last = (t == nt - 2);
;             const char* a1 = cA + (size_t)(t + 1) * kstep;
;             const char* a2 = last ? nA : cA + (size_t)(t + 2) * kstep; const char* b2 = last ? nB : cB + (size_t)(t + 2) * kstep;
;             const char* a3 = a2 + kstep; const char* b3 = b2 + kstep;
;             if (last && has_next) S.a_ready(nxt);
;             if constexpr (SP2) {
;             PG8_LDB(B0, 0, 0); PG8_LDB(B1, 0, 1); PG8_SCHED; PG8_LDA(At, 0, 0); PG8_STAGE(PG8_SA(1, 1), a1 + hA, voffA);
;             PG8_WAIT_V(8); PG8_WAIT_L(0); PG8_BAR; PG8_MMA(0, 0, At, B0); PG8_MMA(0, 1, At, B1); PG8_BAR; PG8_SCHED;
.LBB0_887:
	s_ashr_i32 s25, s24, 31
	s_lshl_b64 s[38:39], s[24:25], 20
	s_add_u32 s38, s33, s38
	s_addc_u32 s39, s51, s39
	s_and_b64 s[40:41], s[6:7], exec
	s_cselect_b32 s25, s39, s45
	s_cselect_b32 s70, s38, s44
	s_ashr_i32 s23, s22, 31
	s_lshl_b64 s[40:41], s[22:23], 20
	s_add_u32 s40, s52, s40
	s_addc_u32 s41, s53, s41
	s_and_b64 s[48:49], s[6:7], exec
	s_cselect_b32 s23, s41, s47
	s_cselect_b32 s71, s40, s46
	s_add_u32 s44, s44, 0x80080
	s_addc_u32 s45, s45, 0
	s_add_u32 s72, s46, 0x100
	v_mov_b32_e32 v2, 0
	s_addc_u32 s73, s47, 0
	s_mov_b32 s74, -2
	v_mov_b32_e32 v3, v2
	s_add_u32 s90, s44, 0xfff80180
	s_addc_u32 s91, s45, -1
	v_mov_b32_e32 v248, s90
	v_mov_b32_e32 v249, s91
	s_add_u32 s90, s72, 0x100
	s_addc_u32 s91, s73, 0
	v_mov_b32_e32 v250, s90
	v_mov_b32_e32 v251, s91
	s_mov_b64 s[90:91], 0xff0
	v_cndmask_b32_e64 v248, v248, v250, s[90:91]
	v_cndmask_b32_e64 v249, v249, v251, s[90:91]
	v_and_b32_e32 v247, 63, v0
	v_lshrrev_b32_e32 v250, 6, v0
	v_and_b32_e32 v251, 3, v247
	v_lshl_add_u32 v251, v250, 2, v251
	v_add_u32_e32 v247, 4, v247
	v_and_b32_e32 v247, 7, v247
	v_lshl_add_u32 v247, v250, 3, v247
	s_and_b32 s90, s2, 0xe0
	s_and_b32 s91, s2, 0x18
	s_lshl_b32 s91, s91, 3
	v_add_u32_e32 v251, s90, v251
	v_add_u32_e32 v247, s91, v247
	s_mov_b64 s[90:91], 0xff0
	v_cndmask_b32_e64 v247, v251, v247, s[90:91]
	v_mul_u32_u24_e32 v250, 0x1000, v247
	v_mov_b32_e32 v251, 0
	s_nop 0
	v_lshl_add_u64 v[248:249], v[250:251], 0, v[248:249]
	s_mov_b32 s91, 0
	s_mov_b32 s90, 0x80
	ds_read_b128 v[130:133], v172
	ds_read_b128 v[134:137], v172 offset:1024
	ds_read_b128 v[138:141], v172 offset:2048
	ds_read_b128 v[142:145], v172 offset:3072
	ds_read_b128 v[162:165], v173
	ds_read_b128 v[166:169], v173 offset:1024
	ds_read_b128 v[176:179], v173 offset:2048
	ds_read_b128 v[180:183], v173 offset:3072
	s_add_u32 s18, s44, 0xfff80080
	s_addc_u32 s19, s45, -1
	s_cmp_eq_u32 s74, 28
	s_cselect_b32 s49, s25, s19
	s_cselect_b32 s48, s70, s18
	s_cselect_b32 s47, s23, s73
	s_cselect_b32 s46, s71, s72
	s_cmp_lt_i32 s74, 23
	s_cselect_b32 s90, 0x80, 0
	s_add_i32 m0, s43, 0xc000
	ds_read_b128 v[184:187], v174
	ds_read_b128 v[188:191], v174 offset:1024
	ds_read_b128 v[192:195], v174 offset:2048
	ds_read_b128 v[196:199], v174 offset:3072
	ds_read_b128 v[200:203], v174 offset:4096
	ds_read_b128 v[204:207], v174 offset:5120
	ds_read_b128 v[208:211], v174 offset:6144
	ds_read_b128 v[212:215], v174 offset:7168
	global_load_lds_dwordx4 v154, s[44:45]
	s_add_i32 m0, s43, 0xe000
	s_nop 0
	global_load_lds_dwordx4 v156, s[44:45]
	s_waitcnt vmcnt(9)
	s_waitcnt lgkmcnt(0)
	s_barrier
	s_waitcnt lgkmcnt(0)
	v_mfma_f32_16x16x32_bf16 v[126:129], v[130:133], v[184:187], 0
	v_mfma_f32_16x16x32_bf16 v[122:125], v[138:141], v[184:187], 0
	v_mfma_f32_16x16x32_bf16 v[110:113], v[130:133], v[192:195], 0
	v_mfma_f32_16x16x32_bf16 v[106:109], v[138:141], v[192:195], 0
	v_mfma_f32_16x16x32_bf16 v[94:97], v[130:133], v[200:203], 0
	v_mfma_f32_16x16x32_bf16 v[90:93], v[138:141], v[200:203], 0
	v_mfma_f32_16x16x32_bf16 v[78:81], v[130:133], v[208:211], 0
	v_mfma_f32_16x16x32_bf16 v[74:77], v[138:141], v[208:211], 0
	v_mfma_f32_16x16x32_bf16 v[126:129], v[134:137], v[188:191], v[126:129]
	v_mfma_f32_16x16x32_bf16 v[122:125], v[142:145], v[188:191], v[122:125]
	v_mfma_f32_16x16x32_bf16 v[110:113], v[134:137], v[196:199], v[110:113]
	v_mfma_f32_16x16x32_bf16 v[106:109], v[142:145], v[196:199], v[106:109]
	v_mfma_f32_16x16x32_bf16 v[94:97], v[134:137], v[204:207], v[94:97]
	v_mfma_f32_16x16x32_bf16 v[90:93], v[142:145], v[204:207], v[90:93]
	v_mfma_f32_16x16x32_bf16 v[78:81], v[134:137], v[212:215], v[78:81]
	v_mfma_f32_16x16x32_bf16 v[74:77], v[142:145], v[212:215], v[74:77]
	v_mfma_f32_16x16x32_bf16 v[118:121], v[162:165], v[184:187], 0
	v_mfma_f32_16x16x32_bf16 v[114:117], v[176:179], v[184:187], 0
	v_mfma_f32_16x16x32_bf16 v[102:105], v[162:165], v[192:195], 0
	v_mfma_f32_16x16x32_bf16 v[98:101], v[176:179], v[192:195], 0
	v_mfma_f32_16x16x32_bf16 v[86:89], v[162:165], v[200:203], 0
	v_mfma_f32_16x16x32_bf16 v[82:85], v[176:179], v[200:203], 0
	v_mfma_f32_16x16x32_bf16 v[70:73], v[162:165], v[208:211], 0
	v_mfma_f32_16x16x32_bf16 v[66:69], v[176:179], v[208:211], 0
	v_mfma_f32_16x16x32_bf16 v[118:121], v[166:169], v[188:191], v[118:121]
	v_mfma_f32_16x16x32_bf16 v[114:117], v[180:183], v[188:191], v[114:117]
	v_mfma_f32_16x16x32_bf16 v[102:105], v[166:169], v[196:199], v[102:105]
	v_mfma_f32_16x16x32_bf16 v[98:101], v[180:183], v[196:199], v[98:101]
	v_mfma_f32_16x16x32_bf16 v[86:89], v[166:169], v[204:207], v[86:89]
	v_mfma_f32_16x16x32_bf16 v[82:85], v[180:183], v[204:207], v[82:85]
	v_mfma_f32_16x16x32_bf16 v[70:73], v[166:169], v[212:215], v[70:73]
	v_mfma_f32_16x16x32_bf16 v[66:69], v[180:183], v[212:215], v[66:69]
	s_barrier
	s_add_i32 s18, s66, s58
	s_add_u32 s78, s46, s16
	s_addc_u32 s79, s47, s17
	s_mov_b32 m0, s18
	ds_read_b128 v[184:187], v174 offset:16384
	ds_read_b128 v[188:191], v174 offset:17408
	ds_read_b128 v[192:195], v174 offset:18432
	ds_read_b128 v[196:199], v174 offset:19456
	ds_read_b128 v[200:203], v174 offset:20480
	ds_read_b128 v[204:207], v174 offset:21504
	ds_read_b128 v[208:211], v174 offset:22528
	ds_read_b128 v[212:215], v174 offset:23552
	global_load_lds_dwordx4 v150, s[46:47]
	s_add_i32 m0, s18, 0x2000
	s_add_u32 s76, s46, 0x80000
	s_addc_u32 s77, s47, 0
	s_add_i32 s18, s67, s58
	global_load_lds_dwordx4 v146, s[46:47]
	s_mov_b32 m0, s18
	s_nop 0
	global_load_lds_dwordx4 v150, s[76:77]
	s_add_i32 m0, s18, 0x2000
	s_nop 0
	global_load_lds_dwordx4 v146, s[76:77]
	s_add_u32 s80, s48, s16
	s_addc_u32 s81, s49, s17
	s_mov_b32 m0, s43
	s_nop 0
	global_load_lds_dwordx4 v152, s[48:49]
	s_mov_b32 m0, s59
	s_nop 0
	global_load_lds_dwordx4 v148, s[48:49]
	global_load_dword v247, v[248:249], off
	v_lshl_add_u64 v[248:249], v[248:249], 0, s[90:91]
	s_waitcnt vmcnt(9)
	s_waitcnt lgkmcnt(0)
	s_barrier
; #define PG8_STAGE(bufoff, gbase, voff) do { _Pragma("unroll") for (int _i = 0; _i < 2; ++_i) \
;         __builtin_amdgcn_global_load_lds((const unsigned*)((const char*)(gbase) + (voff)[_i]), (PG8_LAS unsigned*)(lds + (bufoff) + ldsw + _i * 8192), 16, 0, 0); } while (0)
; #define PG8_LDA(dst, b, h) do { _Pragma("unroll") for (int m = 0; m < 4; ++m) _Pragma("unroll") for (int k = 0; k < 2; ++k) dst[m][k] = *(const PG8_LAS bf16x8*)(lds + PG8_SA(b, h) + aoff + m * 2048 + k * 1024); } while (0)
; #define PG8_LDB(dst, b, h) do { _Pragma("unroll") for (int n = 0; n < 2; ++n) _Pragma("unroll") for (int k = 0; k < 2; ++k) dst[n][k] = *(const PG8_LAS bf16x8*)(lds + PG8_SB(b, h) + boff + n * 2048 + k * 1024); } while (0)
; #define PG8_MMA(ai, bj, At, Bt) do { __builtin_amdgcn_s_setprio(1); _Pragma("unroll") for (int m = 0; m < 4; ++m) _Pragma("unroll") for (int n = 0; n < 2; ++n) _Pragma("unroll") for (int k = 0; k < 2; ++k) \
;         acc[ai][bj][m][n] = __builtin_amdgcn_mfma_f32_16x16x32_bf16(Bt[n][k], At[m][k], acc[ai][bj][m][n], 0, 0, 0); __builtin_amdgcn_s_setprio(0); } while (0)
; #define PG8_WAIT_V(n) asm volatile("s_waitcnt vmcnt(" #n ")" ::: "memory")
; #define PG8_WAIT_L(n) asm volatile("s_waitcnt lgkmcnt(" #n ")" ::: "memory")
; #define PG8_BAR __builtin_amdgcn_s_barrier()
; #define PG8_SCHED __builtin_amdgcn_sched_barrier(0)
; template <class Epi, class Sched, bool ALIGN_EPI = false, bool SP2 = false>
; __device__ __forceinline__ void gemm_phase(PG8_LAS unsigned char* lds, const Gemm g, const Sched& S, const Epi& E) {
;     ...
;             PG8_WAIT_V(8); PG8_WAIT_L(0); PG8_BAR; PG8_MMA(0, 0, At, B0); PG8_MMA(0, 1, At, B1); PG8_BAR; PG8_SCHED;
;             PG8_LDA(At, 0, 1); PG8_STAGE(PG8_SB(0, 0), b2, voffB); PG8_STAGE(PG8_SB(0, 1), b2 + hB, voffB); PG8_STAGE(PG8_SA(0, 0), a2, voffA);
;             PG8_WAIT_V(8); PG8_WAIT_L(0); PG8_BAR; PG8_MMA(1, 0, At, B0); PG8_MMA(1, 1, At, B1); PG8_BAR; PG8_SCHED;
;             PG8_LDB(B0, 1, 0); PG8_LDB(B1, 1, 1); PG8_SCHED; PG8_LDA(At, 1, 0); PG8_STAGE(PG8_SA(0, 1), a2 + hA, voffA);
;             PG8_WAIT_V(8); PG8_WAIT_L(0); PG8_BAR; PG8_MMA(0, 0, At, B0); PG8_MMA(0, 1, At, B1); PG8_BAR; PG8_SCHED;
	s_waitcnt lgkmcnt(0)
	v_mfma_f32_16x16x32_bf16 v[62:65], v[130:133], v[184:187], 0
	v_mfma_f32_16x16x32_bf16 v[58:61], v[138:141], v[184:187], 0
	v_mfma_f32_16x16x32_bf16 v[46:49], v[130:133], v[192:195], 0
	v_mfma_f32_16x16x32_bf16 v[42:45], v[138:141], v[192:195], 0
	v_mfma_f32_16x16x32_bf16 v[30:33], v[130:133], v[200:203], 0
	v_mfma_f32_16x16x32_bf16 v[26:29], v[138:141], v[200:203], 0
	v_mfma_f32_16x16x32_bf16 v[14:17], v[130:133], v[208:211], 0
	v_mfma_f32_16x16x32_bf16 v[10:13], v[138:141], v[208:211], 0
	v_mfma_f32_16x16x32_bf16 v[62:65], v[134:137], v[188:191], v[62:65]
	v_mfma_f32_16x16x32_bf16 v[58:61], v[142:145], v[188:191], v[58:61]
	v_mfma_f32_16x16x32_bf16 v[46:49], v[134:137], v[196:199], v[46:49]
	v_mfma_f32_16x16x32_bf16 v[42:45], v[142:145], v[196:199], v[42:45]
	v_mfma_f32_16x16x32_bf16 v[30:33], v[134:137], v[204:207], v[30:33]
	v_mfma_f32_16x16x32_bf16 v[26:29], v[142:145], v[204:207], v[26:29]
	v_mfma_f32_16x16x32_bf16 v[14:17], v[134:137], v[212:215], v[14:17]
	v_mfma_f32_16x16x32_bf16 v[10:13], v[142:145], v[212:215], v[10:13]
	v_mfma_f32_16x16x32_bf16 v[54:57], v[162:165], v[184:187], 0
	v_mfma_f32_16x16x32_bf16 v[50:53], v[176:179], v[184:187], 0
	v_mfma_f32_16x16x32_bf16 v[38:41], v[162:165], v[192:195], 0
	v_mfma_f32_16x16x32_bf16 v[34:37], v[176:179], v[192:195], 0
	v_mfma_f32_16x16x32_bf16 v[22:25], v[162:165], v[200:203], 0
	v_mfma_f32_16x16x32_bf16 v[18:21], v[176:179], v[200:203], 0
	v_mfma_f32_16x16x32_bf16 v[6:9], v[162:165], v[208:211], 0
	v_mfma_f32_16x16x32_bf16 v[2:5], v[176:179], v[208:211], 0
	v_mfma_f32_16x16x32_bf16 v[54:57], v[166:169], v[188:191], v[54:57]
	v_mfma_f32_16x16x32_bf16 v[50:53], v[180:183], v[188:191], v[50:53]
	v_mfma_f32_16x16x32_bf16 v[38:41], v[166:169], v[196:199], v[38:41]
	v_mfma_f32_16x16x32_bf16 v[34:37], v[180:183], v[196:199], v[34:37]
	v_mfma_f32_16x16x32_bf16 v[22:25], v[166:169], v[204:207], v[22:25]
	v_mfma_f32_16x16x32_bf16 v[18:21], v[180:183], v[204:207], v[18:21]
	v_mfma_f32_16x16x32_bf16 v[6:9], v[166:169], v[212:215], v[6:9]
	v_mfma_f32_16x16x32_bf16 v[2:5], v[180:183], v[212:215], v[2:5]
	s_barrier
	s_add_i32 s18, 0, 0x18000
	s_add_i32 s19, 0, 0x1c000
	v_add_u32_e32 v142, s18, v170
	v_add_u32_e32 v175, s19, v170
	ds_read_b128 v[130:133], v142
	ds_read_b128 v[134:137], v142 offset:1024
	ds_read_b128 v[138:141], v142 offset:2048
	ds_read_b128 v[142:145], v142 offset:3072
	ds_read_b128 v[162:165], v175
	ds_read_b128 v[166:169], v175 offset:1024
	ds_read_b128 v[176:179], v175 offset:2048
	ds_read_b128 v[180:183], v175 offset:3072
	s_add_u32 s48, s48, 0x80000
	s_addc_u32 s49, s49, 0
	s_mov_b32 m0, s60
	ds_read_b128 v[184:187], v174 offset:32768
	ds_read_b128 v[188:191], v174 offset:33792
	ds_read_b128 v[192:195], v174 offset:34816
	ds_read_b128 v[196:199], v174 offset:35840
	ds_read_b128 v[200:203], v174 offset:36864
	ds_read_b128 v[204:207], v174 offset:37888
	ds_read_b128 v[208:211], v174 offset:38912
	ds_read_b128 v[212:215], v174 offset:39936
	global_load_lds_dwordx4 v152, s[48:49]
	s_mov_b32 m0, s61
	s_nop 0
	global_load_lds_dwordx4 v148, s[48:49]
	s_waitcnt vmcnt(9)
	s_waitcnt lgkmcnt(0)
	s_barrier
	s_waitcnt lgkmcnt(0)
	v_mfma_f32_16x16x32_bf16 v[126:129], v[130:133], v[184:187], v[126:129]
	v_mfma_f32_16x16x32_bf16 v[122:125], v[138:141], v[184:187], v[122:125]
	v_mfma_f32_16x16x32_bf16 v[110:113], v[130:133], v[192:195], v[110:113]
	v_mfma_f32_16x16x32_bf16 v[106:109], v[138:141], v[192:195], v[106:109]
	v_mfma_f32_16x16x32_bf16 v[94:97], v[130:133], v[200:203], v[94:97]
	v_mfma_f32_16x16x32_bf16 v[90:93], v[138:141], v[200:203], v[90:93]
	v_mfma_f32_16x16x32_bf16 v[78:81], v[130:133], v[208:211], v[78:81]
	v_mfma_f32_16x16x32_bf16 v[74:77], v[138:141], v[208:211], v[74:77]
	v_mfma_f32_16x16x32_bf16 v[126:129], v[134:137], v[188:191], v[126:129]
	v_mfma_f32_16x16x32_bf16 v[122:125], v[142:145], v[188:191], v[122:125]
	v_mfma_f32_16x16x32_bf16 v[110:113], v[134:137], v[196:199], v[110:113]
	v_mfma_f32_16x16x32_bf16 v[106:109], v[142:145], v[196:199], v[106:109]
	v_mfma_f32_16x16x32_bf16 v[94:97], v[134:137], v[204:207], v[94:97]
	v_mfma_f32_16x16x32_bf16 v[90:93], v[142:145], v[204:207], v[90:93]
	v_mfma_f32_16x16x32_bf16 v[78:81], v[134:137], v[212:215], v[78:81]
	v_mfma_f32_16x16x32_bf16 v[74:77], v[142:145], v[212:215], v[74:77]
	v_mfma_f32_16x16x32_bf16 v[118:121], v[162:165], v[184:187], v[118:121]
	v_mfma_f32_16x16x32_bf16 v[114:117], v[176:179], v[184:187], v[114:117]
	v_mfma_f32_16x16x32_bf16 v[102:105], v[162:165], v[192:195], v[102:105]
	v_mfma_f32_16x16x32_bf16 v[98:101], v[176:179], v[192:195], v[98:101]
	v_mfma_f32_16x16x32_bf16 v[86:89], v[162:165], v[200:203], v[86:89]
	v_mfma_f32_16x16x32_bf16 v[82:85], v[176:179], v[200:203], v[82:85]
	v_mfma_f32_16x16x32_bf16 v[70:73], v[162:165], v[208:211], v[70:73]
	v_mfma_f32_16x16x32_bf16 v[66:69], v[176:179], v[208:211], v[66:69]
	v_mfma_f32_16x16x32_bf16 v[118:121], v[166:169], v[188:191], v[118:121]
	v_mfma_f32_16x16x32_bf16 v[114:117], v[180:183], v[188:191], v[114:117]
	v_mfma_f32_16x16x32_bf16 v[102:105], v[166:169], v[196:199], v[102:105]
	v_mfma_f32_16x16x32_bf16 v[98:101], v[180:183], v[196:199], v[98:101]
	v_mfma_f32_16x16x32_bf16 v[86:89], v[166:169], v[204:207], v[86:89]
	v_mfma_f32_16x16x32_bf16 v[82:85], v[180:183], v[204:207], v[82:85]
	v_mfma_f32_16x16x32_bf16 v[70:73], v[166:169], v[212:215], v[70:73]
	v_mfma_f32_16x16x32_bf16 v[66:69], v[180:183], v[212:215], v[66:69]
	s_barrier
; #define PG8_STAGE(bufoff, gbase, voff) do { _Pragma("unroll") for (int _i = 0; _i < 2; ++_i) \
;         __builtin_amdgcn_global_load_lds((const unsigned*)((const char*)(gbase) + (voff)[_i]), (PG8_LAS unsigned*)(lds + (bufoff) + ldsw + _i * 8192), 16, 0, 0); } while (0)
; #define PG8_LDA(dst, b, h) do { _Pragma("unroll") for (int m = 0; m < 4; ++m) _Pragma("unroll") for (int k = 0; k < 2; ++k) dst[m][k] = *(const PG8_LAS bf16x8*)(lds + PG8_SA(b, h) + aoff + m * 2048 + k * 1024); } while (0)
; #define PG8_LDB(dst, b, h) do { _Pragma("unroll") for (int n = 0; n < 2; ++n) _Pragma("unroll") for (int k = 0; k < 2; ++k) dst[n][k] = *(const PG8_LAS bf16x8*)(lds + PG8_SB(b, h) + boff + n * 2048 + k * 1024); } while (0)
; #define PG8_MMA(ai, bj, At, Bt) do { __builtin_amdgcn_s_setprio(1); _Pragma("unroll") for (int m = 0; m < 4; ++m) _Pragma("unroll") for (int n = 0; n < 2; ++n) _Pragma("unroll") for (int k = 0; k < 2; ++k) \
;         acc[ai][bj][m][n] = __builtin_amdgcn_mfma_f32_16x16x32_bf16(Bt[n][k], At[m][k], acc[ai][bj][m][n], 0, 0, 0); __builtin_amdgcn_s_setprio(0); } while (0)
; #define PG8_WAIT_V(n) asm volatile("s_waitcnt vmcnt(" #n ")" ::: "memory")
; #define PG8_WAIT_L(n) asm volatile("s_waitcnt lgkmcnt(" #n ")" ::: "memory")
; #define PG8_BAR __builtin_amdgcn_s_barrier()
; #define PG8_SCHED __builtin_amdgcn_sched_barrier(0)
; template <class Epi, class Sched, bool ALIGN_EPI = false, bool SP2 = false>
; __device__ __forceinline__ void gemm_phase(PG8_LAS unsigned char* lds, const Gemm g, const Sched& S, const Epi& E) {
;     ...
;         for (int t = 0; t < nt; t += 2) {
;             const bool last = (t == nt - 2);
;             const char* a1 = cA + (size_t)(t + 1) * kstep;
;             const char* a2 = last ? nA : cA + (size_t)(t + 2) * kstep; const char* b2 = last ? nB : cB + (size_t)(t + 2) * kstep;
;             const char* a3 = a2 + kstep; const char* b3 = b2 + kstep;
;             if (last && has_next) S.a_ready(nxt);
;             if constexpr (SP2) {
;             PG8_LDB(B0, 0, 0); PG8_LDB(B1, 0, 1); PG8_SCHED; PG8_LDA(At, 0, 0); PG8_STAGE(PG8_SA(1, 1), a1 + hA, voffA);
;     ...
;             PG8_LDA(At, 1, 1); PG8_STAGE(PG8_SB(1, 0), b3, voffB); PG8_STAGE(PG8_SB(1, 1), b3 + hB, voffB); PG8_STAGE(PG8_SA(1, 0), a3, voffA);
;             PG8_WAIT_V(8); PG8_WAIT_L(0); PG8_BAR; PG8_MMA(1, 0, At, B0); PG8_MMA(1, 1, At, B1); PG8_BAR; PG8_SCHED;
	s_add_i32 s18, s18, s58
	s_mov_b32 m0, s18
	ds_read_b128 v[184:187], v174 offset:49152
	ds_read_b128 v[188:191], v174 offset:50176
	ds_read_b128 v[192:195], v174 offset:51200
	ds_read_b128 v[196:199], v174 offset:52224
	ds_read_b128 v[200:203], v174 offset:53248
	ds_read_b128 v[204:207], v174 offset:54272
	ds_read_b128 v[208:211], v174 offset:55296
	ds_read_b128 v[212:215], v174 offset:56320
	global_load_lds_dwordx4 v150, s[78:79]
	s_add_i32 m0, s18, 0x2000
	s_add_u32 s46, s46, 0x80080
	s_addc_u32 s47, s47, 0
	s_add_i32 s18, s19, s58
	global_load_lds_dwordx4 v146, s[78:79]
	s_mov_b32 m0, s18
	s_nop 0
	global_load_lds_dwordx4 v150, s[46:47]
	s_add_i32 m0, s18, 0x2000
	s_nop 0
	global_load_lds_dwordx4 v146, s[46:47]
	s_mov_b32 m0, s63
	s_nop 0
	global_load_lds_dwordx4 v152, s[80:81]
	s_mov_b32 m0, s64
	s_nop 0
	global_load_lds_dwordx4 v148, s[80:81]
	global_load_dword v247, v[248:249], off
	v_lshl_add_u64 v[248:249], v[248:249], 0, s[90:91]
	s_waitcnt vmcnt(10)
	s_waitcnt lgkmcnt(0)
	s_barrier
	s_waitcnt lgkmcnt(0)
	v_mfma_f32_16x16x32_bf16 v[62:65], v[130:133], v[184:187], v[62:65]
	v_mfma_f32_16x16x32_bf16 v[58:61], v[138:141], v[184:187], v[58:61]
	v_mfma_f32_16x16x32_bf16 v[46:49], v[130:133], v[192:195], v[46:49]
	v_mfma_f32_16x16x32_bf16 v[42:45], v[138:141], v[192:195], v[42:45]
	v_mfma_f32_16x16x32_bf16 v[30:33], v[130:133], v[200:203], v[30:33]
	v_mfma_f32_16x16x32_bf16 v[26:29], v[138:141], v[200:203], v[26:29]
	v_mfma_f32_16x16x32_bf16 v[14:17], v[130:133], v[208:211], v[14:17]
	v_mfma_f32_16x16x32_bf16 v[10:13], v[138:141], v[208:211], v[10:13]
	v_mfma_f32_16x16x32_bf16 v[62:65], v[134:137], v[188:191], v[62:65]
	v_mfma_f32_16x16x32_bf16 v[58:61], v[142:145], v[188:191], v[58:61]
	v_mfma_f32_16x16x32_bf16 v[46:49], v[134:137], v[196:199], v[46:49]
	v_mfma_f32_16x16x32_bf16 v[42:45], v[142:145], v[196:199], v[42:45]
	v_mfma_f32_16x16x32_bf16 v[30:33], v[134:137], v[204:207], v[30:33]
	v_mfma_f32_16x16x32_bf16 v[26:29], v[142:145], v[204:207], v[26:29]
	v_mfma_f32_16x16x32_bf16 v[14:17], v[134:137], v[212:215], v[14:17]
	v_mfma_f32_16x16x32_bf16 v[10:13], v[142:145], v[212:215], v[10:13]
	v_mfma_f32_16x16x32_bf16 v[54:57], v[162:165], v[184:187], v[54:57]
	v_mfma_f32_16x16x32_bf16 v[50:53], v[176:179], v[184:187], v[50:53]
	v_mfma_f32_16x16x32_bf16 v[38:41], v[162:165], v[192:195], v[38:41]
	v_mfma_f32_16x16x32_bf16 v[34:37], v[176:179], v[192:195], v[34:37]
	v_mfma_f32_16x16x32_bf16 v[22:25], v[162:165], v[200:203], v[22:25]
	v_mfma_f32_16x16x32_bf16 v[18:21], v[176:179], v[200:203], v[18:21]
	v_mfma_f32_16x16x32_bf16 v[6:9], v[162:165], v[208:211], v[6:9]
	v_mfma_f32_16x16x32_bf16 v[2:5], v[176:179], v[208:211], v[2:5]
	v_mfma_f32_16x16x32_bf16 v[54:57], v[166:169], v[188:191], v[54:57]
	v_mfma_f32_16x16x32_bf16 v[50:53], v[180:183], v[188:191], v[50:53]
	v_mfma_f32_16x16x32_bf16 v[38:41], v[166:169], v[196:199], v[38:41]
	v_mfma_f32_16x16x32_bf16 v[34:37], v[180:183], v[196:199], v[34:37]
	v_mfma_f32_16x16x32_bf16 v[22:25], v[166:169], v[204:207], v[22:25]
	v_mfma_f32_16x16x32_bf16 v[18:21], v[180:183], v[204:207], v[18:21]
	v_mfma_f32_16x16x32_bf16 v[6:9], v[166:169], v[212:215], v[6:9]
	v_mfma_f32_16x16x32_bf16 v[2:5], v[180:183], v[212:215], v[2:5]
	s_barrier
	s_add_i32 s74, s74, 2
	s_add_u32 s44, s44, 0x100
	s_addc_u32 s45, s45, 0
	s_add_u32 s72, s72, 0x100
	s_addc_u32 s73, s73, 0
	s_cmp_gt_u32 s74, 29
.LBB0_888:
	ds_read_b128 v[130:133], v172
	ds_read_b128 v[134:137], v172 offset:1024
	ds_read_b128 v[138:141], v172 offset:2048
	ds_read_b128 v[142:145], v172 offset:3072
	ds_read_b128 v[162:165], v173
	ds_read_b128 v[166:169], v173 offset:1024
	ds_read_b128 v[176:179], v173 offset:2048
	ds_read_b128 v[180:183], v173 offset:3072
	s_add_u32 s18, s44, 0xfff80080
	s_addc_u32 s19, s45, -1
	s_cmp_eq_u32 s74, 28
	s_cselect_b32 s49, s25, s19
	s_cselect_b32 s48, s70, s18
	s_cselect_b32 s47, s23, s73
	s_cselect_b32 s46, s71, s72
	s_cmp_lt_i32 s74, 23
	s_cselect_b32 s90, 0x80, 0
	s_add_i32 m0, s43, 0xc000
	ds_read_b128 v[184:187], v174
	ds_read_b128 v[188:191], v174 offset:1024
	ds_read_b128 v[192:195], v174 offset:2048
	ds_read_b128 v[196:199], v174 offset:3072
	ds_read_b128 v[200:203], v174 offset:4096
	ds_read_b128 v[204:207], v174 offset:5120
	ds_read_b128 v[208:211], v174 offset:6144
	ds_read_b128 v[212:215], v174 offset:7168
	global_load_lds_dwordx4 v154, s[44:45]
	s_add_i32 m0, s43, 0xe000
	s_nop 0
	global_load_lds_dwordx4 v156, s[44:45]
	s_waitcnt vmcnt(9)
	s_waitcnt lgkmcnt(0)
	s_barrier
	s_waitcnt lgkmcnt(0)
	v_mfma_f32_16x16x32_bf16 v[126:129], v[130:133], v[184:187], v[126:129]
	v_mfma_f32_16x16x32_bf16 v[122:125], v[138:141], v[184:187], v[122:125]
	v_mfma_f32_16x16x32_bf16 v[110:113], v[130:133], v[192:195], v[110:113]
	v_mfma_f32_16x16x32_bf16 v[106:109], v[138:141], v[192:195], v[106:109]
	v_mfma_f32_16x16x32_bf16 v[94:97], v[130:133], v[200:203], v[94:97]
	v_mfma_f32_16x16x32_bf16 v[90:93], v[138:141], v[200:203], v[90:93]
	v_mfma_f32_16x16x32_bf16 v[78:81], v[130:133], v[208:211], v[78:81]
	v_mfma_f32_16x16x32_bf16 v[74:77], v[138:141], v[208:211], v[74:77]
	v_mfma_f32_16x16x32_bf16 v[126:129], v[134:137], v[188:191], v[126:129]
	v_mfma_f32_16x16x32_bf16 v[122:125], v[142:145], v[188:191], v[122:125]
	v_mfma_f32_16x16x32_bf16 v[110:113], v[134:137], v[196:199], v[110:113]
	v_mfma_f32_16x16x32_bf16 v[106:109], v[142:145], v[196:199], v[106:109]
	v_mfma_f32_16x16x32_bf16 v[94:97], v[134:137], v[204:207], v[94:97]
	v_mfma_f32_16x16x32_bf16 v[90:93], v[142:145], v[204:207], v[90:93]
	v_mfma_f32_16x16x32_bf16 v[78:81], v[134:137], v[212:215], v[78:81]
	v_mfma_f32_16x16x32_bf16 v[74:77], v[142:145], v[212:215], v[74:77]
	v_mfma_f32_16x16x32_bf16 v[118:121], v[162:165], v[184:187], v[118:121]
	v_mfma_f32_16x16x32_bf16 v[114:117], v[176:179], v[184:187], v[114:117]
	v_mfma_f32_16x16x32_bf16 v[102:105], v[162:165], v[192:195], v[102:105]
	v_mfma_f32_16x16x32_bf16 v[98:101], v[176:179], v[192:195], v[98:101]
	v_mfma_f32_16x16x32_bf16 v[86:89], v[162:165], v[200:203], v[86:89]
	v_mfma_f32_16x16x32_bf16 v[82:85], v[176:179], v[200:203], v[82:85]
	v_mfma_f32_16x16x32_bf16 v[70:73], v[162:165], v[208:211], v[70:73]
	v_mfma_f32_16x16x32_bf16 v[66:69], v[176:179], v[208:211], v[66:69]
	v_mfma_f32_16x16x32_bf16 v[118:121], v[166:169], v[188:191], v[118:121]
	v_mfma_f32_16x16x32_bf16 v[114:117], v[180:183], v[188:191], v[114:117]
	v_mfma_f32_16x16x32_bf16 v[102:105], v[166:169], v[196:199], v[102:105]
	v_mfma_f32_16x16x32_bf16 v[98:101], v[180:183], v[196:199], v[98:101]
	v_mfma_f32_16x16x32_bf16 v[86:89], v[166:169], v[204:207], v[86:89]
	v_mfma_f32_16x16x32_bf16 v[82:85], v[180:183], v[204:207], v[82:85]
	v_mfma_f32_16x16x32_bf16 v[70:73], v[166:169], v[212:215], v[70:73]
	v_mfma_f32_16x16x32_bf16 v[66:69], v[180:183], v[212:215], v[66:69]
	s_barrier
; #define PG8_STAGE(bufoff, gbase, voff) do { _Pragma("unroll") for (int _i = 0; _i < 2; ++_i) \
;         __builtin_amdgcn_global_load_lds((const unsigned*)((const char*)(gbase) + (voff)[_i]), (PG8_LAS unsigned*)(lds + (bufoff) + ldsw + _i * 8192), 16, 0, 0); } while (0)
; #define PG8_LDA(dst, b, h) do { _Pragma("unroll") for (int m = 0; m < 4; ++m) _Pragma("unroll") for (int k = 0; k < 2; ++k) dst[m][k] = *(const PG8_LAS bf16x8*)(lds + PG8_SA(b, h) + aoff + m * 2048 + k * 1024); } while (0)
; #define PG8_LDB(dst, b, h) do { _Pragma("unroll") for (int n = 0; n < 2; ++n) _Pragma("unroll") for (int k = 0; k < 2; ++k) dst[n][k] = *(const PG8_LAS bf16x8*)(lds + PG8_SB(b, h) + boff + n * 2048 + k * 1024); } while (0)
; #define PG8_MMA(ai, bj, At, Bt) do { __builtin_amdgcn_s_setprio(1); _Pragma("unroll") for (int m = 0; m < 4; ++m) _Pragma("unroll") for (int n = 0; n < 2; ++n) _Pragma("unroll") for (int k = 0; k < 2; ++k) \
;         acc[ai][bj][m][n] = __builtin_amdgcn_mfma_f32_16x16x32_bf16(Bt[n][k], At[m][k], acc[ai][bj][m][n], 0, 0, 0); __builtin_amdgcn_s_setprio(0); } while (0)
; #define PG8_WAIT_V(n) asm volatile("s_waitcnt vmcnt(" #n ")" ::: "memory")
; #define PG8_WAIT_L(n) asm volatile("s_waitcnt lgkmcnt(" #n ")" ::: "memory")
; #define PG8_BAR __builtin_amdgcn_s_barrier()
; #define PG8_SCHED __builtin_amdgcn_sched_barrier(0)
; template <class Epi, class Sched, bool ALIGN_EPI = false, bool SP2 = false>
; __device__ __forceinline__ void gemm_phase(PG8_LAS unsigned char* lds, const Gemm g, const Sched& S, const Epi& E) {
;     ...
;             PG8_WAIT_V(8); PG8_WAIT_L(0); PG8_BAR; PG8_MMA(0, 0, At, B0); PG8_MMA(0, 1, At, B1); PG8_BAR; PG8_SCHED;
;             PG8_LDA(At, 0, 1); PG8_STAGE(PG8_SB(0, 0), b2, voffB); PG8_STAGE(PG8_SB(0, 1), b2 + hB, voffB); PG8_STAGE(PG8_SA(0, 0), a2, voffA);
;             PG8_WAIT_V(8); PG8_WAIT_L(0); PG8_BAR; PG8_MMA(1, 0, At, B0); PG8_MMA(1, 1, At, B1); PG8_BAR; PG8_SCHED;
;             PG8_LDB(B0, 1, 0); PG8_LDB(B1, 1, 1); PG8_SCHED; PG8_LDA(At, 1, 0); PG8_STAGE(PG8_SA(0, 1), a2 + hA, voffA);
;             PG8_WAIT_V(8); PG8_WAIT_L(0); PG8_BAR; PG8_MMA(0, 0, At, B0); PG8_MMA(0, 1, At, B1); PG8_BAR; PG8_SCHED;
;             PG8_LDA(At, 1, 1); PG8_STAGE(PG8_SB(1, 0), b3, voffB); PG8_STAGE(PG8_SB(1, 1), b3 + hB, voffB); PG8_STAGE(PG8_SA(1, 0), a3, voffA);
	s_add_i32 s18, s66, s58
	s_add_u32 s78, s46, s16
	s_addc_u32 s79, s47, s17
	s_mov_b32 m0, s18
	ds_read_b128 v[184:187], v174 offset:16384
	ds_read_b128 v[188:191], v174 offset:17408
	ds_read_b128 v[192:195], v174 offset:18432
	ds_read_b128 v[196:199], v174 offset:19456
	ds_read_b128 v[200:203], v174 offset:20480
	ds_read_b128 v[204:207], v174 offset:21504
	ds_read_b128 v[208:211], v174 offset:22528
	ds_read_b128 v[212:215], v174 offset:23552
	global_load_lds_dwordx4 v150, s[46:47]
	s_add_i32 m0, s18, 0x2000
	s_add_u32 s76, s46, 0x80000
	s_addc_u32 s77, s47, 0
	s_add_i32 s18, s67, s58
	global_load_lds_dwordx4 v146, s[46:47]
	s_mov_b32 m0, s18
	s_nop 0
	global_load_lds_dwordx4 v150, s[76:77]
	s_add_i32 m0, s18, 0x2000
	s_nop 0
	global_load_lds_dwordx4 v146, s[76:77]
	s_add_u32 s80, s48, s16
	s_addc_u32 s81, s49, s17
	s_mov_b32 m0, s43
	s_nop 0
	global_load_lds_dwordx4 v152, s[48:49]
	s_mov_b32 m0, s59
	s_nop 0
	global_load_lds_dwordx4 v148, s[48:49]
	global_load_dword v247, v[248:249], off
	v_lshl_add_u64 v[248:249], v[248:249], 0, s[90:91]
	s_waitcnt vmcnt(10)
	s_waitcnt lgkmcnt(0)
	s_barrier
	s_waitcnt lgkmcnt(0)
	v_mfma_f32_16x16x32_bf16 v[62:65], v[130:133], v[184:187], v[62:65]
	v_mfma_f32_16x16x32_bf16 v[58:61], v[138:141], v[184:187], v[58:61]
	v_mfma_f32_16x16x32_bf16 v[46:49], v[130:133], v[192:195], v[46:49]
	v_mfma_f32_16x16x32_bf16 v[42:45], v[138:141], v[192:195], v[42:45]
	v_mfma_f32_16x16x32_bf16 v[30:33], v[130:133], v[200:203], v[30:33]
	v_mfma_f32_16x16x32_bf16 v[26:29], v[138:141], v[200:203], v[26:29]
	v_mfma_f32_16x16x32_bf16 v[14:17], v[130:133], v[208:211], v[14:17]
	v_mfma_f32_16x16x32_bf16 v[10:13], v[138:141], v[208:211], v[10:13]
	v_mfma_f32_16x16x32_bf16 v[62:65], v[134:137], v[188:191], v[62:65]
	v_mfma_f32_16x16x32_bf16 v[58:61], v[142:145], v[188:191], v[58:61]
	v_mfma_f32_16x16x32_bf16 v[46:49], v[134:137], v[196:199], v[46:49]
	v_mfma_f32_16x16x32_bf16 v[42:45], v[142:145], v[196:199], v[42:45]
	v_mfma_f32_16x16x32_bf16 v[30:33], v[134:137], v[204:207], v[30:33]
	v_mfma_f32_16x16x32_bf16 v[26:29], v[142:145], v[204:207], v[26:29]
	v_mfma_f32_16x16x32_bf16 v[14:17], v[134:137], v[212:215], v[14:17]
	v_mfma_f32_16x16x32_bf16 v[10:13], v[142:145], v[212:215], v[10:13]
	v_mfma_f32_16x16x32_bf16 v[54:57], v[162:165], v[184:187], v[54:57]
	v_mfma_f32_16x16x32_bf16 v[50:53], v[176:179], v[184:187], v[50:53]
	v_mfma_f32_16x16x32_bf16 v[38:41], v[162:165], v[192:195], v[38:41]
	v_mfma_f32_16x16x32_bf16 v[34:37], v[176:179], v[192:195], v[34:37]
	v_mfma_f32_16x16x32_bf16 v[22:25], v[162:165], v[200:203], v[22:25]
	v_mfma_f32_16x16x32_bf16 v[18:21], v[176:179], v[200:203], v[18:21]
	v_mfma_f32_16x16x32_bf16 v[6:9], v[162:165], v[208:211], v[6:9]
	v_mfma_f32_16x16x32_bf16 v[2:5], v[176:179], v[208:211], v[2:5]
	v_mfma_f32_16x16x32_bf16 v[54:57], v[166:169], v[188:191], v[54:57]
	v_mfma_f32_16x16x32_bf16 v[50:53], v[180:183], v[188:191], v[50:53]
	v_mfma_f32_16x16x32_bf16 v[38:41], v[166:169], v[196:199], v[38:41]
	v_mfma_f32_16x16x32_bf16 v[34:37], v[180:183], v[196:199], v[34:37]
	v_mfma_f32_16x16x32_bf16 v[22:25], v[166:169], v[204:207], v[22:25]
	v_mfma_f32_16x16x32_bf16 v[18:21], v[180:183], v[204:207], v[18:21]
	v_mfma_f32_16x16x32_bf16 v[6:9], v[166:169], v[212:215], v[6:9]
	v_mfma_f32_16x16x32_bf16 v[2:5], v[180:183], v[212:215], v[2:5]
	s_barrier
	s_add_i32 s18, 0, 0x18000
	s_add_i32 s19, 0, 0x1c000
	v_add_u32_e32 v142, s18, v170
	v_add_u32_e32 v175, s19, v170
	ds_read_b128 v[130:133], v142
	ds_read_b128 v[134:137], v142 offset:1024
	ds_read_b128 v[138:141], v142 offset:2048
	ds_read_b128 v[142:145], v142 offset:3072
	ds_read_b128 v[162:165], v175
	ds_read_b128 v[166:169], v175 offset:1024
	ds_read_b128 v[176:179], v175 offset:2048
	ds_read_b128 v[180:183], v175 offset:3072
	s_add_u32 s48, s48, 0x80000
	s_addc_u32 s49, s49, 0
	s_mov_b32 m0, s60
	ds_read_b128 v[184:187], v174 offset:32768
	ds_read_b128 v[188:191], v174 offset:33792
	ds_read_b128 v[192:195], v174 offset:34816
	ds_read_b128 v[196:199], v174 offset:35840
	ds_read_b128 v[200:203], v174 offset:36864
	ds_read_b128 v[204:207], v174 offset:37888
	ds_read_b128 v[208:211], v174 offset:38912
	ds_read_b128 v[212:215], v174 offset:39936
	global_load_lds_dwordx4 v152, s[48:49]
	s_mov_b32 m0, s61
	s_nop 0
	global_load_lds_dwordx4 v148, s[48:49]
	s_waitcnt vmcnt(9)
	s_waitcnt lgkmcnt(0)
	s_barrier
; #define PG8_STAGE(bufoff, gbase, voff) do { _Pragma("unroll") for (int _i = 0; _i < 2; ++_i) \
;         __builtin_amdgcn_global_load_lds((const unsigned*)((const char*)(gbase) + (voff)[_i]), (PG8_LAS unsigned*)(lds + (bufoff) + ldsw + _i * 8192), 16, 0, 0); } while (0)
; #define PG8_LDA(dst, b, h) do { _Pragma("unroll") for (int m = 0; m < 4; ++m) _Pragma("unroll") for (int k = 0; k < 2; ++k) dst[m][k] = *(const PG8_LAS bf16x8*)(lds + PG8_SA(b, h) + aoff + m * 2048 + k * 1024); } while (0)
; #define PG8_MMA(ai, bj, At, Bt) do { __builtin_amdgcn_s_setprio(1); _Pragma("unroll") for (int m = 0; m < 4; ++m) _Pragma("unroll") for (int n = 0; n < 2; ++n) _Pragma("unroll") for (int k = 0; k < 2; ++k) \
;         acc[ai][bj][m][n] = __builtin_amdgcn_mfma_f32_16x16x32_bf16(Bt[n][k], At[m][k], acc[ai][bj][m][n], 0, 0, 0); __builtin_amdgcn_s_setprio(0); } while (0)
; #define PG8_WAIT_V(n) asm volatile("s_waitcnt vmcnt(" #n ")" ::: "memory")
; #define PG8_WAIT_L(n) asm volatile("s_waitcnt lgkmcnt(" #n ")" ::: "memory")
; #define PG8_BAR __builtin_amdgcn_s_barrier()
; #define PG8_SCHED __builtin_amdgcn_sched_barrier(0)
; template <class Epi, class Sched, bool ALIGN_EPI = false, bool SP2 = false>
; __device__ __forceinline__ void gemm_phase(PG8_LAS unsigned char* lds, const Gemm g, const Sched& S, const Epi& E) {
;     ...
;             PG8_WAIT_V(8); PG8_WAIT_L(0); PG8_BAR; PG8_MMA(0, 0, At, B0); PG8_MMA(0, 1, At, B1); PG8_BAR; PG8_SCHED;
;             PG8_LDA(At, 1, 1); PG8_STAGE(PG8_SB(1, 0), b3, voffB); PG8_STAGE(PG8_SB(1, 1), b3 + hB, voffB); PG8_STAGE(PG8_SA(1, 0), a3, voffA);
;             PG8_WAIT_V(8); PG8_WAIT_L(0); PG8_BAR; PG8_MMA(1, 0, At, B0); PG8_MMA(1, 1, At, B1); PG8_BAR; PG8_SCHED;
;     ...
;         if constexpr (ALIGN_EPI) { if (wr == 0) PG8_BAR; }
;         if constexpr (!Epi::AFTER_DRAIN) { E(acc, cur, wr, wc, fr, fq); S.done(cur); }
;         if (!has_next) break;
	s_waitcnt lgkmcnt(0)
	v_mfma_f32_16x16x32_bf16 v[126:129], v[130:133], v[184:187], v[126:129]
	v_mfma_f32_16x16x32_bf16 v[122:125], v[138:141], v[184:187], v[122:125]
	v_mfma_f32_16x16x32_bf16 v[110:113], v[130:133], v[192:195], v[110:113]
	v_mfma_f32_16x16x32_bf16 v[106:109], v[138:141], v[192:195], v[106:109]
	v_mfma_f32_16x16x32_bf16 v[94:97], v[130:133], v[200:203], v[94:97]
	v_mfma_f32_16x16x32_bf16 v[90:93], v[138:141], v[200:203], v[90:93]
	v_mfma_f32_16x16x32_bf16 v[78:81], v[130:133], v[208:211], v[78:81]
	v_mfma_f32_16x16x32_bf16 v[74:77], v[138:141], v[208:211], v[74:77]
	v_mfma_f32_16x16x32_bf16 v[126:129], v[134:137], v[188:191], v[126:129]
	v_mfma_f32_16x16x32_bf16 v[122:125], v[142:145], v[188:191], v[122:125]
	v_mfma_f32_16x16x32_bf16 v[110:113], v[134:137], v[196:199], v[110:113]
	v_mfma_f32_16x16x32_bf16 v[106:109], v[142:145], v[196:199], v[106:109]
	v_mfma_f32_16x16x32_bf16 v[94:97], v[134:137], v[204:207], v[94:97]
	v_mfma_f32_16x16x32_bf16 v[90:93], v[142:145], v[204:207], v[90:93]
	v_mfma_f32_16x16x32_bf16 v[78:81], v[134:137], v[212:215], v[78:81]
	v_mfma_f32_16x16x32_bf16 v[74:77], v[142:145], v[212:215], v[74:77]
	v_mfma_f32_16x16x32_bf16 v[118:121], v[162:165], v[184:187], v[118:121]
	v_mfma_f32_16x16x32_bf16 v[114:117], v[176:179], v[184:187], v[114:117]
	v_mfma_f32_16x16x32_bf16 v[102:105], v[162:165], v[192:195], v[102:105]
	v_mfma_f32_16x16x32_bf16 v[98:101], v[176:179], v[192:195], v[98:101]
	v_mfma_f32_16x16x32_bf16 v[86:89], v[162:165], v[200:203], v[86:89]
	v_mfma_f32_16x16x32_bf16 v[82:85], v[176:179], v[200:203], v[82:85]
	v_mfma_f32_16x16x32_bf16 v[70:73], v[162:165], v[208:211], v[70:73]
	v_mfma_f32_16x16x32_bf16 v[66:69], v[176:179], v[208:211], v[66:69]
	v_mfma_f32_16x16x32_bf16 v[118:121], v[166:169], v[188:191], v[118:121]
	v_mfma_f32_16x16x32_bf16 v[114:117], v[180:183], v[188:191], v[114:117]
	v_mfma_f32_16x16x32_bf16 v[102:105], v[166:169], v[196:199], v[102:105]
	v_mfma_f32_16x16x32_bf16 v[98:101], v[180:183], v[196:199], v[98:101]
	v_mfma_f32_16x16x32_bf16 v[86:89], v[166:169], v[204:207], v[86:89]
	v_mfma_f32_16x16x32_bf16 v[82:85], v[180:183], v[204:207], v[82:85]
	v_mfma_f32_16x16x32_bf16 v[70:73], v[166:169], v[212:215], v[70:73]
	v_mfma_f32_16x16x32_bf16 v[66:69], v[180:183], v[212:215], v[66:69]
	s_barrier
	s_add_i32 s18, s18, s58
	s_mov_b32 m0, s18
	ds_read_b128 v[184:187], v174 offset:49152
	ds_read_b128 v[188:191], v174 offset:50176
	ds_read_b128 v[192:195], v174 offset:51200
	ds_read_b128 v[196:199], v174 offset:52224
	ds_read_b128 v[200:203], v174 offset:53248
	ds_read_b128 v[204:207], v174 offset:54272
	ds_read_b128 v[208:211], v174 offset:55296
	ds_read_b128 v[212:215], v174 offset:56320
	global_load_lds_dwordx4 v150, s[78:79]
	s_add_i32 m0, s18, 0x2000
	s_add_u32 s46, s46, 0x80080
	s_addc_u32 s47, s47, 0
	s_add_i32 s18, s19, s58
	global_load_lds_dwordx4 v146, s[78:79]
	s_mov_b32 m0, s18
	s_nop 0
	global_load_lds_dwordx4 v150, s[46:47]
	s_add_i32 m0, s18, 0x2000
	s_nop 0
	global_load_lds_dwordx4 v146, s[46:47]
	s_mov_b32 m0, s63
	s_nop 0
	global_load_lds_dwordx4 v152, s[80:81]
	s_mov_b32 m0, s64
	s_nop 0
	global_load_lds_dwordx4 v148, s[80:81]
	global_load_dword v247, v[248:249], off
	v_lshl_add_u64 v[248:249], v[248:249], 0, s[90:91]
	s_waitcnt vmcnt(10)
	s_waitcnt lgkmcnt(0)
	s_barrier
	s_waitcnt lgkmcnt(0)
	v_mfma_f32_16x16x32_bf16 v[62:65], v[130:133], v[184:187], v[62:65]
	v_mfma_f32_16x16x32_bf16 v[58:61], v[138:141], v[184:187], v[58:61]
	v_mfma_f32_16x16x32_bf16 v[46:49], v[130:133], v[192:195], v[46:49]
	v_mfma_f32_16x16x32_bf16 v[42:45], v[138:141], v[192:195], v[42:45]
	v_mfma_f32_16x16x32_bf16 v[30:33], v[130:133], v[200:203], v[30:33]
	v_mfma_f32_16x16x32_bf16 v[26:29], v[138:141], v[200:203], v[26:29]
	v_mfma_f32_16x16x32_bf16 v[14:17], v[130:133], v[208:211], v[14:17]
	v_mfma_f32_16x16x32_bf16 v[10:13], v[138:141], v[208:211], v[10:13]
	v_mfma_f32_16x16x32_bf16 v[62:65], v[134:137], v[188:191], v[62:65]
	v_mfma_f32_16x16x32_bf16 v[58:61], v[142:145], v[188:191], v[58:61]
	v_mfma_f32_16x16x32_bf16 v[46:49], v[134:137], v[196:199], v[46:49]
	v_mfma_f32_16x16x32_bf16 v[42:45], v[142:145], v[196:199], v[42:45]
	v_mfma_f32_16x16x32_bf16 v[30:33], v[134:137], v[204:207], v[30:33]
	v_mfma_f32_16x16x32_bf16 v[26:29], v[142:145], v[204:207], v[26:29]
	v_mfma_f32_16x16x32_bf16 v[14:17], v[134:137], v[212:215], v[14:17]
	v_mfma_f32_16x16x32_bf16 v[10:13], v[142:145], v[212:215], v[10:13]
	v_mfma_f32_16x16x32_bf16 v[54:57], v[162:165], v[184:187], v[54:57]
	v_mfma_f32_16x16x32_bf16 v[50:53], v[176:179], v[184:187], v[50:53]
	v_mfma_f32_16x16x32_bf16 v[38:41], v[162:165], v[192:195], v[38:41]
	v_mfma_f32_16x16x32_bf16 v[34:37], v[176:179], v[192:195], v[34:37]
	v_mfma_f32_16x16x32_bf16 v[22:25], v[162:165], v[200:203], v[22:25]
	v_mfma_f32_16x16x32_bf16 v[18:21], v[176:179], v[200:203], v[18:21]
	v_mfma_f32_16x16x32_bf16 v[6:9], v[162:165], v[208:211], v[6:9]
	v_mfma_f32_16x16x32_bf16 v[2:5], v[176:179], v[208:211], v[2:5]
	v_mfma_f32_16x16x32_bf16 v[54:57], v[166:169], v[188:191], v[54:57]
	v_mfma_f32_16x16x32_bf16 v[50:53], v[180:183], v[188:191], v[50:53]
	v_mfma_f32_16x16x32_bf16 v[38:41], v[166:169], v[196:199], v[38:41]
	v_mfma_f32_16x16x32_bf16 v[34:37], v[180:183], v[196:199], v[34:37]
	v_mfma_f32_16x16x32_bf16 v[22:25], v[166:169], v[204:207], v[22:25]
	v_mfma_f32_16x16x32_bf16 v[18:21], v[180:183], v[204:207], v[18:21]
	v_mfma_f32_16x16x32_bf16 v[6:9], v[166:169], v[212:215], v[6:9]
	v_mfma_f32_16x16x32_bf16 v[2:5], v[180:183], v[212:215], v[2:5]
	s_barrier
	s_add_i32 s74, s74, 2
	s_add_u32 s44, s44, 0x100
	s_addc_u32 s45, s45, 0
	s_add_u32 s72, s72, 0x100
	s_addc_u32 s73, s73, 0
	s_cmp_gt_u32 s74, 29
	s_cbranch_scc0 .LBB0_888
	s_and_b64 vcc, exec, s[20:21]
	s_cbranch_vccz .LBB0_891
	s_barrier

; #define PG8_STAGE(bufoff, gbase, voff) do { _Pragma("unroll") for (int _i = 0; _i < 2; ++_i) \
;         __builtin_amdgcn_global_load_lds((const unsigned*)((const char*)(gbase) + (voff)[_i]), (PG8_LAS unsigned*)(lds + (bufoff) + ldsw + _i * 8192), 16, 0, 0); } while (0)
; #define PG8_LDA(dst, b, h) do { _Pragma("unroll") for (int m = 0; m < 4; ++m) _Pragma("unroll") for (int k = 0; k < 2; ++k) dst[m][k] = *(const PG8_LAS bf16x8*)(lds + PG8_SA(b, h) + aoff + m * 2048 + k * 1024); } while (0)
; #define PG8_LDB(dst, b, h) do { _Pragma("unroll") for (int n = 0; n < 2; ++n) _Pragma("unroll") for (int k = 0; k < 2; ++k) dst[n][k] = *(const PG8_LAS bf16x8*)(lds + PG8_SB(b, h) + boff + n * 2048 + k * 1024); } while (0)
; #define PG8_MMA(ai, bj, At, Bt) do { __builtin_amdgcn_s_setprio(1); _Pragma("unroll") for (int m = 0; m < 4; ++m) _Pragma("unroll") for (int n = 0; n < 2; ++n) _Pragma("unroll") for (int k = 0; k < 2; ++k) \
;         acc[ai][bj][m][n] = __builtin_amdgcn_mfma_f32_16x16x32_bf16(Bt[n][k], At[m][k], acc[ai][bj][m][n], 0, 0, 0); __builtin_amdgcn_s_setprio(0); } while (0)
; #define PG8_WAIT_V(n) asm volatile("s_waitcnt vmcnt(" #n ")" ::: "memory")
; #define PG8_BAR __builtin_amdgcn_s_barrier()
; template <class Epi, class Sched, bool ALIGN_EPI = false, bool SP2 = false>
; __device__ __forceinline__ void gemm_phase(PG8_LAS unsigned char* lds, const Gemm g, const Sched& S, const Epi& E) {
;     ...
;     for (;;) {
;         const bool has_next = S.next(ui + 1, nxt);
;         const char* nA = has_next ? (const char*)g.A + (size_t)nxt.pm * tA + (size_t)nxt.pn * pnA : cA; const char* nB = has_next ? (const char*)g.Bt + (size_t)nxt.pn * tB : cB;
; #pragma nounroll
;         for (int t = 0; t < nt; t += 2) {
;             const bool last = (t == nt - 2);
;             const char* a1 = cA + (size_t)(t + 1) * kstep;
;             const char* a2 = last ? nA : cA + (size_t)(t + 2) * kstep; const char* b2 = last ? nB : cB + (size_t)(t + 2) * kstep;
;             const char* a3 = a2 + kstep; const char* b3 = b2 + kstep;
;             if (last && has_next) S.a_ready(nxt);
;             if constexpr (SP2) {
;             PG8_LDB(B0, 0, 0); PG8_LDB(B1, 0, 1); PG8_SCHED; PG8_LDA(At, 0, 0); PG8_STAGE(PG8_SA(1, 1), a1 + hA, voffA);
;             PG8_WAIT_V(8); PG8_WAIT_L(0); PG8_BAR; PG8_MMA(0, 0, At, B0); PG8_MMA(0, 1, At, B1); PG8_BAR; PG8_SCHED;
.LBB0_962:
	s_ashr_i32 s41, s40, 31
	s_lshl_b64 s[42:43], s[40:41], 20
	s_add_u32 s42, s33, s42
	s_addc_u32 s43, s58, s43
	s_and_b64 s[44:45], s[8:9], exec
	s_cselect_b32 s41, s43, s49
	s_cselect_b32 s47, s42, s48
	s_ashr_i32 s39, s38, 31
	s_lshl_b64 s[44:45], s[38:39], 20
	s_add_u32 s44, s59, s44
	s_addc_u32 s45, s60, s45
	s_and_b64 s[52:53], s[8:9], exec
	s_cselect_b32 s39, s45, s51
	s_cselect_b32 s75, s44, s50
	s_add_u32 s48, s48, 0x80080
	s_addc_u32 s49, s49, 0
	s_add_u32 s76, s50, 0x100
	v_mov_b32_e32 v2, 0
	s_addc_u32 s77, s51, 0
	s_mov_b32 s78, -2
	s_waitcnt lgkmcnt(0)
	v_mov_b32_e32 v3, v2
	s_add_u32 s92, s48, 0xfff80180
	s_addc_u32 s93, s49, -1
	v_mov_b32_e32 v248, s92
	v_mov_b32_e32 v249, s93
	s_add_u32 s92, s76, 0x100
	s_addc_u32 s93, s77, 0
	v_mov_b32_e32 v250, s92
	v_mov_b32_e32 v251, s93
	s_mov_b64 s[92:93], 0xff0
	v_cndmask_b32_e64 v248, v248, v250, s[92:93]
	v_cndmask_b32_e64 v249, v249, v251, s[92:93]
	v_and_b32_e32 v247, 63, v0
	v_lshrrev_b32_e32 v250, 6, v0
	v_and_b32_e32 v251, 3, v247
	v_lshl_add_u32 v251, v250, 2, v251
	v_add_u32_e32 v247, 4, v247
	v_and_b32_e32 v247, 7, v247
	v_lshl_add_u32 v247, v250, 3, v247
	s_and_b32 s92, s2, 0xe0
	s_and_b32 s93, s2, 0x18
	s_lshl_b32 s93, s93, 3
	v_add_u32_e32 v251, s92, v251
	v_add_u32_e32 v247, s93, v247
	s_mov_b64 s[92:93], 0xff0
	v_cndmask_b32_e64 v247, v251, v247, s[92:93]
	v_mul_u32_u24_e32 v250, 0x1000, v247
	v_mov_b32_e32 v251, 0
	s_nop 0
	v_lshl_add_u64 v[248:249], v[250:251], 0, v[248:249]
	s_mov_b32 s93, 0
	s_mov_b32 s92, 0x80
	ds_read_b128 v[130:133], v208
	ds_read_b128 v[134:137], v208 offset:1024
	ds_read_b128 v[138:141], v208 offset:2048
	ds_read_b128 v[142:145], v208 offset:3072
	ds_read_b128 v[146:149], v209
	ds_read_b128 v[150:153], v209 offset:1024
	ds_read_b128 v[154:157], v209 offset:2048
	ds_read_b128 v[158:161], v209 offset:3072
	s_add_u32 s18, s48, 0xfff80080
	s_addc_u32 s19, s49, -1
	s_cmp_eq_u32 s78, 28
	s_cselect_b32 s53, s41, s19
	s_cselect_b32 s52, s47, s18
	s_cselect_b32 s51, s39, s77
	s_cselect_b32 s50, s75, s76
	s_cmp_lt_i32 s78, 23
	s_cselect_b32 s92, 0x80, 0
	s_add_i32 m0, s62, 0xc000
	ds_read_b128 v[162:165], v210
	ds_read_b128 v[166:169], v210 offset:1024
	ds_read_b128 v[170:173], v210 offset:2048
	ds_read_b128 v[174:177], v210 offset:3072
	ds_read_b128 v[194:197], v210 offset:4096
	ds_read_b128 v[198:201], v210 offset:5120
	ds_read_b128 v[202:205], v210 offset:6144
	ds_read_b128 v[212:215], v210 offset:7168
	global_load_lds_dwordx4 v186, s[48:49]
	s_add_i32 m0, s62, 0xe000
	s_nop 0
	global_load_lds_dwordx4 v188, s[48:49]
	s_waitcnt vmcnt(9)
	s_waitcnt lgkmcnt(0)
	s_barrier
	s_waitcnt lgkmcnt(0)
	v_mfma_f32_16x16x32_bf16 v[126:129], v[130:133], v[162:165], 0
	v_mfma_f32_16x16x32_bf16 v[122:125], v[138:141], v[162:165], 0
	v_mfma_f32_16x16x32_bf16 v[110:113], v[130:133], v[170:173], 0
	v_mfma_f32_16x16x32_bf16 v[106:109], v[138:141], v[170:173], 0
	v_mfma_f32_16x16x32_bf16 v[94:97], v[130:133], v[194:197], 0
	v_mfma_f32_16x16x32_bf16 v[90:93], v[138:141], v[194:197], 0
	v_mfma_f32_16x16x32_bf16 v[78:81], v[130:133], v[202:205], 0
	v_mfma_f32_16x16x32_bf16 v[74:77], v[138:141], v[202:205], 0
	v_mfma_f32_16x16x32_bf16 v[126:129], v[134:137], v[166:169], v[126:129]
	v_mfma_f32_16x16x32_bf16 v[122:125], v[142:145], v[166:169], v[122:125]
	v_mfma_f32_16x16x32_bf16 v[110:113], v[134:137], v[174:177], v[110:113]
	v_mfma_f32_16x16x32_bf16 v[106:109], v[142:145], v[174:177], v[106:109]
	v_mfma_f32_16x16x32_bf16 v[94:97], v[134:137], v[198:201], v[94:97]
	v_mfma_f32_16x16x32_bf16 v[90:93], v[142:145], v[198:201], v[90:93]
	v_mfma_f32_16x16x32_bf16 v[78:81], v[134:137], v[212:215], v[78:81]
	v_mfma_f32_16x16x32_bf16 v[74:77], v[142:145], v[212:215], v[74:77]
	v_mfma_f32_16x16x32_bf16 v[118:121], v[146:149], v[162:165], 0
	v_mfma_f32_16x16x32_bf16 v[114:117], v[154:157], v[162:165], 0
	v_mfma_f32_16x16x32_bf16 v[102:105], v[146:149], v[170:173], 0
	v_mfma_f32_16x16x32_bf16 v[98:101], v[154:157], v[170:173], 0
	v_mfma_f32_16x16x32_bf16 v[86:89], v[146:149], v[194:197], 0
	v_mfma_f32_16x16x32_bf16 v[82:85], v[154:157], v[194:197], 0
	v_mfma_f32_16x16x32_bf16 v[70:73], v[146:149], v[202:205], 0
	v_mfma_f32_16x16x32_bf16 v[66:69], v[154:157], v[202:205], 0
	v_mfma_f32_16x16x32_bf16 v[118:121], v[150:153], v[166:169], v[118:121]
	v_mfma_f32_16x16x32_bf16 v[114:117], v[158:161], v[166:169], v[114:117]
	v_mfma_f32_16x16x32_bf16 v[102:105], v[150:153], v[174:177], v[102:105]
	v_mfma_f32_16x16x32_bf16 v[98:101], v[158:161], v[174:177], v[98:101]
	v_mfma_f32_16x16x32_bf16 v[86:89], v[150:153], v[198:201], v[86:89]
	v_mfma_f32_16x16x32_bf16 v[82:85], v[158:161], v[198:201], v[82:85]
	v_mfma_f32_16x16x32_bf16 v[70:73], v[150:153], v[212:215], v[70:73]
	v_mfma_f32_16x16x32_bf16 v[66:69], v[158:161], v[212:215], v[66:69]
	s_barrier
	s_add_i32 s18, s72, s61
	s_add_u32 s82, s50, s22
	s_addc_u32 s83, s51, s23
	s_mov_b32 m0, s18
	ds_read_b128 v[162:165], v210 offset:16384
	ds_read_b128 v[166:169], v210 offset:17408
	ds_read_b128 v[170:173], v210 offset:18432
	ds_read_b128 v[174:177], v210 offset:19456
	ds_read_b128 v[194:197], v210 offset:20480
	ds_read_b128 v[198:201], v210 offset:21504
	ds_read_b128 v[202:205], v210 offset:22528
	ds_read_b128 v[212:215], v210 offset:23552
	global_load_lds_dwordx4 v180, s[50:51]
	s_add_i32 m0, s18, 0x2000
	s_add_u32 s80, s50, 0x80000
	s_addc_u32 s81, s51, 0
	s_add_i32 s18, s73, s61
	global_load_lds_dwordx4 v184, s[50:51]
	s_mov_b32 m0, s18
	s_nop 0
	global_load_lds_dwordx4 v180, s[80:81]
	s_add_i32 m0, s18, 0x2000
	s_nop 0
	global_load_lds_dwordx4 v184, s[80:81]
	s_add_u32 s88, s52, s22
	s_addc_u32 s89, s53, s23
	s_mov_b32 m0, s62
	s_nop 0
	global_load_lds_dwordx4 v178, s[52:53]
	s_mov_b32 m0, s63
	s_nop 0
	global_load_lds_dwordx4 v182, s[52:53]
	global_load_dword v247, v[248:249], off
	v_lshl_add_u64 v[248:249], v[248:249], 0, s[92:93]
	s_waitcnt vmcnt(9)
	s_waitcnt lgkmcnt(0)
	s_barrier
; #define PG8_STAGE(bufoff, gbase, voff) do { _Pragma("unroll") for (int _i = 0; _i < 2; ++_i) \
;         __builtin_amdgcn_global_load_lds((const unsigned*)((const char*)(gbase) + (voff)[_i]), (PG8_LAS unsigned*)(lds + (bufoff) + ldsw + _i * 8192), 16, 0, 0); } while (0)
; #define PG8_LDA(dst, b, h) do { _Pragma("unroll") for (int m = 0; m < 4; ++m) _Pragma("unroll") for (int k = 0; k < 2; ++k) dst[m][k] = *(const PG8_LAS bf16x8*)(lds + PG8_SA(b, h) + aoff + m * 2048 + k * 1024); } while (0)
; #define PG8_LDB(dst, b, h) do { _Pragma("unroll") for (int n = 0; n < 2; ++n) _Pragma("unroll") for (int k = 0; k < 2; ++k) dst[n][k] = *(const PG8_LAS bf16x8*)(lds + PG8_SB(b, h) + boff + n * 2048 + k * 1024); } while (0)
; #define PG8_MMA(ai, bj, At, Bt) do { __builtin_amdgcn_s_setprio(1); _Pragma("unroll") for (int m = 0; m < 4; ++m) _Pragma("unroll") for (int n = 0; n < 2; ++n) _Pragma("unroll") for (int k = 0; k < 2; ++k) \
;         acc[ai][bj][m][n] = __builtin_amdgcn_mfma_f32_16x16x32_bf16(Bt[n][k], At[m][k], acc[ai][bj][m][n], 0, 0, 0); __builtin_amdgcn_s_setprio(0); } while (0)
; #define PG8_WAIT_V(n) asm volatile("s_waitcnt vmcnt(" #n ")" ::: "memory")
; #define PG8_WAIT_L(n) asm volatile("s_waitcnt lgkmcnt(" #n ")" ::: "memory")
; #define PG8_BAR __builtin_amdgcn_s_barrier()
; #define PG8_SCHED __builtin_amdgcn_sched_barrier(0)
; template <class Epi, class Sched, bool ALIGN_EPI = false, bool SP2 = false>
; __device__ __forceinline__ void gemm_phase(PG8_LAS unsigned char* lds, const Gemm g, const Sched& S, const Epi& E) {
;     ...
;             PG8_WAIT_V(8); PG8_WAIT_L(0); PG8_BAR; PG8_MMA(0, 0, At, B0); PG8_MMA(0, 1, At, B1); PG8_BAR; PG8_SCHED;
;             PG8_LDA(At, 0, 1); PG8_STAGE(PG8_SB(0, 0), b2, voffB); PG8_STAGE(PG8_SB(0, 1), b2 + hB, voffB); PG8_STAGE(PG8_SA(0, 0), a2, voffA);
;             PG8_WAIT_V(8); PG8_WAIT_L(0); PG8_BAR; PG8_MMA(1, 0, At, B0); PG8_MMA(1, 1, At, B1); PG8_BAR; PG8_SCHED;
;             PG8_LDB(B0, 1, 0); PG8_LDB(B1, 1, 1); PG8_SCHED; PG8_LDA(At, 1, 0); PG8_STAGE(PG8_SA(0, 1), a2 + hA, voffA);
;             PG8_WAIT_V(8); PG8_WAIT_L(0); PG8_BAR; PG8_MMA(0, 0, At, B0); PG8_MMA(0, 1, At, B1); PG8_BAR; PG8_SCHED;
	s_waitcnt lgkmcnt(0)
	v_mfma_f32_16x16x32_bf16 v[62:65], v[130:133], v[162:165], 0
	v_mfma_f32_16x16x32_bf16 v[58:61], v[138:141], v[162:165], 0
	v_mfma_f32_16x16x32_bf16 v[46:49], v[130:133], v[170:173], 0
	v_mfma_f32_16x16x32_bf16 v[42:45], v[138:141], v[170:173], 0
	v_mfma_f32_16x16x32_bf16 v[30:33], v[130:133], v[194:197], 0
	v_mfma_f32_16x16x32_bf16 v[26:29], v[138:141], v[194:197], 0
	v_mfma_f32_16x16x32_bf16 v[14:17], v[130:133], v[202:205], 0
	v_mfma_f32_16x16x32_bf16 v[10:13], v[138:141], v[202:205], 0
	v_mfma_f32_16x16x32_bf16 v[62:65], v[134:137], v[166:169], v[62:65]
	v_mfma_f32_16x16x32_bf16 v[58:61], v[142:145], v[166:169], v[58:61]
	v_mfma_f32_16x16x32_bf16 v[46:49], v[134:137], v[174:177], v[46:49]
	v_mfma_f32_16x16x32_bf16 v[42:45], v[142:145], v[174:177], v[42:45]
	v_mfma_f32_16x16x32_bf16 v[30:33], v[134:137], v[198:201], v[30:33]
	v_mfma_f32_16x16x32_bf16 v[26:29], v[142:145], v[198:201], v[26:29]
	v_mfma_f32_16x16x32_bf16 v[14:17], v[134:137], v[212:215], v[14:17]
	v_mfma_f32_16x16x32_bf16 v[10:13], v[142:145], v[212:215], v[10:13]
	v_mfma_f32_16x16x32_bf16 v[54:57], v[146:149], v[162:165], 0
	v_mfma_f32_16x16x32_bf16 v[50:53], v[154:157], v[162:165], 0
	v_mfma_f32_16x16x32_bf16 v[38:41], v[146:149], v[170:173], 0
	v_mfma_f32_16x16x32_bf16 v[34:37], v[154:157], v[170:173], 0
	v_mfma_f32_16x16x32_bf16 v[22:25], v[146:149], v[194:197], 0
	v_mfma_f32_16x16x32_bf16 v[18:21], v[154:157], v[194:197], 0
	v_mfma_f32_16x16x32_bf16 v[6:9], v[146:149], v[202:205], 0
	v_mfma_f32_16x16x32_bf16 v[2:5], v[154:157], v[202:205], 0
	v_mfma_f32_16x16x32_bf16 v[54:57], v[150:153], v[166:169], v[54:57]
	v_mfma_f32_16x16x32_bf16 v[50:53], v[158:161], v[166:169], v[50:53]
	v_mfma_f32_16x16x32_bf16 v[38:41], v[150:153], v[174:177], v[38:41]
	v_mfma_f32_16x16x32_bf16 v[34:37], v[158:161], v[174:177], v[34:37]
	v_mfma_f32_16x16x32_bf16 v[22:25], v[150:153], v[198:201], v[22:25]
	v_mfma_f32_16x16x32_bf16 v[18:21], v[158:161], v[198:201], v[18:21]
	v_mfma_f32_16x16x32_bf16 v[6:9], v[150:153], v[212:215], v[6:9]
	v_mfma_f32_16x16x32_bf16 v[2:5], v[158:161], v[212:215], v[2:5]
	s_barrier
	s_add_i32 s18, 0, 0x18000
	s_add_i32 s19, 0, 0x1c000
	v_add_u32_e32 v142, s18, v206
	v_add_u32_e32 v158, s19, v206
	ds_read_b128 v[130:133], v142
	ds_read_b128 v[134:137], v142 offset:1024
	ds_read_b128 v[138:141], v142 offset:2048
	ds_read_b128 v[142:145], v142 offset:3072
	ds_read_b128 v[146:149], v158
	ds_read_b128 v[150:153], v158 offset:1024
	ds_read_b128 v[154:157], v158 offset:2048
	ds_read_b128 v[158:161], v158 offset:3072
	s_add_u32 s52, s52, 0x80000
	s_addc_u32 s53, s53, 0
	s_mov_b32 m0, s64
	ds_read_b128 v[162:165], v210 offset:32768
	ds_read_b128 v[166:169], v210 offset:33792
	ds_read_b128 v[170:173], v210 offset:34816
	ds_read_b128 v[174:177], v210 offset:35840
	ds_read_b128 v[194:197], v210 offset:36864
	ds_read_b128 v[198:201], v210 offset:37888
	ds_read_b128 v[202:205], v210 offset:38912
	ds_read_b128 v[212:215], v210 offset:39936
	global_load_lds_dwordx4 v178, s[52:53]
	s_mov_b32 m0, s65
	s_nop 0
	global_load_lds_dwordx4 v182, s[52:53]
	s_waitcnt vmcnt(9)
	s_waitcnt lgkmcnt(0)
	s_barrier
	s_waitcnt lgkmcnt(0)
	v_mfma_f32_16x16x32_bf16 v[126:129], v[130:133], v[162:165], v[126:129]
	v_mfma_f32_16x16x32_bf16 v[122:125], v[138:141], v[162:165], v[122:125]
	v_mfma_f32_16x16x32_bf16 v[110:113], v[130:133], v[170:173], v[110:113]
	v_mfma_f32_16x16x32_bf16 v[106:109], v[138:141], v[170:173], v[106:109]
	v_mfma_f32_16x16x32_bf16 v[94:97], v[130:133], v[194:197], v[94:97]
	v_mfma_f32_16x16x32_bf16 v[90:93], v[138:141], v[194:197], v[90:93]
	v_mfma_f32_16x16x32_bf16 v[78:81], v[130:133], v[202:205], v[78:81]
	v_mfma_f32_16x16x32_bf16 v[74:77], v[138:141], v[202:205], v[74:77]
	v_mfma_f32_16x16x32_bf16 v[126:129], v[134:137], v[166:169], v[126:129]
	v_mfma_f32_16x16x32_bf16 v[122:125], v[142:145], v[166:169], v[122:125]
	v_mfma_f32_16x16x32_bf16 v[110:113], v[134:137], v[174:177], v[110:113]
	v_mfma_f32_16x16x32_bf16 v[106:109], v[142:145], v[174:177], v[106:109]
	v_mfma_f32_16x16x32_bf16 v[94:97], v[134:137], v[198:201], v[94:97]
	v_mfma_f32_16x16x32_bf16 v[90:93], v[142:145], v[198:201], v[90:93]
	v_mfma_f32_16x16x32_bf16 v[78:81], v[134:137], v[212:215], v[78:81]
	v_mfma_f32_16x16x32_bf16 v[74:77], v[142:145], v[212:215], v[74:77]
	v_mfma_f32_16x16x32_bf16 v[118:121], v[146:149], v[162:165], v[118:121]
	v_mfma_f32_16x16x32_bf16 v[114:117], v[154:157], v[162:165], v[114:117]
	v_mfma_f32_16x16x32_bf16 v[102:105], v[146:149], v[170:173], v[102:105]
	v_mfma_f32_16x16x32_bf16 v[98:101], v[154:157], v[170:173], v[98:101]
	v_mfma_f32_16x16x32_bf16 v[86:89], v[146:149], v[194:197], v[86:89]
	v_mfma_f32_16x16x32_bf16 v[82:85], v[154:157], v[194:197], v[82:85]
	v_mfma_f32_16x16x32_bf16 v[70:73], v[146:149], v[202:205], v[70:73]
	v_mfma_f32_16x16x32_bf16 v[66:69], v[154:157], v[202:205], v[66:69]
	v_mfma_f32_16x16x32_bf16 v[118:121], v[150:153], v[166:169], v[118:121]
	v_mfma_f32_16x16x32_bf16 v[114:117], v[158:161], v[166:169], v[114:117]
	v_mfma_f32_16x16x32_bf16 v[102:105], v[150:153], v[174:177], v[102:105]
	v_mfma_f32_16x16x32_bf16 v[98:101], v[158:161], v[174:177], v[98:101]
	v_mfma_f32_16x16x32_bf16 v[86:89], v[150:153], v[198:201], v[86:89]
	v_mfma_f32_16x16x32_bf16 v[82:85], v[158:161], v[198:201], v[82:85]
	v_mfma_f32_16x16x32_bf16 v[70:73], v[150:153], v[212:215], v[70:73]
	v_mfma_f32_16x16x32_bf16 v[66:69], v[158:161], v[212:215], v[66:69]
	s_barrier
; #define PG8_STAGE(bufoff, gbase, voff) do { _Pragma("unroll") for (int _i = 0; _i < 2; ++_i) \
;         __builtin_amdgcn_global_load_lds((const unsigned*)((const char*)(gbase) + (voff)[_i]), (PG8_LAS unsigned*)(lds + (bufoff) + ldsw + _i * 8192), 16, 0, 0); } while (0)
; #define PG8_LDA(dst, b, h) do { _Pragma("unroll") for (int m = 0; m < 4; ++m) _Pragma("unroll") for (int k = 0; k < 2; ++k) dst[m][k] = *(const PG8_LAS bf16x8*)(lds + PG8_SA(b, h) + aoff + m * 2048 + k * 1024); } while (0)
; #define PG8_LDB(dst, b, h) do { _Pragma("unroll") for (int n = 0; n < 2; ++n) _Pragma("unroll") for (int k = 0; k < 2; ++k) dst[n][k] = *(const PG8_LAS bf16x8*)(lds + PG8_SB(b, h) + boff + n * 2048 + k * 1024); } while (0)
; #define PG8_MMA(ai, bj, At, Bt) do { __builtin_amdgcn_s_setprio(1); _Pragma("unroll") for (int m = 0; m < 4; ++m) _Pragma("unroll") for (int n = 0; n < 2; ++n) _Pragma("unroll") for (int k = 0; k < 2; ++k) \
;         acc[ai][bj][m][n] = __builtin_amdgcn_mfma_f32_16x16x32_bf16(Bt[n][k], At[m][k], acc[ai][bj][m][n], 0, 0, 0); __builtin_amdgcn_s_setprio(0); } while (0)
; #define PG8_WAIT_V(n) asm volatile("s_waitcnt vmcnt(" #n ")" ::: "memory")
; #define PG8_WAIT_L(n) asm volatile("s_waitcnt lgkmcnt(" #n ")" ::: "memory")
; #define PG8_BAR __builtin_amdgcn_s_barrier()
; #define PG8_SCHED __builtin_amdgcn_sched_barrier(0)
; template <class Epi, class Sched, bool ALIGN_EPI = false, bool SP2 = false>
; __device__ __forceinline__ void gemm_phase(PG8_LAS unsigned char* lds, const Gemm g, const Sched& S, const Epi& E) {
;     ...
;         for (int t = 0; t < nt; t += 2) {
;             const bool last = (t == nt - 2);
;             const char* a1 = cA + (size_t)(t + 1) * kstep;
;             const char* a2 = last ? nA : cA + (size_t)(t + 2) * kstep; const char* b2 = last ? nB : cB + (size_t)(t + 2) * kstep;
;             const char* a3 = a2 + kstep; const char* b3 = b2 + kstep;
;             if (last && has_next) S.a_ready(nxt);
;             if constexpr (SP2) {
;             PG8_LDB(B0, 0, 0); PG8_LDB(B1, 0, 1); PG8_SCHED; PG8_LDA(At, 0, 0); PG8_STAGE(PG8_SA(1, 1), a1 + hA, voffA);
;     ...
;             PG8_LDA(At, 1, 1); PG8_STAGE(PG8_SB(1, 0), b3, voffB); PG8_STAGE(PG8_SB(1, 1), b3 + hB, voffB); PG8_STAGE(PG8_SA(1, 0), a3, voffA);
;             PG8_WAIT_V(8); PG8_WAIT_L(0); PG8_BAR; PG8_MMA(1, 0, At, B0); PG8_MMA(1, 1, At, B1); PG8_BAR; PG8_SCHED;
	s_add_i32 s18, s18, s61
	s_mov_b32 m0, s18
	ds_read_b128 v[162:165], v210 offset:49152
	ds_read_b128 v[166:169], v210 offset:50176
	ds_read_b128 v[170:173], v210 offset:51200
	ds_read_b128 v[174:177], v210 offset:52224
	ds_read_b128 v[194:197], v210 offset:53248
	ds_read_b128 v[198:201], v210 offset:54272
	ds_read_b128 v[202:205], v210 offset:55296
	ds_read_b128 v[212:215], v210 offset:56320
	global_load_lds_dwordx4 v180, s[82:83]
	s_add_i32 m0, s18, 0x2000
	s_add_u32 s50, s50, 0x80080
	s_addc_u32 s51, s51, 0
	s_add_i32 s18, s19, s61
	global_load_lds_dwordx4 v184, s[82:83]
	s_mov_b32 m0, s18
	s_nop 0
	global_load_lds_dwordx4 v180, s[50:51]
	s_add_i32 m0, s18, 0x2000
	s_nop 0
	global_load_lds_dwordx4 v184, s[50:51]
	s_mov_b32 m0, s69
	s_nop 0
	global_load_lds_dwordx4 v178, s[88:89]
	s_mov_b32 m0, s70
	s_nop 0
	global_load_lds_dwordx4 v182, s[88:89]
	global_load_dword v247, v[248:249], off
	v_lshl_add_u64 v[248:249], v[248:249], 0, s[92:93]
	s_waitcnt vmcnt(10)
	s_waitcnt lgkmcnt(0)
	s_barrier
	s_waitcnt lgkmcnt(0)
	v_mfma_f32_16x16x32_bf16 v[62:65], v[130:133], v[162:165], v[62:65]
	v_mfma_f32_16x16x32_bf16 v[58:61], v[138:141], v[162:165], v[58:61]
	v_mfma_f32_16x16x32_bf16 v[46:49], v[130:133], v[170:173], v[46:49]
	v_mfma_f32_16x16x32_bf16 v[42:45], v[138:141], v[170:173], v[42:45]
	v_mfma_f32_16x16x32_bf16 v[30:33], v[130:133], v[194:197], v[30:33]
	v_mfma_f32_16x16x32_bf16 v[26:29], v[138:141], v[194:197], v[26:29]
	v_mfma_f32_16x16x32_bf16 v[14:17], v[130:133], v[202:205], v[14:17]
	v_mfma_f32_16x16x32_bf16 v[10:13], v[138:141], v[202:205], v[10:13]
	v_mfma_f32_16x16x32_bf16 v[62:65], v[134:137], v[166:169], v[62:65]
	v_mfma_f32_16x16x32_bf16 v[58:61], v[142:145], v[166:169], v[58:61]
	v_mfma_f32_16x16x32_bf16 v[46:49], v[134:137], v[174:177], v[46:49]
	v_mfma_f32_16x16x32_bf16 v[42:45], v[142:145], v[174:177], v[42:45]
	v_mfma_f32_16x16x32_bf16 v[30:33], v[134:137], v[198:201], v[30:33]
	v_mfma_f32_16x16x32_bf16 v[26:29], v[142:145], v[198:201], v[26:29]
	v_mfma_f32_16x16x32_bf16 v[14:17], v[134:137], v[212:215], v[14:17]
	v_mfma_f32_16x16x32_bf16 v[10:13], v[142:145], v[212:215], v[10:13]
	v_mfma_f32_16x16x32_bf16 v[54:57], v[146:149], v[162:165], v[54:57]
	v_mfma_f32_16x16x32_bf16 v[50:53], v[154:157], v[162:165], v[50:53]
	v_mfma_f32_16x16x32_bf16 v[38:41], v[146:149], v[170:173], v[38:41]
	v_mfma_f32_16x16x32_bf16 v[34:37], v[154:157], v[170:173], v[34:37]
	v_mfma_f32_16x16x32_bf16 v[22:25], v[146:149], v[194:197], v[22:25]
	v_mfma_f32_16x16x32_bf16 v[18:21], v[154:157], v[194:197], v[18:21]
	v_mfma_f32_16x16x32_bf16 v[6:9], v[146:149], v[202:205], v[6:9]
	v_mfma_f32_16x16x32_bf16 v[2:5], v[154:157], v[202:205], v[2:5]
	v_mfma_f32_16x16x32_bf16 v[54:57], v[150:153], v[166:169], v[54:57]
	v_mfma_f32_16x16x32_bf16 v[50:53], v[158:161], v[166:169], v[50:53]
	v_mfma_f32_16x16x32_bf16 v[38:41], v[150:153], v[174:177], v[38:41]
	v_mfma_f32_16x16x32_bf16 v[34:37], v[158:161], v[174:177], v[34:37]
	v_mfma_f32_16x16x32_bf16 v[22:25], v[150:153], v[198:201], v[22:25]
	v_mfma_f32_16x16x32_bf16 v[18:21], v[158:161], v[198:201], v[18:21]
	v_mfma_f32_16x16x32_bf16 v[6:9], v[150:153], v[212:215], v[6:9]
	v_mfma_f32_16x16x32_bf16 v[2:5], v[158:161], v[212:215], v[2:5]
	s_barrier
	s_add_i32 s78, s78, 2
	s_add_u32 s48, s48, 0x100
	s_addc_u32 s49, s49, 0
	s_add_u32 s76, s76, 0x100
	s_addc_u32 s77, s77, 0
	s_cmp_gt_u32 s78, 29
.LBB0_963:
	ds_read_b128 v[130:133], v208
	ds_read_b128 v[134:137], v208 offset:1024
	ds_read_b128 v[138:141], v208 offset:2048
	ds_read_b128 v[142:145], v208 offset:3072
	ds_read_b128 v[146:149], v209
	ds_read_b128 v[150:153], v209 offset:1024
	ds_read_b128 v[154:157], v209 offset:2048
	ds_read_b128 v[158:161], v209 offset:3072
	s_add_u32 s18, s48, 0xfff80080
	s_addc_u32 s19, s49, -1
	s_cmp_eq_u32 s78, 28
	s_cselect_b32 s53, s41, s19
	s_cselect_b32 s52, s47, s18
	s_cselect_b32 s51, s39, s77
	s_cselect_b32 s50, s75, s76
	s_cmp_lt_i32 s78, 23
	s_cselect_b32 s92, 0x80, 0
	s_add_i32 m0, s62, 0xc000
	ds_read_b128 v[162:165], v210
	ds_read_b128 v[166:169], v210 offset:1024
	ds_read_b128 v[170:173], v210 offset:2048
	ds_read_b128 v[174:177], v210 offset:3072
	ds_read_b128 v[194:197], v210 offset:4096
	ds_read_b128 v[198:201], v210 offset:5120
	ds_read_b128 v[202:205], v210 offset:6144
	ds_read_b128 v[212:215], v210 offset:7168
	global_load_lds_dwordx4 v186, s[48:49]
	s_add_i32 m0, s62, 0xe000
	s_nop 0
	global_load_lds_dwordx4 v188, s[48:49]
	s_waitcnt vmcnt(9)
	s_waitcnt lgkmcnt(0)
	s_barrier
	s_waitcnt lgkmcnt(0)
	v_mfma_f32_16x16x32_bf16 v[126:129], v[130:133], v[162:165], v[126:129]
	v_mfma_f32_16x16x32_bf16 v[122:125], v[138:141], v[162:165], v[122:125]
	v_mfma_f32_16x16x32_bf16 v[110:113], v[130:133], v[170:173], v[110:113]
	v_mfma_f32_16x16x32_bf16 v[106:109], v[138:141], v[170:173], v[106:109]
	v_mfma_f32_16x16x32_bf16 v[94:97], v[130:133], v[194:197], v[94:97]
	v_mfma_f32_16x16x32_bf16 v[90:93], v[138:141], v[194:197], v[90:93]
	v_mfma_f32_16x16x32_bf16 v[78:81], v[130:133], v[202:205], v[78:81]
	v_mfma_f32_16x16x32_bf16 v[74:77], v[138:141], v[202:205], v[74:77]
	v_mfma_f32_16x16x32_bf16 v[126:129], v[134:137], v[166:169], v[126:129]
	v_mfma_f32_16x16x32_bf16 v[122:125], v[142:145], v[166:169], v[122:125]
	v_mfma_f32_16x16x32_bf16 v[110:113], v[134:137], v[174:177], v[110:113]
	v_mfma_f32_16x16x32_bf16 v[106:109], v[142:145], v[174:177], v[106:109]
	v_mfma_f32_16x16x32_bf16 v[94:97], v[134:137], v[198:201], v[94:97]
	v_mfma_f32_16x16x32_bf16 v[90:93], v[142:145], v[198:201], v[90:93]
	v_mfma_f32_16x16x32_bf16 v[78:81], v[134:137], v[212:215], v[78:81]
	v_mfma_f32_16x16x32_bf16 v[74:77], v[142:145], v[212:215], v[74:77]
	v_mfma_f32_16x16x32_bf16 v[118:121], v[146:149], v[162:165], v[118:121]
	v_mfma_f32_16x16x32_bf16 v[114:117], v[154:157], v[162:165], v[114:117]
	v_mfma_f32_16x16x32_bf16 v[102:105], v[146:149], v[170:173], v[102:105]
	v_mfma_f32_16x16x32_bf16 v[98:101], v[154:157], v[170:173], v[98:101]
	v_mfma_f32_16x16x32_bf16 v[86:89], v[146:149], v[194:197], v[86:89]
	v_mfma_f32_16x16x32_bf16 v[82:85], v[154:157], v[194:197], v[82:85]
	v_mfma_f32_16x16x32_bf16 v[70:73], v[146:149], v[202:205], v[70:73]
	v_mfma_f32_16x16x32_bf16 v[66:69], v[154:157], v[202:205], v[66:69]
	v_mfma_f32_16x16x32_bf16 v[118:121], v[150:153], v[166:169], v[118:121]
	v_mfma_f32_16x16x32_bf16 v[114:117], v[158:161], v[166:169], v[114:117]
	v_mfma_f32_16x16x32_bf16 v[102:105], v[150:153], v[174:177], v[102:105]
	v_mfma_f32_16x16x32_bf16 v[98:101], v[158:161], v[174:177], v[98:101]
	v_mfma_f32_16x16x32_bf16 v[86:89], v[150:153], v[198:201], v[86:89]
	v_mfma_f32_16x16x32_bf16 v[82:85], v[158:161], v[198:201], v[82:85]
	v_mfma_f32_16x16x32_bf16 v[70:73], v[150:153], v[212:215], v[70:73]
	v_mfma_f32_16x16x32_bf16 v[66:69], v[158:161], v[212:215], v[66:69]
	s_barrier
; #define PG8_STAGE(bufoff, gbase, voff) do { _Pragma("unroll") for (int _i = 0; _i < 2; ++_i) \
;         __builtin_amdgcn_global_load_lds((const unsigned*)((const char*)(gbase) + (voff)[_i]), (PG8_LAS unsigned*)(lds + (bufoff) + ldsw + _i * 8192), 16, 0, 0); } while (0)
; #define PG8_LDA(dst, b, h) do { _Pragma("unroll") for (int m = 0; m < 4; ++m) _Pragma("unroll") for (int k = 0; k < 2; ++k) dst[m][k] = *(const PG8_LAS bf16x8*)(lds + PG8_SA(b, h) + aoff + m * 2048 + k * 1024); } while (0)
; #define PG8_LDB(dst, b, h) do { _Pragma("unroll") for (int n = 0; n < 2; ++n) _Pragma("unroll") for (int k = 0; k < 2; ++k) dst[n][k] = *(const PG8_LAS bf16x8*)(lds + PG8_SB(b, h) + boff + n * 2048 + k * 1024); } while (0)
; #define PG8_MMA(ai, bj, At, Bt) do { __builtin_amdgcn_s_setprio(1); _Pragma("unroll") for (int m = 0; m < 4; ++m) _Pragma("unroll") for (int n = 0; n < 2; ++n) _Pragma("unroll") for (int k = 0; k < 2; ++k) \
;         acc[ai][bj][m][n] = __builtin_amdgcn_mfma_f32_16x16x32_bf16(Bt[n][k], At[m][k], acc[ai][bj][m][n], 0, 0, 0); __builtin_amdgcn_s_setprio(0); } while (0)
; #define PG8_WAIT_V(n) asm volatile("s_waitcnt vmcnt(" #n ")" ::: "memory")
; #define PG8_WAIT_L(n) asm volatile("s_waitcnt lgkmcnt(" #n ")" ::: "memory")
; #define PG8_BAR __builtin_amdgcn_s_barrier()
; #define PG8_SCHED __builtin_amdgcn_sched_barrier(0)
; template <class Epi, class Sched, bool ALIGN_EPI = false, bool SP2 = false>
; __device__ __forceinline__ void gemm_phase(PG8_LAS unsigned char* lds, const Gemm g, const Sched& S, const Epi& E) {
;     ...
;             PG8_WAIT_V(8); PG8_WAIT_L(0); PG8_BAR; PG8_MMA(0, 0, At, B0); PG8_MMA(0, 1, At, B1); PG8_BAR; PG8_SCHED;
;             PG8_LDA(At, 0, 1); PG8_STAGE(PG8_SB(0, 0), b2, voffB); PG8_STAGE(PG8_SB(0, 1), b2 + hB, voffB); PG8_STAGE(PG8_SA(0, 0), a2, voffA);
;             PG8_WAIT_V(8); PG8_WAIT_L(0); PG8_BAR; PG8_MMA(1, 0, At, B0); PG8_MMA(1, 1, At, B1); PG8_BAR; PG8_SCHED;
;             PG8_LDB(B0, 1, 0); PG8_LDB(B1, 1, 1); PG8_SCHED; PG8_LDA(At, 1, 0); PG8_STAGE(PG8_SA(0, 1), a2 + hA, voffA);
;             PG8_WAIT_V(8); PG8_WAIT_L(0); PG8_BAR; PG8_MMA(0, 0, At, B0); PG8_MMA(0, 1, At, B1); PG8_BAR; PG8_SCHED;
;             PG8_LDA(At, 1, 1); PG8_STAGE(PG8_SB(1, 0), b3, voffB); PG8_STAGE(PG8_SB(1, 1), b3 + hB, voffB); PG8_STAGE(PG8_SA(1, 0), a3, voffA);
	s_add_i32 s18, s72, s61
	s_add_u32 s82, s50, s22
	s_addc_u32 s83, s51, s23
	s_mov_b32 m0, s18
	ds_read_b128 v[162:165], v210 offset:16384
	ds_read_b128 v[166:169], v210 offset:17408
	ds_read_b128 v[170:173], v210 offset:18432
	ds_read_b128 v[174:177], v210 offset:19456
	ds_read_b128 v[194:197], v210 offset:20480
	ds_read_b128 v[198:201], v210 offset:21504
	ds_read_b128 v[202:205], v210 offset:22528
	ds_read_b128 v[212:215], v210 offset:23552
	global_load_lds_dwordx4 v180, s[50:51]
	s_add_i32 m0, s18, 0x2000
	s_add_u32 s80, s50, 0x80000
	s_addc_u32 s81, s51, 0
	s_add_i32 s18, s73, s61
	global_load_lds_dwordx4 v184, s[50:51]
	s_mov_b32 m0, s18
	s_nop 0
	global_load_lds_dwordx4 v180, s[80:81]
	s_add_i32 m0, s18, 0x2000
	s_nop 0
	global_load_lds_dwordx4 v184, s[80:81]
	s_add_u32 s88, s52, s22
	s_addc_u32 s89, s53, s23
	s_mov_b32 m0, s62
	s_nop 0
	global_load_lds_dwordx4 v178, s[52:53]
	s_mov_b32 m0, s63
	s_nop 0
	global_load_lds_dwordx4 v182, s[52:53]
	global_load_dword v247, v[248:249], off
	v_lshl_add_u64 v[248:249], v[248:249], 0, s[92:93]
	s_waitcnt vmcnt(10)
	s_waitcnt lgkmcnt(0)
	s_barrier
	s_waitcnt lgkmcnt(0)
	v_mfma_f32_16x16x32_bf16 v[62:65], v[130:133], v[162:165], v[62:65]
	v_mfma_f32_16x16x32_bf16 v[58:61], v[138:141], v[162:165], v[58:61]
	v_mfma_f32_16x16x32_bf16 v[46:49], v[130:133], v[170:173], v[46:49]
	v_mfma_f32_16x16x32_bf16 v[42:45], v[138:141], v[170:173], v[42:45]
	v_mfma_f32_16x16x32_bf16 v[30:33], v[130:133], v[194:197], v[30:33]
	v_mfma_f32_16x16x32_bf16 v[26:29], v[138:141], v[194:197], v[26:29]
	v_mfma_f32_16x16x32_bf16 v[14:17], v[130:133], v[202:205], v[14:17]
	v_mfma_f32_16x16x32_bf16 v[10:13], v[138:141], v[202:205], v[10:13]
	v_mfma_f32_16x16x32_bf16 v[62:65], v[134:137], v[166:169], v[62:65]
	v_mfma_f32_16x16x32_bf16 v[58:61], v[142:145], v[166:169], v[58:61]
	v_mfma_f32_16x16x32_bf16 v[46:49], v[134:137], v[174:177], v[46:49]
	v_mfma_f32_16x16x32_bf16 v[42:45], v[142:145], v[174:177], v[42:45]
	v_mfma_f32_16x16x32_bf16 v[30:33], v[134:137], v[198:201], v[30:33]
	v_mfma_f32_16x16x32_bf16 v[26:29], v[142:145], v[198:201], v[26:29]
	v_mfma_f32_16x16x32_bf16 v[14:17], v[134:137], v[212:215], v[14:17]
	v_mfma_f32_16x16x32_bf16 v[10:13], v[142:145], v[212:215], v[10:13]
	v_mfma_f32_16x16x32_bf16 v[54:57], v[146:149], v[162:165], v[54:57]
	v_mfma_f32_16x16x32_bf16 v[50:53], v[154:157], v[162:165], v[50:53]
	v_mfma_f32_16x16x32_bf16 v[38:41], v[146:149], v[170:173], v[38:41]
	v_mfma_f32_16x16x32_bf16 v[34:37], v[154:157], v[170:173], v[34:37]
	v_mfma_f32_16x16x32_bf16 v[22:25], v[146:149], v[194:197], v[22:25]
	v_mfma_f32_16x16x32_bf16 v[18:21], v[154:157], v[194:197], v[18:21]
	v_mfma_f32_16x16x32_bf16 v[6:9], v[146:149], v[202:205], v[6:9]
	v_mfma_f32_16x16x32_bf16 v[2:5], v[154:157], v[202:205], v[2:5]
	v_mfma_f32_16x16x32_bf16 v[54:57], v[150:153], v[166:169], v[54:57]
	v_mfma_f32_16x16x32_bf16 v[50:53], v[158:161], v[166:169], v[50:53]
	v_mfma_f32_16x16x32_bf16 v[38:41], v[150:153], v[174:177], v[38:41]
	v_mfma_f32_16x16x32_bf16 v[34:37], v[158:161], v[174:177], v[34:37]
	v_mfma_f32_16x16x32_bf16 v[22:25], v[150:153], v[198:201], v[22:25]
	v_mfma_f32_16x16x32_bf16 v[18:21], v[158:161], v[198:201], v[18:21]
	v_mfma_f32_16x16x32_bf16 v[6:9], v[150:153], v[212:215], v[6:9]
	v_mfma_f32_16x16x32_bf16 v[2:5], v[158:161], v[212:215], v[2:5]
	s_barrier
	s_add_i32 s18, 0, 0x18000
	s_add_i32 s19, 0, 0x1c000
	v_add_u32_e32 v142, s18, v206
	v_add_u32_e32 v158, s19, v206
	ds_read_b128 v[130:133], v142
	ds_read_b128 v[134:137], v142 offset:1024
	ds_read_b128 v[138:141], v142 offset:2048
	ds_read_b128 v[142:145], v142 offset:3072
	ds_read_b128 v[146:149], v158
	ds_read_b128 v[150:153], v158 offset:1024
	ds_read_b128 v[154:157], v158 offset:2048
	ds_read_b128 v[158:161], v158 offset:3072
	s_add_u32 s52, s52, 0x80000
	s_addc_u32 s53, s53, 0
	s_mov_b32 m0, s64
	ds_read_b128 v[162:165], v210 offset:32768
	ds_read_b128 v[166:169], v210 offset:33792
	ds_read_b128 v[170:173], v210 offset:34816
	ds_read_b128 v[174:177], v210 offset:35840
	ds_read_b128 v[194:197], v210 offset:36864
	ds_read_b128 v[198:201], v210 offset:37888
	ds_read_b128 v[202:205], v210 offset:38912
	ds_read_b128 v[212:215], v210 offset:39936
	global_load_lds_dwordx4 v178, s[52:53]
	s_mov_b32 m0, s65
	s_nop 0
	global_load_lds_dwordx4 v182, s[52:53]
	s_waitcnt vmcnt(9)
	s_waitcnt lgkmcnt(0)
	s_barrier
; #define PG8_STAGE(bufoff, gbase, voff) do { _Pragma("unroll") for (int _i = 0; _i < 2; ++_i) \
;         __builtin_amdgcn_global_load_lds((const unsigned*)((const char*)(gbase) + (voff)[_i]), (PG8_LAS unsigned*)(lds + (bufoff) + ldsw + _i * 8192), 16, 0, 0); } while (0)
; #define PG8_LDA(dst, b, h) do { _Pragma("unroll") for (int m = 0; m < 4; ++m) _Pragma("unroll") for (int k = 0; k < 2; ++k) dst[m][k] = *(const PG8_LAS bf16x8*)(lds + PG8_SA(b, h) + aoff + m * 2048 + k * 1024); } while (0)
; #define PG8_MMA(ai, bj, At, Bt) do { __builtin_amdgcn_s_setprio(1); _Pragma("unroll") for (int m = 0; m < 4; ++m) _Pragma("unroll") for (int n = 0; n < 2; ++n) _Pragma("unroll") for (int k = 0; k < 2; ++k) \
;         acc[ai][bj][m][n] = __builtin_amdgcn_mfma_f32_16x16x32_bf16(Bt[n][k], At[m][k], acc[ai][bj][m][n], 0, 0, 0); __builtin_amdgcn_s_setprio(0); } while (0)
; #define PG8_WAIT_V(n) asm volatile("s_waitcnt vmcnt(" #n ")" ::: "memory")
; #define PG8_WAIT_L(n) asm volatile("s_waitcnt lgkmcnt(" #n ")" ::: "memory")
; #define PG8_BAR __builtin_amdgcn_s_barrier()
; #define PG8_SCHED __builtin_amdgcn_sched_barrier(0)
; template <class Epi, class Sched, bool ALIGN_EPI = false, bool SP2 = false>
; __device__ __forceinline__ void gemm_phase(PG8_LAS unsigned char* lds, const Gemm g, const Sched& S, const Epi& E) {
;     ...
;             PG8_WAIT_V(8); PG8_WAIT_L(0); PG8_BAR; PG8_MMA(0, 0, At, B0); PG8_MMA(0, 1, At, B1); PG8_BAR; PG8_SCHED;
;             PG8_LDA(At, 1, 1); PG8_STAGE(PG8_SB(1, 0), b3, voffB); PG8_STAGE(PG8_SB(1, 1), b3 + hB, voffB); PG8_STAGE(PG8_SA(1, 0), a3, voffA);
;             PG8_WAIT_V(8); PG8_WAIT_L(0); PG8_BAR; PG8_MMA(1, 0, At, B0); PG8_MMA(1, 1, At, B1); PG8_BAR; PG8_SCHED;
;     ...
;         if constexpr (ALIGN_EPI) { if (wr == 0) PG8_BAR; }
;         if constexpr (!Epi::AFTER_DRAIN) { E(acc, cur, wr, wc, fr, fq); S.done(cur); }
;         if (!has_next) break;
	s_waitcnt lgkmcnt(0)
	v_mfma_f32_16x16x32_bf16 v[126:129], v[130:133], v[162:165], v[126:129]
	v_mfma_f32_16x16x32_bf16 v[122:125], v[138:141], v[162:165], v[122:125]
	v_mfma_f32_16x16x32_bf16 v[110:113], v[130:133], v[170:173], v[110:113]
	v_mfma_f32_16x16x32_bf16 v[106:109], v[138:141], v[170:173], v[106:109]
	v_mfma_f32_16x16x32_bf16 v[94:97], v[130:133], v[194:197], v[94:97]
	v_mfma_f32_16x16x32_bf16 v[90:93], v[138:141], v[194:197], v[90:93]
	v_mfma_f32_16x16x32_bf16 v[78:81], v[130:133], v[202:205], v[78:81]
	v_mfma_f32_16x16x32_bf16 v[74:77], v[138:141], v[202:205], v[74:77]
	v_mfma_f32_16x16x32_bf16 v[126:129], v[134:137], v[166:169], v[126:129]
	v_mfma_f32_16x16x32_bf16 v[122:125], v[142:145], v[166:169], v[122:125]
	v_mfma_f32_16x16x32_bf16 v[110:113], v[134:137], v[174:177], v[110:113]
	v_mfma_f32_16x16x32_bf16 v[106:109], v[142:145], v[174:177], v[106:109]
	v_mfma_f32_16x16x32_bf16 v[94:97], v[134:137], v[198:201], v[94:97]
	v_mfma_f32_16x16x32_bf16 v[90:93], v[142:145], v[198:201], v[90:93]
	v_mfma_f32_16x16x32_bf16 v[78:81], v[134:137], v[212:215], v[78:81]
	v_mfma_f32_16x16x32_bf16 v[74:77], v[142:145], v[212:215], v[74:77]
	v_mfma_f32_16x16x32_bf16 v[118:121], v[146:149], v[162:165], v[118:121]
	v_mfma_f32_16x16x32_bf16 v[114:117], v[154:157], v[162:165], v[114:117]
	v_mfma_f32_16x16x32_bf16 v[102:105], v[146:149], v[170:173], v[102:105]
	v_mfma_f32_16x16x32_bf16 v[98:101], v[154:157], v[170:173], v[98:101]
	v_mfma_f32_16x16x32_bf16 v[86:89], v[146:149], v[194:197], v[86:89]
	v_mfma_f32_16x16x32_bf16 v[82:85], v[154:157], v[194:197], v[82:85]
	v_mfma_f32_16x16x32_bf16 v[70:73], v[146:149], v[202:205], v[70:73]
	v_mfma_f32_16x16x32_bf16 v[66:69], v[154:157], v[202:205], v[66:69]
	v_mfma_f32_16x16x32_bf16 v[118:121], v[150:153], v[166:169], v[118:121]
	v_mfma_f32_16x16x32_bf16 v[114:117], v[158:161], v[166:169], v[114:117]
	v_mfma_f32_16x16x32_bf16 v[102:105], v[150:153], v[174:177], v[102:105]
	v_mfma_f32_16x16x32_bf16 v[98:101], v[158:161], v[174:177], v[98:101]
	v_mfma_f32_16x16x32_bf16 v[86:89], v[150:153], v[198:201], v[86:89]
	v_mfma_f32_16x16x32_bf16 v[82:85], v[158:161], v[198:201], v[82:85]
	v_mfma_f32_16x16x32_bf16 v[70:73], v[150:153], v[212:215], v[70:73]
	v_mfma_f32_16x16x32_bf16 v[66:69], v[158:161], v[212:215], v[66:69]
	s_barrier
	s_add_i32 s18, s18, s61
	s_mov_b32 m0, s18
	ds_read_b128 v[162:165], v210 offset:49152
	ds_read_b128 v[166:169], v210 offset:50176
	ds_read_b128 v[170:173], v210 offset:51200
	ds_read_b128 v[174:177], v210 offset:52224
	ds_read_b128 v[194:197], v210 offset:53248
	ds_read_b128 v[198:201], v210 offset:54272
	ds_read_b128 v[202:205], v210 offset:55296
	ds_read_b128 v[212:215], v210 offset:56320
	global_load_lds_dwordx4 v180, s[82:83]
	s_add_i32 m0, s18, 0x2000
	s_add_u32 s50, s50, 0x80080
	s_addc_u32 s51, s51, 0
	s_add_i32 s18, s19, s61
	global_load_lds_dwordx4 v184, s[82:83]
	s_mov_b32 m0, s18
	s_nop 0
	global_load_lds_dwordx4 v180, s[50:51]
	s_add_i32 m0, s18, 0x2000
	s_nop 0
	global_load_lds_dwordx4 v184, s[50:51]
	s_mov_b32 m0, s69
	s_nop 0
	global_load_lds_dwordx4 v178, s[88:89]
	s_mov_b32 m0, s70
	s_nop 0
	global_load_lds_dwordx4 v182, s[88:89]
	global_load_dword v247, v[248:249], off
	v_lshl_add_u64 v[248:249], v[248:249], 0, s[92:93]
	s_waitcnt vmcnt(10)
	s_waitcnt lgkmcnt(0)
	s_barrier
	s_waitcnt lgkmcnt(0)
	v_mfma_f32_16x16x32_bf16 v[62:65], v[130:133], v[162:165], v[62:65]
	v_mfma_f32_16x16x32_bf16 v[58:61], v[138:141], v[162:165], v[58:61]
	v_mfma_f32_16x16x32_bf16 v[46:49], v[130:133], v[170:173], v[46:49]
	v_mfma_f32_16x16x32_bf16 v[42:45], v[138:141], v[170:173], v[42:45]
	v_mfma_f32_16x16x32_bf16 v[30:33], v[130:133], v[194:197], v[30:33]
	v_mfma_f32_16x16x32_bf16 v[26:29], v[138:141], v[194:197], v[26:29]
	v_mfma_f32_16x16x32_bf16 v[14:17], v[130:133], v[202:205], v[14:17]
	v_mfma_f32_16x16x32_bf16 v[10:13], v[138:141], v[202:205], v[10:13]
	v_mfma_f32_16x16x32_bf16 v[62:65], v[134:137], v[166:169], v[62:65]
	v_mfma_f32_16x16x32_bf16 v[58:61], v[142:145], v[166:169], v[58:61]
	v_mfma_f32_16x16x32_bf16 v[46:49], v[134:137], v[174:177], v[46:49]
	v_mfma_f32_16x16x32_bf16 v[42:45], v[142:145], v[174:177], v[42:45]
	v_mfma_f32_16x16x32_bf16 v[30:33], v[134:137], v[198:201], v[30:33]
	v_mfma_f32_16x16x32_bf16 v[26:29], v[142:145], v[198:201], v[26:29]
	v_mfma_f32_16x16x32_bf16 v[14:17], v[134:137], v[212:215], v[14:17]
	v_mfma_f32_16x16x32_bf16 v[10:13], v[142:145], v[212:215], v[10:13]
	v_mfma_f32_16x16x32_bf16 v[54:57], v[146:149], v[162:165], v[54:57]
	v_mfma_f32_16x16x32_bf16 v[50:53], v[154:157], v[162:165], v[50:53]
	v_mfma_f32_16x16x32_bf16 v[38:41], v[146:149], v[170:173], v[38:41]
	v_mfma_f32_16x16x32_bf16 v[34:37], v[154:157], v[170:173], v[34:37]
	v_mfma_f32_16x16x32_bf16 v[22:25], v[146:149], v[194:197], v[22:25]
	v_mfma_f32_16x16x32_bf16 v[18:21], v[154:157], v[194:197], v[18:21]
	v_mfma_f32_16x16x32_bf16 v[6:9], v[146:149], v[202:205], v[6:9]
	v_mfma_f32_16x16x32_bf16 v[2:5], v[154:157], v[202:205], v[2:5]
	v_mfma_f32_16x16x32_bf16 v[54:57], v[150:153], v[166:169], v[54:57]
	v_mfma_f32_16x16x32_bf16 v[50:53], v[158:161], v[166:169], v[50:53]
	v_mfma_f32_16x16x32_bf16 v[38:41], v[150:153], v[174:177], v[38:41]
	v_mfma_f32_16x16x32_bf16 v[34:37], v[158:161], v[174:177], v[34:37]
	v_mfma_f32_16x16x32_bf16 v[22:25], v[150:153], v[198:201], v[22:25]
	v_mfma_f32_16x16x32_bf16 v[18:21], v[158:161], v[198:201], v[18:21]
	v_mfma_f32_16x16x32_bf16 v[6:9], v[150:153], v[212:215], v[6:9]
	v_mfma_f32_16x16x32_bf16 v[2:5], v[158:161], v[212:215], v[2:5]
	s_barrier
	s_add_i32 s78, s78, 2
	s_add_u32 s48, s48, 0x100
	s_addc_u32 s49, s49, 0
	s_add_u32 s76, s76, 0x100
	s_addc_u32 s77, s77, 0
	s_cmp_gt_u32 s78, 29
	s_cbranch_scc0 .LBB0_963
	s_and_b64 vcc, exec, s[24:25]
	s_cbranch_vccz .LBB0_966
	s_barrier

; #define PG8_STAGE(bufoff, gbase, voff) do { _Pragma("unroll") for (int _i = 0; _i < 2; ++_i) \
;         __builtin_amdgcn_global_load_lds((const unsigned*)((const char*)(gbase) + (voff)[_i]), (PG8_LAS unsigned*)(lds + (bufoff) + ldsw + _i * 8192), 16, 0, 0); } while (0)
; #define PG8_LDA(dst, b, h) do { _Pragma("unroll") for (int m = 0; m < 4; ++m) _Pragma("unroll") for (int k = 0; k < 2; ++k) dst[m][k] = *(const PG8_LAS bf16x8*)(lds + PG8_SA(b, h) + aoff + m * 2048 + k * 1024); } while (0)
; #define PG8_LDB(dst, b, h) do { _Pragma("unroll") for (int n = 0; n < 2; ++n) _Pragma("unroll") for (int k = 0; k < 2; ++k) dst[n][k] = *(const PG8_LAS bf16x8*)(lds + PG8_SB(b, h) + boff + n * 2048 + k * 1024); } while (0)
; #define PG8_MMA(ai, bj, At, Bt) do { __builtin_amdgcn_s_setprio(1); _Pragma("unroll") for (int m = 0; m < 4; ++m) _Pragma("unroll") for (int n = 0; n < 2; ++n) _Pragma("unroll") for (int k = 0; k < 2; ++k) \
;         acc[ai][bj][m][n] = __builtin_amdgcn_mfma_f32_16x16x32_bf16(Bt[n][k], At[m][k], acc[ai][bj][m][n], 0, 0, 0); __builtin_amdgcn_s_setprio(0); } while (0)
; #define PG8_WAIT_V(n) asm volatile("s_waitcnt vmcnt(" #n ")" ::: "memory")
; #define PG8_BAR __builtin_amdgcn_s_barrier()
; template <class Epi, class Sched, bool ALIGN_EPI = false, bool SP2 = false>
; __device__ __forceinline__ void gemm_phase(PG8_LAS unsigned char* lds, const Gemm g, const Sched& S, const Epi& E) {
;     ...
;     for (;;) {
;         const bool has_next = S.next(ui + 1, nxt);
;         const char* nA = has_next ? (const char*)g.A + (size_t)nxt.pm * tA + (size_t)nxt.pn * pnA : cA; const char* nB = has_next ? (const char*)g.Bt + (size_t)nxt.pn * tB : cB;
; #pragma nounroll
;         for (int t = 0; t < nt; t += 2) {
;             const bool last = (t == nt - 2);
;             const char* a1 = cA + (size_t)(t + 1) * kstep;
;             const char* a2 = last ? nA : cA + (size_t)(t + 2) * kstep; const char* b2 = last ? nB : cB + (size_t)(t + 2) * kstep;
;             const char* a3 = a2 + kstep; const char* b3 = b2 + kstep;
;             if (last && has_next) S.a_ready(nxt);
;             if constexpr (SP2) {
;             PG8_LDB(B0, 0, 0); PG8_LDB(B1, 0, 1); PG8_SCHED; PG8_LDA(At, 0, 0); PG8_STAGE(PG8_SA(1, 1), a1 + hA, voffA);
;             PG8_WAIT_V(8); PG8_WAIT_L(0); PG8_BAR; PG8_MMA(0, 0, At, B0); PG8_MMA(0, 1, At, B1); PG8_BAR; PG8_SCHED;
.LBB0_1047:
	s_ashr_i32 s37, s36, 31
	s_lshl_b64 s[38:39], s[36:37], 20
	s_add_u32 s38, s33, s38
	s_addc_u32 s39, s46, s39
	s_and_b64 s[40:41], s[6:7], exec
	s_cselect_b32 s1, s39, s9
	s_cselect_b32 s37, s38, s8
	s_ashr_i32 s25, s24, 31
	s_lshl_b64 s[40:41], s[24:25], 20
	s_add_u32 s40, s47, s40
	s_addc_u32 s41, s48, s41
	s_and_b64 s[44:45], s[6:7], exec
	s_cselect_b32 s25, s41, s43
	s_cselect_b32 s69, s40, s42
	s_add_u32 s8, s8, 0x80080
	s_addc_u32 s9, s9, 0
	s_add_u32 s70, s42, 0x100
	v_mov_b32_e32 v2, 0
	s_addc_u32 s71, s43, 0
	s_mov_b32 s72, -2
	v_mov_b32_e32 v3, v2
	s_add_u32 s80, s8, 0xfff80180
	s_addc_u32 s81, s9, -1
	v_mov_b32_e32 v240, s80
	v_mov_b32_e32 v241, s81
	s_add_u32 s80, s70, 0x100
	s_addc_u32 s81, s71, 0
	v_mov_b32_e32 v242, s80
	v_mov_b32_e32 v243, s81
	s_mov_b64 s[80:81], 0xff0
	v_cndmask_b32_e64 v240, v240, v242, s[80:81]
	v_cndmask_b32_e64 v241, v241, v243, s[80:81]
	v_and_b32_e32 v247, 63, v0
	v_lshrrev_b32_e32 v242, 6, v0
	v_and_b32_e32 v243, 3, v247
	v_lshl_add_u32 v243, v242, 2, v243
	v_add_u32_e32 v247, 4, v247
	v_and_b32_e32 v247, 7, v247
	v_lshl_add_u32 v247, v242, 3, v247
	s_and_b32 s80, s2, 0xe0
	s_and_b32 s81, s2, 0x18
	s_lshl_b32 s81, s81, 3
	v_add_u32_e32 v243, s80, v243
	v_add_u32_e32 v247, s81, v247
	s_mov_b64 s[80:81], 0xff0
	v_cndmask_b32_e64 v247, v243, v247, s[80:81]
	v_mul_u32_u24_e32 v242, 0x1000, v247
	v_mov_b32_e32 v243, 0
	s_nop 0
	v_lshl_add_u64 v[240:241], v[242:243], 0, v[240:241]
	s_mov_b32 s81, 0
	s_mov_b32 s80, 0x80
	ds_read_b128 v[148:151], v169
	ds_read_b128 v[152:155], v169 offset:1024
	ds_read_b128 v[156:159], v169 offset:2048
	ds_read_b128 v[160:163], v169 offset:3072
	ds_read_b128 v[180:183], v171
	ds_read_b128 v[184:187], v171 offset:1024
	ds_read_b128 v[188:191], v171 offset:2048
	ds_read_b128 v[192:195], v171 offset:3072
	s_add_u32 s18, s8, 0xfff80080
	s_addc_u32 s19, s9, -1
	s_cmp_eq_u32 s72, 28
	s_cselect_b32 s45, s1, s19
	s_cselect_b32 s44, s37, s18
	s_cselect_b32 s43, s25, s71
	s_cselect_b32 s42, s69, s70
	s_cmp_lt_i32 s72, 23
	s_cselect_b32 s80, 0x80, 0
	s_add_i32 m0, s51, 0xc000
	ds_read_b128 v[196:199], v173
	ds_read_b128 v[200:203], v173 offset:1024
	ds_read_b128 v[204:207], v173 offset:2048
	ds_read_b128 v[208:211], v173 offset:3072
	ds_read_b128 v[212:215], v173 offset:4096
	ds_read_b128 v[216:219], v173 offset:5120
	ds_read_b128 v[224:227], v173 offset:6144
	ds_read_b128 v[228:231], v173 offset:7168
	global_load_lds_dwordx4 v140, s[8:9]
	s_add_i32 m0, s51, 0xe000
	s_nop 0
	global_load_lds_dwordx4 v142, s[8:9]
	s_waitcnt vmcnt(9)
	s_waitcnt lgkmcnt(0)
	s_barrier
	s_waitcnt lgkmcnt(0)
	v_mfma_f32_16x16x32_bf16 v[126:129], v[148:151], v[196:199], 0
	v_mfma_f32_16x16x32_bf16 v[122:125], v[156:159], v[196:199], 0
	v_mfma_f32_16x16x32_bf16 v[110:113], v[148:151], v[204:207], 0
	v_mfma_f32_16x16x32_bf16 v[106:109], v[156:159], v[204:207], 0
	v_mfma_f32_16x16x32_bf16 v[94:97], v[148:151], v[212:215], 0
	v_mfma_f32_16x16x32_bf16 v[90:93], v[156:159], v[212:215], 0
	v_mfma_f32_16x16x32_bf16 v[78:81], v[148:151], v[224:227], 0
	v_mfma_f32_16x16x32_bf16 v[74:77], v[156:159], v[224:227], 0
	v_mfma_f32_16x16x32_bf16 v[126:129], v[152:155], v[200:203], v[126:129]
	v_mfma_f32_16x16x32_bf16 v[122:125], v[160:163], v[200:203], v[122:125]
	v_mfma_f32_16x16x32_bf16 v[110:113], v[152:155], v[208:211], v[110:113]
	v_mfma_f32_16x16x32_bf16 v[106:109], v[160:163], v[208:211], v[106:109]
	v_mfma_f32_16x16x32_bf16 v[94:97], v[152:155], v[216:219], v[94:97]
	v_mfma_f32_16x16x32_bf16 v[90:93], v[160:163], v[216:219], v[90:93]
	v_mfma_f32_16x16x32_bf16 v[78:81], v[152:155], v[228:231], v[78:81]
	v_mfma_f32_16x16x32_bf16 v[74:77], v[160:163], v[228:231], v[74:77]
	v_mfma_f32_16x16x32_bf16 v[118:121], v[180:183], v[196:199], 0
	v_mfma_f32_16x16x32_bf16 v[114:117], v[188:191], v[196:199], 0
	v_mfma_f32_16x16x32_bf16 v[102:105], v[180:183], v[204:207], 0
	v_mfma_f32_16x16x32_bf16 v[98:101], v[188:191], v[204:207], 0
	v_mfma_f32_16x16x32_bf16 v[86:89], v[180:183], v[212:215], 0
	v_mfma_f32_16x16x32_bf16 v[82:85], v[188:191], v[212:215], 0
	v_mfma_f32_16x16x32_bf16 v[70:73], v[180:183], v[224:227], 0
	v_mfma_f32_16x16x32_bf16 v[66:69], v[188:191], v[224:227], 0
	v_mfma_f32_16x16x32_bf16 v[118:121], v[184:187], v[200:203], v[118:121]
	v_mfma_f32_16x16x32_bf16 v[114:117], v[192:195], v[200:203], v[114:117]
	v_mfma_f32_16x16x32_bf16 v[102:105], v[184:187], v[208:211], v[102:105]
	v_mfma_f32_16x16x32_bf16 v[98:101], v[192:195], v[208:211], v[98:101]
	v_mfma_f32_16x16x32_bf16 v[86:89], v[184:187], v[216:219], v[86:89]
	v_mfma_f32_16x16x32_bf16 v[82:85], v[192:195], v[216:219], v[82:85]
	v_mfma_f32_16x16x32_bf16 v[70:73], v[184:187], v[228:231], v[70:73]
	v_mfma_f32_16x16x32_bf16 v[66:69], v[192:195], v[228:231], v[66:69]
	s_barrier
	s_add_i32 s18, s63, s49
	s_add_u32 s76, s42, s20
	s_addc_u32 s77, s43, s21
	s_mov_b32 m0, s18
	ds_read_b128 v[196:199], v173 offset:16384
	ds_read_b128 v[200:203], v173 offset:17408
	ds_read_b128 v[204:207], v173 offset:18432
	ds_read_b128 v[208:211], v173 offset:19456
	ds_read_b128 v[212:215], v173 offset:20480
	ds_read_b128 v[216:219], v173 offset:21504
	ds_read_b128 v[224:227], v173 offset:22528
	ds_read_b128 v[228:231], v173 offset:23552
	global_load_lds_dwordx4 v134, s[42:43]
	s_add_i32 m0, s18, 0x2000
	s_add_u32 s74, s42, 0x80000
	s_addc_u32 s75, s43, 0
	s_add_i32 s18, s64, s49
	global_load_lds_dwordx4 v130, s[42:43]
	s_mov_b32 m0, s18
	s_nop 0
	global_load_lds_dwordx4 v134, s[74:75]
	s_add_i32 m0, s18, 0x2000
	s_nop 0
	global_load_lds_dwordx4 v130, s[74:75]
	s_add_u32 s78, s44, s20
	s_addc_u32 s79, s45, s21
	s_mov_b32 m0, s51
	s_nop 0
	global_load_lds_dwordx4 v136, s[44:45]
	s_mov_b32 m0, s52
	s_nop 0
	global_load_lds_dwordx4 v132, s[44:45]
	global_load_dword v247, v[240:241], off
	v_lshl_add_u64 v[240:241], v[240:241], 0, s[80:81]
	s_waitcnt vmcnt(9)
	s_waitcnt lgkmcnt(0)
	s_barrier
; #define PG8_STAGE(bufoff, gbase, voff) do { _Pragma("unroll") for (int _i = 0; _i < 2; ++_i) \
;         __builtin_amdgcn_global_load_lds((const unsigned*)((const char*)(gbase) + (voff)[_i]), (PG8_LAS unsigned*)(lds + (bufoff) + ldsw + _i * 8192), 16, 0, 0); } while (0)
; #define PG8_LDA(dst, b, h) do { _Pragma("unroll") for (int m = 0; m < 4; ++m) _Pragma("unroll") for (int k = 0; k < 2; ++k) dst[m][k] = *(const PG8_LAS bf16x8*)(lds + PG8_SA(b, h) + aoff + m * 2048 + k * 1024); } while (0)
; #define PG8_LDB(dst, b, h) do { _Pragma("unroll") for (int n = 0; n < 2; ++n) _Pragma("unroll") for (int k = 0; k < 2; ++k) dst[n][k] = *(const PG8_LAS bf16x8*)(lds + PG8_SB(b, h) + boff + n * 2048 + k * 1024); } while (0)
; #define PG8_MMA(ai, bj, At, Bt) do { __builtin_amdgcn_s_setprio(1); _Pragma("unroll") for (int m = 0; m < 4; ++m) _Pragma("unroll") for (int n = 0; n < 2; ++n) _Pragma("unroll") for (int k = 0; k < 2; ++k) \
;         acc[ai][bj][m][n] = __builtin_amdgcn_mfma_f32_16x16x32_bf16(Bt[n][k], At[m][k], acc[ai][bj][m][n], 0, 0, 0); __builtin_amdgcn_s_setprio(0); } while (0)
; #define PG8_WAIT_V(n) asm volatile("s_waitcnt vmcnt(" #n ")" ::: "memory")
; template <class Epi, class Sched, bool ALIGN_EPI = false, bool SP2 = false>
; __device__ __forceinline__ void gemm_phase(PG8_LAS unsigned char* lds, const Gemm g, const Sched& S, const Epi& E) {
;     ...
;             PG8_LDB(B0, 0, 0); PG8_LDB(B1, 0, 1); PG8_SCHED; PG8_LDA(At, 0, 0); PG8_STAGE(PG8_SA(1, 1), a1 + hA, voffA);
;             PG8_WAIT_V(8); PG8_WAIT_L(0); PG8_BAR; PG8_MMA(0, 0, At, B0); PG8_MMA(0, 1, At, B1); PG8_BAR; PG8_SCHED;
;             PG8_LDA(At, 0, 1); PG8_STAGE(PG8_SB(0, 0), b2, voffB); PG8_STAGE(PG8_SB(0, 1), b2 + hB, voffB); PG8_STAGE(PG8_SA(0, 0), a2, voffA);
;             PG8_WAIT_V(8); PG8_WAIT_L(0); PG8_BAR; PG8_MMA(1, 0, At, B0); PG8_MMA(1, 1, At, B1); PG8_BAR; PG8_SCHED;
;             PG8_LDB(B0, 1, 0); PG8_LDB(B1, 1, 1); PG8_SCHED; PG8_LDA(At, 1, 0); PG8_STAGE(PG8_SA(0, 1), a2 + hA, voffA);
;             PG8_WAIT_V(8); PG8_WAIT_L(0); PG8_BAR; PG8_MMA(0, 0, At, B0); PG8_MMA(0, 1, At, B1); PG8_BAR; PG8_SCHED;
;             PG8_LDA(At, 1, 1); PG8_STAGE(PG8_SB(1, 0), b3, voffB); PG8_STAGE(PG8_SB(1, 1), b3 + hB, voffB); PG8_STAGE(PG8_SA(1, 0), a3, voffA);
;             PG8_WAIT_V(8); PG8_WAIT_L(0); PG8_BAR; PG8_MMA(1, 0, At, B0); PG8_MMA(1, 1, At, B1); PG8_BAR; PG8_SCHED;
	s_waitcnt lgkmcnt(0)
	v_mfma_f32_16x16x32_bf16 v[62:65], v[148:151], v[196:199], 0
	v_mfma_f32_16x16x32_bf16 v[58:61], v[156:159], v[196:199], 0
	v_mfma_f32_16x16x32_bf16 v[46:49], v[148:151], v[204:207], 0
	v_mfma_f32_16x16x32_bf16 v[42:45], v[156:159], v[204:207], 0
	v_mfma_f32_16x16x32_bf16 v[30:33], v[148:151], v[212:215], 0
	v_mfma_f32_16x16x32_bf16 v[26:29], v[156:159], v[212:215], 0
	v_mfma_f32_16x16x32_bf16 v[14:17], v[148:151], v[224:227], 0
	v_mfma_f32_16x16x32_bf16 v[10:13], v[156:159], v[224:227], 0
	v_mfma_f32_16x16x32_bf16 v[62:65], v[152:155], v[200:203], v[62:65]
	v_mfma_f32_16x16x32_bf16 v[58:61], v[160:163], v[200:203], v[58:61]
	v_mfma_f32_16x16x32_bf16 v[46:49], v[152:155], v[208:211], v[46:49]
	v_mfma_f32_16x16x32_bf16 v[42:45], v[160:163], v[208:211], v[42:45]
	v_mfma_f32_16x16x32_bf16 v[30:33], v[152:155], v[216:219], v[30:33]
	v_mfma_f32_16x16x32_bf16 v[26:29], v[160:163], v[216:219], v[26:29]
	v_mfma_f32_16x16x32_bf16 v[14:17], v[152:155], v[228:231], v[14:17]
	v_mfma_f32_16x16x32_bf16 v[10:13], v[160:163], v[228:231], v[10:13]
	v_mfma_f32_16x16x32_bf16 v[54:57], v[180:183], v[196:199], 0
	v_mfma_f32_16x16x32_bf16 v[50:53], v[188:191], v[196:199], 0
	v_mfma_f32_16x16x32_bf16 v[38:41], v[180:183], v[204:207], 0
	v_mfma_f32_16x16x32_bf16 v[34:37], v[188:191], v[204:207], 0
	v_mfma_f32_16x16x32_bf16 v[22:25], v[180:183], v[212:215], 0
	v_mfma_f32_16x16x32_bf16 v[18:21], v[188:191], v[212:215], 0
	v_mfma_f32_16x16x32_bf16 v[6:9], v[180:183], v[224:227], 0
	v_mfma_f32_16x16x32_bf16 v[2:5], v[188:191], v[224:227], 0
	v_mfma_f32_16x16x32_bf16 v[54:57], v[184:187], v[200:203], v[54:57]
	v_mfma_f32_16x16x32_bf16 v[50:53], v[192:195], v[200:203], v[50:53]
	v_mfma_f32_16x16x32_bf16 v[38:41], v[184:187], v[208:211], v[38:41]
	v_mfma_f32_16x16x32_bf16 v[34:37], v[192:195], v[208:211], v[34:37]
	v_mfma_f32_16x16x32_bf16 v[22:25], v[184:187], v[216:219], v[22:25]
	v_mfma_f32_16x16x32_bf16 v[18:21], v[192:195], v[216:219], v[18:21]
	v_mfma_f32_16x16x32_bf16 v[6:9], v[184:187], v[228:231], v[6:9]
	v_mfma_f32_16x16x32_bf16 v[2:5], v[192:195], v[228:231], v[2:5]
	s_barrier
	s_add_i32 s18, 0, 0x18000
	s_add_i32 s19, 0, 0x1c000
	v_add_u32_e32 v160, s18, v165
	v_add_u32_e32 v164, s19, v165
	ds_read_b128 v[148:151], v160
	ds_read_b128 v[152:155], v160 offset:1024
	ds_read_b128 v[156:159], v160 offset:2048
	ds_read_b128 v[160:163], v160 offset:3072
	ds_read_b128 v[180:183], v164
	ds_read_b128 v[184:187], v164 offset:1024
	ds_read_b128 v[188:191], v164 offset:2048
	ds_read_b128 v[192:195], v164 offset:3072
	s_add_u32 s44, s44, 0x80000
	s_addc_u32 s45, s45, 0
	s_mov_b32 m0, s53
	ds_read_b128 v[196:199], v173 offset:32768
	ds_read_b128 v[200:203], v173 offset:33792
	ds_read_b128 v[204:207], v173 offset:34816
	ds_read_b128 v[208:211], v173 offset:35840
	ds_read_b128 v[212:215], v173 offset:36864
	ds_read_b128 v[216:219], v173 offset:37888
	ds_read_b128 v[224:227], v173 offset:38912
	ds_read_b128 v[228:231], v173 offset:39936
	global_load_lds_dwordx4 v136, s[44:45]
	s_mov_b32 m0, s57
	s_nop 0
	global_load_lds_dwordx4 v132, s[44:45]
	s_waitcnt vmcnt(9)
	s_waitcnt lgkmcnt(0)
	s_barrier
	s_waitcnt lgkmcnt(0)
	v_mfma_f32_16x16x32_bf16 v[126:129], v[148:151], v[196:199], v[126:129]
	v_mfma_f32_16x16x32_bf16 v[122:125], v[156:159], v[196:199], v[122:125]
	v_mfma_f32_16x16x32_bf16 v[110:113], v[148:151], v[204:207], v[110:113]
	v_mfma_f32_16x16x32_bf16 v[106:109], v[156:159], v[204:207], v[106:109]
	v_mfma_f32_16x16x32_bf16 v[94:97], v[148:151], v[212:215], v[94:97]
	v_mfma_f32_16x16x32_bf16 v[90:93], v[156:159], v[212:215], v[90:93]
	v_mfma_f32_16x16x32_bf16 v[78:81], v[148:151], v[224:227], v[78:81]
	v_mfma_f32_16x16x32_bf16 v[74:77], v[156:159], v[224:227], v[74:77]
	v_mfma_f32_16x16x32_bf16 v[126:129], v[152:155], v[200:203], v[126:129]
	v_mfma_f32_16x16x32_bf16 v[122:125], v[160:163], v[200:203], v[122:125]
	v_mfma_f32_16x16x32_bf16 v[110:113], v[152:155], v[208:211], v[110:113]
	v_mfma_f32_16x16x32_bf16 v[106:109], v[160:163], v[208:211], v[106:109]
	v_mfma_f32_16x16x32_bf16 v[94:97], v[152:155], v[216:219], v[94:97]
	v_mfma_f32_16x16x32_bf16 v[90:93], v[160:163], v[216:219], v[90:93]
	v_mfma_f32_16x16x32_bf16 v[78:81], v[152:155], v[228:231], v[78:81]
	v_mfma_f32_16x16x32_bf16 v[74:77], v[160:163], v[228:231], v[74:77]
	v_mfma_f32_16x16x32_bf16 v[118:121], v[180:183], v[196:199], v[118:121]
	v_mfma_f32_16x16x32_bf16 v[114:117], v[188:191], v[196:199], v[114:117]
	v_mfma_f32_16x16x32_bf16 v[102:105], v[180:183], v[204:207], v[102:105]
	v_mfma_f32_16x16x32_bf16 v[98:101], v[188:191], v[204:207], v[98:101]
	v_mfma_f32_16x16x32_bf16 v[86:89], v[180:183], v[212:215], v[86:89]
	v_mfma_f32_16x16x32_bf16 v[82:85], v[188:191], v[212:215], v[82:85]
	v_mfma_f32_16x16x32_bf16 v[70:73], v[180:183], v[224:227], v[70:73]
	v_mfma_f32_16x16x32_bf16 v[66:69], v[188:191], v[224:227], v[66:69]
	v_mfma_f32_16x16x32_bf16 v[118:121], v[184:187], v[200:203], v[118:121]
	v_mfma_f32_16x16x32_bf16 v[114:117], v[192:195], v[200:203], v[114:117]
	v_mfma_f32_16x16x32_bf16 v[102:105], v[184:187], v[208:211], v[102:105]
	v_mfma_f32_16x16x32_bf16 v[98:101], v[192:195], v[208:211], v[98:101]
	v_mfma_f32_16x16x32_bf16 v[86:89], v[184:187], v[216:219], v[86:89]
	v_mfma_f32_16x16x32_bf16 v[82:85], v[192:195], v[216:219], v[82:85]
	v_mfma_f32_16x16x32_bf16 v[70:73], v[184:187], v[228:231], v[70:73]
	v_mfma_f32_16x16x32_bf16 v[66:69], v[192:195], v[228:231], v[66:69]
	s_barrier
; #define PG8_STAGE(bufoff, gbase, voff) do { _Pragma("unroll") for (int _i = 0; _i < 2; ++_i) \
;         __builtin_amdgcn_global_load_lds((const unsigned*)((const char*)(gbase) + (voff)[_i]), (PG8_LAS unsigned*)(lds + (bufoff) + ldsw + _i * 8192), 16, 0, 0); } while (0)
; #define PG8_LDA(dst, b, h) do { _Pragma("unroll") for (int m = 0; m < 4; ++m) _Pragma("unroll") for (int k = 0; k < 2; ++k) dst[m][k] = *(const PG8_LAS bf16x8*)(lds + PG8_SA(b, h) + aoff + m * 2048 + k * 1024); } while (0)
; #define PG8_LDB(dst, b, h) do { _Pragma("unroll") for (int n = 0; n < 2; ++n) _Pragma("unroll") for (int k = 0; k < 2; ++k) dst[n][k] = *(const PG8_LAS bf16x8*)(lds + PG8_SB(b, h) + boff + n * 2048 + k * 1024); } while (0)
; template <class Epi, class Sched, bool ALIGN_EPI = false, bool SP2 = false>
; __device__ __forceinline__ void gemm_phase(PG8_LAS unsigned char* lds, const Gemm g, const Sched& S, const Epi& E) {
;     ...
;         for (int t = 0; t < nt; t += 2) {
;             const bool last = (t == nt - 2);
;             const char* a1 = cA + (size_t)(t + 1) * kstep;
;             const char* a2 = last ? nA : cA + (size_t)(t + 2) * kstep; const char* b2 = last ? nB : cB + (size_t)(t + 2) * kstep;
;             const char* a3 = a2 + kstep; const char* b3 = b2 + kstep;
;             if (last && has_next) S.a_ready(nxt);
;             if constexpr (SP2) {
;             PG8_LDB(B0, 0, 0); PG8_LDB(B1, 0, 1); PG8_SCHED; PG8_LDA(At, 0, 0); PG8_STAGE(PG8_SA(1, 1), a1 + hA, voffA);
;             PG8_WAIT_V(8); PG8_WAIT_L(0); PG8_BAR; PG8_MMA(0, 0, At, B0); PG8_MMA(0, 1, At, B1); PG8_BAR; PG8_SCHED;
;             PG8_LDA(At, 0, 1); PG8_STAGE(PG8_SB(0, 0), b2, voffB); PG8_STAGE(PG8_SB(0, 1), b2 + hB, voffB); PG8_STAGE(PG8_SA(0, 0), a2, voffA);
;             PG8_WAIT_V(8); PG8_WAIT_L(0); PG8_BAR; PG8_MMA(1, 0, At, B0); PG8_MMA(1, 1, At, B1); PG8_BAR; PG8_SCHED;
;             PG8_LDB(B0, 1, 0); PG8_LDB(B1, 1, 1); PG8_SCHED; PG8_LDA(At, 1, 0); PG8_STAGE(PG8_SA(0, 1), a2 + hA, voffA);
;             PG8_WAIT_V(8); PG8_WAIT_L(0); PG8_BAR; PG8_MMA(0, 0, At, B0); PG8_MMA(0, 1, At, B1); PG8_BAR; PG8_SCHED;
;             PG8_LDA(At, 1, 1); PG8_STAGE(PG8_SB(1, 0), b3, voffB); PG8_STAGE(PG8_SB(1, 1), b3 + hB, voffB); PG8_STAGE(PG8_SA(1, 0), a3, voffA);
;             PG8_WAIT_V(8); PG8_WAIT_L(0); PG8_BAR; PG8_MMA(1, 0, At, B0); PG8_MMA(1, 1, At, B1); PG8_BAR; PG8_SCHED;
	s_add_i32 s18, s18, s49
	s_mov_b32 m0, s18
	ds_read_b128 v[196:199], v173 offset:49152
	ds_read_b128 v[200:203], v173 offset:50176
	ds_read_b128 v[204:207], v173 offset:51200
	ds_read_b128 v[208:211], v173 offset:52224
	ds_read_b128 v[212:215], v173 offset:53248
	ds_read_b128 v[216:219], v173 offset:54272
	ds_read_b128 v[224:227], v173 offset:55296
	ds_read_b128 v[228:231], v173 offset:56320
	global_load_lds_dwordx4 v134, s[76:77]
	s_add_i32 m0, s18, 0x2000
	s_add_u32 s42, s42, 0x80080
	s_addc_u32 s43, s43, 0
	s_add_i32 s18, s19, s49
	global_load_lds_dwordx4 v130, s[76:77]
	s_mov_b32 m0, s18
	s_nop 0
	global_load_lds_dwordx4 v134, s[42:43]
	s_add_i32 m0, s18, 0x2000
	s_nop 0
	global_load_lds_dwordx4 v130, s[42:43]
	s_mov_b32 m0, s60
	s_nop 0
	global_load_lds_dwordx4 v136, s[78:79]
	s_mov_b32 m0, s61
	s_nop 0
	global_load_lds_dwordx4 v132, s[78:79]
	global_load_dword v247, v[240:241], off
	v_lshl_add_u64 v[240:241], v[240:241], 0, s[80:81]
	s_waitcnt vmcnt(10)
	s_waitcnt lgkmcnt(0)
	s_barrier
	s_waitcnt lgkmcnt(0)
	v_mfma_f32_16x16x32_bf16 v[62:65], v[148:151], v[196:199], v[62:65]
	v_mfma_f32_16x16x32_bf16 v[58:61], v[156:159], v[196:199], v[58:61]
	v_mfma_f32_16x16x32_bf16 v[46:49], v[148:151], v[204:207], v[46:49]
	v_mfma_f32_16x16x32_bf16 v[42:45], v[156:159], v[204:207], v[42:45]
	v_mfma_f32_16x16x32_bf16 v[30:33], v[148:151], v[212:215], v[30:33]
	v_mfma_f32_16x16x32_bf16 v[26:29], v[156:159], v[212:215], v[26:29]
	v_mfma_f32_16x16x32_bf16 v[14:17], v[148:151], v[224:227], v[14:17]
	v_mfma_f32_16x16x32_bf16 v[10:13], v[156:159], v[224:227], v[10:13]
	v_mfma_f32_16x16x32_bf16 v[62:65], v[152:155], v[200:203], v[62:65]
	v_mfma_f32_16x16x32_bf16 v[58:61], v[160:163], v[200:203], v[58:61]
	v_mfma_f32_16x16x32_bf16 v[46:49], v[152:155], v[208:211], v[46:49]
	v_mfma_f32_16x16x32_bf16 v[42:45], v[160:163], v[208:211], v[42:45]
	v_mfma_f32_16x16x32_bf16 v[30:33], v[152:155], v[216:219], v[30:33]
	v_mfma_f32_16x16x32_bf16 v[26:29], v[160:163], v[216:219], v[26:29]
	v_mfma_f32_16x16x32_bf16 v[14:17], v[152:155], v[228:231], v[14:17]
	v_mfma_f32_16x16x32_bf16 v[10:13], v[160:163], v[228:231], v[10:13]
	v_mfma_f32_16x16x32_bf16 v[54:57], v[180:183], v[196:199], v[54:57]
	v_mfma_f32_16x16x32_bf16 v[50:53], v[188:191], v[196:199], v[50:53]
	v_mfma_f32_16x16x32_bf16 v[38:41], v[180:183], v[204:207], v[38:41]
	v_mfma_f32_16x16x32_bf16 v[34:37], v[188:191], v[204:207], v[34:37]
	v_mfma_f32_16x16x32_bf16 v[22:25], v[180:183], v[212:215], v[22:25]
	v_mfma_f32_16x16x32_bf16 v[18:21], v[188:191], v[212:215], v[18:21]
	v_mfma_f32_16x16x32_bf16 v[6:9], v[180:183], v[224:227], v[6:9]
	v_mfma_f32_16x16x32_bf16 v[2:5], v[188:191], v[224:227], v[2:5]
	v_mfma_f32_16x16x32_bf16 v[54:57], v[184:187], v[200:203], v[54:57]
	v_mfma_f32_16x16x32_bf16 v[50:53], v[192:195], v[200:203], v[50:53]
	v_mfma_f32_16x16x32_bf16 v[38:41], v[184:187], v[208:211], v[38:41]
	v_mfma_f32_16x16x32_bf16 v[34:37], v[192:195], v[208:211], v[34:37]
	v_mfma_f32_16x16x32_bf16 v[22:25], v[184:187], v[216:219], v[22:25]
	v_mfma_f32_16x16x32_bf16 v[18:21], v[192:195], v[216:219], v[18:21]
	v_mfma_f32_16x16x32_bf16 v[6:9], v[184:187], v[228:231], v[6:9]
	v_mfma_f32_16x16x32_bf16 v[2:5], v[192:195], v[228:231], v[2:5]
	s_barrier
	s_add_i32 s72, s72, 2
	s_add_u32 s8, s8, 0x100
	s_addc_u32 s9, s9, 0
	s_add_u32 s70, s70, 0x100
	s_addc_u32 s71, s71, 0
	s_cmp_gt_u32 s72, 29
.LBB0_1048:
	ds_read_b128 v[148:151], v169
	ds_read_b128 v[152:155], v169 offset:1024
	ds_read_b128 v[156:159], v169 offset:2048
	ds_read_b128 v[160:163], v169 offset:3072
	ds_read_b128 v[180:183], v171
	ds_read_b128 v[184:187], v171 offset:1024
	ds_read_b128 v[188:191], v171 offset:2048
	ds_read_b128 v[192:195], v171 offset:3072
	s_add_u32 s18, s8, 0xfff80080
	s_addc_u32 s19, s9, -1
	s_cmp_eq_u32 s72, 28
	s_cselect_b32 s45, s1, s19
	s_cselect_b32 s44, s37, s18
	s_cselect_b32 s43, s25, s71
	s_cselect_b32 s42, s69, s70
	s_cmp_lt_i32 s72, 23
	s_cselect_b32 s80, 0x80, 0
	s_add_i32 m0, s51, 0xc000
	ds_read_b128 v[196:199], v173
	ds_read_b128 v[200:203], v173 offset:1024
	ds_read_b128 v[204:207], v173 offset:2048
	ds_read_b128 v[208:211], v173 offset:3072
	ds_read_b128 v[212:215], v173 offset:4096
	ds_read_b128 v[216:219], v173 offset:5120
	ds_read_b128 v[224:227], v173 offset:6144
	ds_read_b128 v[228:231], v173 offset:7168
	global_load_lds_dwordx4 v140, s[8:9]
	s_add_i32 m0, s51, 0xe000
	s_nop 0
	global_load_lds_dwordx4 v142, s[8:9]
	s_waitcnt vmcnt(9)
	s_waitcnt lgkmcnt(0)
	s_barrier
	s_waitcnt lgkmcnt(0)
	v_mfma_f32_16x16x32_bf16 v[126:129], v[148:151], v[196:199], v[126:129]
	v_mfma_f32_16x16x32_bf16 v[122:125], v[156:159], v[196:199], v[122:125]
	v_mfma_f32_16x16x32_bf16 v[110:113], v[148:151], v[204:207], v[110:113]
	v_mfma_f32_16x16x32_bf16 v[106:109], v[156:159], v[204:207], v[106:109]
	v_mfma_f32_16x16x32_bf16 v[94:97], v[148:151], v[212:215], v[94:97]
	v_mfma_f32_16x16x32_bf16 v[90:93], v[156:159], v[212:215], v[90:93]
	v_mfma_f32_16x16x32_bf16 v[78:81], v[148:151], v[224:227], v[78:81]
	v_mfma_f32_16x16x32_bf16 v[74:77], v[156:159], v[224:227], v[74:77]
	v_mfma_f32_16x16x32_bf16 v[126:129], v[152:155], v[200:203], v[126:129]
	v_mfma_f32_16x16x32_bf16 v[122:125], v[160:163], v[200:203], v[122:125]
	v_mfma_f32_16x16x32_bf16 v[110:113], v[152:155], v[208:211], v[110:113]
	v_mfma_f32_16x16x32_bf16 v[106:109], v[160:163], v[208:211], v[106:109]
	v_mfma_f32_16x16x32_bf16 v[94:97], v[152:155], v[216:219], v[94:97]
	v_mfma_f32_16x16x32_bf16 v[90:93], v[160:163], v[216:219], v[90:93]
	v_mfma_f32_16x16x32_bf16 v[78:81], v[152:155], v[228:231], v[78:81]
	v_mfma_f32_16x16x32_bf16 v[74:77], v[160:163], v[228:231], v[74:77]
	v_mfma_f32_16x16x32_bf16 v[118:121], v[180:183], v[196:199], v[118:121]
	v_mfma_f32_16x16x32_bf16 v[114:117], v[188:191], v[196:199], v[114:117]
	v_mfma_f32_16x16x32_bf16 v[102:105], v[180:183], v[204:207], v[102:105]
	v_mfma_f32_16x16x32_bf16 v[98:101], v[188:191], v[204:207], v[98:101]
	v_mfma_f32_16x16x32_bf16 v[86:89], v[180:183], v[212:215], v[86:89]
	v_mfma_f32_16x16x32_bf16 v[82:85], v[188:191], v[212:215], v[82:85]
	v_mfma_f32_16x16x32_bf16 v[70:73], v[180:183], v[224:227], v[70:73]
	v_mfma_f32_16x16x32_bf16 v[66:69], v[188:191], v[224:227], v[66:69]
	v_mfma_f32_16x16x32_bf16 v[118:121], v[184:187], v[200:203], v[118:121]
	v_mfma_f32_16x16x32_bf16 v[114:117], v[192:195], v[200:203], v[114:117]
	v_mfma_f32_16x16x32_bf16 v[102:105], v[184:187], v[208:211], v[102:105]
	v_mfma_f32_16x16x32_bf16 v[98:101], v[192:195], v[208:211], v[98:101]
	v_mfma_f32_16x16x32_bf16 v[86:89], v[184:187], v[216:219], v[86:89]
	v_mfma_f32_16x16x32_bf16 v[82:85], v[192:195], v[216:219], v[82:85]
	v_mfma_f32_16x16x32_bf16 v[70:73], v[184:187], v[228:231], v[70:73]
	v_mfma_f32_16x16x32_bf16 v[66:69], v[192:195], v[228:231], v[66:69]
	s_barrier
; #define PG8_STAGE(bufoff, gbase, voff) do { _Pragma("unroll") for (int _i = 0; _i < 2; ++_i) \
;         __builtin_amdgcn_global_load_lds((const unsigned*)((const char*)(gbase) + (voff)[_i]), (PG8_LAS unsigned*)(lds + (bufoff) + ldsw + _i * 8192), 16, 0, 0); } while (0)
; #define PG8_LDA(dst, b, h) do { _Pragma("unroll") for (int m = 0; m < 4; ++m) _Pragma("unroll") for (int k = 0; k < 2; ++k) dst[m][k] = *(const PG8_LAS bf16x8*)(lds + PG8_SA(b, h) + aoff + m * 2048 + k * 1024); } while (0)
; #define PG8_LDB(dst, b, h) do { _Pragma("unroll") for (int n = 0; n < 2; ++n) _Pragma("unroll") for (int k = 0; k < 2; ++k) dst[n][k] = *(const PG8_LAS bf16x8*)(lds + PG8_SB(b, h) + boff + n * 2048 + k * 1024); } while (0)
; #define PG8_MMA(ai, bj, At, Bt) do { __builtin_amdgcn_s_setprio(1); _Pragma("unroll") for (int m = 0; m < 4; ++m) _Pragma("unroll") for (int n = 0; n < 2; ++n) _Pragma("unroll") for (int k = 0; k < 2; ++k) \
;         acc[ai][bj][m][n] = __builtin_amdgcn_mfma_f32_16x16x32_bf16(Bt[n][k], At[m][k], acc[ai][bj][m][n], 0, 0, 0); __builtin_amdgcn_s_setprio(0); } while (0)
; #define PG8_WAIT_V(n) asm volatile("s_waitcnt vmcnt(" #n ")" ::: "memory")
; #define PG8_WAIT_L(n) asm volatile("s_waitcnt lgkmcnt(" #n ")" ::: "memory")
; #define PG8_BAR __builtin_amdgcn_s_barrier()
; template <class Epi, class Sched, bool ALIGN_EPI = false, bool SP2 = false>
; __device__ __forceinline__ void gemm_phase(PG8_LAS unsigned char* lds, const Gemm g, const Sched& S, const Epi& E) {
;     ...
;             PG8_LDB(B0, 0, 0); PG8_LDB(B1, 0, 1); PG8_SCHED; PG8_LDA(At, 0, 0); PG8_STAGE(PG8_SA(1, 1), a1 + hA, voffA);
;             PG8_WAIT_V(8); PG8_WAIT_L(0); PG8_BAR; PG8_MMA(0, 0, At, B0); PG8_MMA(0, 1, At, B1); PG8_BAR; PG8_SCHED;
;             PG8_LDA(At, 0, 1); PG8_STAGE(PG8_SB(0, 0), b2, voffB); PG8_STAGE(PG8_SB(0, 1), b2 + hB, voffB); PG8_STAGE(PG8_SA(0, 0), a2, voffA);
;             PG8_WAIT_V(8); PG8_WAIT_L(0); PG8_BAR; PG8_MMA(1, 0, At, B0); PG8_MMA(1, 1, At, B1); PG8_BAR; PG8_SCHED;
;             PG8_LDB(B0, 1, 0); PG8_LDB(B1, 1, 1); PG8_SCHED; PG8_LDA(At, 1, 0); PG8_STAGE(PG8_SA(0, 1), a2 + hA, voffA);
;             PG8_WAIT_V(8); PG8_WAIT_L(0); PG8_BAR; PG8_MMA(0, 0, At, B0); PG8_MMA(0, 1, At, B1); PG8_BAR; PG8_SCHED;
;             PG8_LDA(At, 1, 1); PG8_STAGE(PG8_SB(1, 0), b3, voffB); PG8_STAGE(PG8_SB(1, 1), b3 + hB, voffB); PG8_STAGE(PG8_SA(1, 0), a3, voffA);
	s_add_i32 s18, s63, s49
	s_add_u32 s76, s42, s20
	s_addc_u32 s77, s43, s21
	s_mov_b32 m0, s18
	ds_read_b128 v[196:199], v173 offset:16384
	ds_read_b128 v[200:203], v173 offset:17408
	ds_read_b128 v[204:207], v173 offset:18432
	ds_read_b128 v[208:211], v173 offset:19456
	ds_read_b128 v[212:215], v173 offset:20480
	ds_read_b128 v[216:219], v173 offset:21504
	ds_read_b128 v[224:227], v173 offset:22528
	ds_read_b128 v[228:231], v173 offset:23552
	global_load_lds_dwordx4 v134, s[42:43]
	s_add_i32 m0, s18, 0x2000
	s_add_u32 s74, s42, 0x80000
	s_addc_u32 s75, s43, 0
	s_add_i32 s18, s64, s49
	global_load_lds_dwordx4 v130, s[42:43]
	s_mov_b32 m0, s18
	s_nop 0
	global_load_lds_dwordx4 v134, s[74:75]
	s_add_i32 m0, s18, 0x2000
	s_nop 0
	global_load_lds_dwordx4 v130, s[74:75]
	s_add_u32 s78, s44, s20
	s_addc_u32 s79, s45, s21
	s_mov_b32 m0, s51
	s_nop 0
	global_load_lds_dwordx4 v136, s[44:45]
	s_mov_b32 m0, s52
	s_nop 0
	global_load_lds_dwordx4 v132, s[44:45]
	global_load_dword v247, v[240:241], off
	v_lshl_add_u64 v[240:241], v[240:241], 0, s[80:81]
	s_waitcnt vmcnt(10)
	s_waitcnt lgkmcnt(0)
	s_barrier
	s_waitcnt lgkmcnt(0)
	v_mfma_f32_16x16x32_bf16 v[62:65], v[148:151], v[196:199], v[62:65]
	v_mfma_f32_16x16x32_bf16 v[58:61], v[156:159], v[196:199], v[58:61]
	v_mfma_f32_16x16x32_bf16 v[46:49], v[148:151], v[204:207], v[46:49]
	v_mfma_f32_16x16x32_bf16 v[42:45], v[156:159], v[204:207], v[42:45]
	v_mfma_f32_16x16x32_bf16 v[30:33], v[148:151], v[212:215], v[30:33]
	v_mfma_f32_16x16x32_bf16 v[26:29], v[156:159], v[212:215], v[26:29]
	v_mfma_f32_16x16x32_bf16 v[14:17], v[148:151], v[224:227], v[14:17]
	v_mfma_f32_16x16x32_bf16 v[10:13], v[156:159], v[224:227], v[10:13]
	v_mfma_f32_16x16x32_bf16 v[62:65], v[152:155], v[200:203], v[62:65]
	v_mfma_f32_16x16x32_bf16 v[58:61], v[160:163], v[200:203], v[58:61]
	v_mfma_f32_16x16x32_bf16 v[46:49], v[152:155], v[208:211], v[46:49]
	v_mfma_f32_16x16x32_bf16 v[42:45], v[160:163], v[208:211], v[42:45]
	v_mfma_f32_16x16x32_bf16 v[30:33], v[152:155], v[216:219], v[30:33]
	v_mfma_f32_16x16x32_bf16 v[26:29], v[160:163], v[216:219], v[26:29]
	v_mfma_f32_16x16x32_bf16 v[14:17], v[152:155], v[228:231], v[14:17]
	v_mfma_f32_16x16x32_bf16 v[10:13], v[160:163], v[228:231], v[10:13]
	v_mfma_f32_16x16x32_bf16 v[54:57], v[180:183], v[196:199], v[54:57]
	v_mfma_f32_16x16x32_bf16 v[50:53], v[188:191], v[196:199], v[50:53]
	v_mfma_f32_16x16x32_bf16 v[38:41], v[180:183], v[204:207], v[38:41]
	v_mfma_f32_16x16x32_bf16 v[34:37], v[188:191], v[204:207], v[34:37]
	v_mfma_f32_16x16x32_bf16 v[22:25], v[180:183], v[212:215], v[22:25]
	v_mfma_f32_16x16x32_bf16 v[18:21], v[188:191], v[212:215], v[18:21]
	v_mfma_f32_16x16x32_bf16 v[6:9], v[180:183], v[224:227], v[6:9]
	v_mfma_f32_16x16x32_bf16 v[2:5], v[188:191], v[224:227], v[2:5]
	v_mfma_f32_16x16x32_bf16 v[54:57], v[184:187], v[200:203], v[54:57]
	v_mfma_f32_16x16x32_bf16 v[50:53], v[192:195], v[200:203], v[50:53]
	v_mfma_f32_16x16x32_bf16 v[38:41], v[184:187], v[208:211], v[38:41]
	v_mfma_f32_16x16x32_bf16 v[34:37], v[192:195], v[208:211], v[34:37]
	v_mfma_f32_16x16x32_bf16 v[22:25], v[184:187], v[216:219], v[22:25]
	v_mfma_f32_16x16x32_bf16 v[18:21], v[192:195], v[216:219], v[18:21]
	v_mfma_f32_16x16x32_bf16 v[6:9], v[184:187], v[228:231], v[6:9]
	v_mfma_f32_16x16x32_bf16 v[2:5], v[192:195], v[228:231], v[2:5]
	s_barrier
	s_add_i32 s18, 0, 0x18000
	s_add_i32 s19, 0, 0x1c000
	v_add_u32_e32 v160, s18, v165
	v_add_u32_e32 v164, s19, v165
	ds_read_b128 v[148:151], v160
	ds_read_b128 v[152:155], v160 offset:1024
	ds_read_b128 v[156:159], v160 offset:2048
	ds_read_b128 v[160:163], v160 offset:3072
	ds_read_b128 v[180:183], v164
	ds_read_b128 v[184:187], v164 offset:1024
	ds_read_b128 v[188:191], v164 offset:2048
	ds_read_b128 v[192:195], v164 offset:3072
	s_add_u32 s44, s44, 0x80000
	s_addc_u32 s45, s45, 0
	s_mov_b32 m0, s53
	ds_read_b128 v[196:199], v173 offset:32768
	ds_read_b128 v[200:203], v173 offset:33792
	ds_read_b128 v[204:207], v173 offset:34816
	ds_read_b128 v[208:211], v173 offset:35840
	ds_read_b128 v[212:215], v173 offset:36864
	ds_read_b128 v[216:219], v173 offset:37888
	ds_read_b128 v[224:227], v173 offset:38912
	ds_read_b128 v[228:231], v173 offset:39936
	global_load_lds_dwordx4 v136, s[44:45]
	s_mov_b32 m0, s57
	s_nop 0
	global_load_lds_dwordx4 v132, s[44:45]
	s_waitcnt vmcnt(9)
	s_waitcnt lgkmcnt(0)
	s_barrier
; #define PG8_STAGE(bufoff, gbase, voff) do { _Pragma("unroll") for (int _i = 0; _i < 2; ++_i) \
;         __builtin_amdgcn_global_load_lds((const unsigned*)((const char*)(gbase) + (voff)[_i]), (PG8_LAS unsigned*)(lds + (bufoff) + ldsw + _i * 8192), 16, 0, 0); } while (0)
; #define PG8_LDA(dst, b, h) do { _Pragma("unroll") for (int m = 0; m < 4; ++m) _Pragma("unroll") for (int k = 0; k < 2; ++k) dst[m][k] = *(const PG8_LAS bf16x8*)(lds + PG8_SA(b, h) + aoff + m * 2048 + k * 1024); } while (0)
; #define PG8_LDB(dst, b, h) do { _Pragma("unroll") for (int n = 0; n < 2; ++n) _Pragma("unroll") for (int k = 0; k < 2; ++k) dst[n][k] = *(const PG8_LAS bf16x8*)(lds + PG8_SB(b, h) + boff + n * 2048 + k * 1024); } while (0)
; #define PG8_MMA(ai, bj, At, Bt) do { __builtin_amdgcn_s_setprio(1); _Pragma("unroll") for (int m = 0; m < 4; ++m) _Pragma("unroll") for (int n = 0; n < 2; ++n) _Pragma("unroll") for (int k = 0; k < 2; ++k) \
;         acc[ai][bj][m][n] = __builtin_amdgcn_mfma_f32_16x16x32_bf16(Bt[n][k], At[m][k], acc[ai][bj][m][n], 0, 0, 0); __builtin_amdgcn_s_setprio(0); } while (0)
; template <class Epi, class Sched, bool ALIGN_EPI = false, bool SP2 = false>
; __device__ __forceinline__ void gemm_phase(PG8_LAS unsigned char* lds, const Gemm g, const Sched& S, const Epi& E) {
;     ...
;             PG8_LDB(B0, 0, 0); PG8_LDB(B1, 0, 1); PG8_SCHED; PG8_LDA(At, 0, 0); PG8_STAGE(PG8_SA(1, 1), a1 + hA, voffA);
;             PG8_WAIT_V(8); PG8_WAIT_L(0); PG8_BAR; PG8_MMA(0, 0, At, B0); PG8_MMA(0, 1, At, B1); PG8_BAR; PG8_SCHED;
;             PG8_LDA(At, 0, 1); PG8_STAGE(PG8_SB(0, 0), b2, voffB); PG8_STAGE(PG8_SB(0, 1), b2 + hB, voffB); PG8_STAGE(PG8_SA(0, 0), a2, voffA);
;             PG8_WAIT_V(8); PG8_WAIT_L(0); PG8_BAR; PG8_MMA(1, 0, At, B0); PG8_MMA(1, 1, At, B1); PG8_BAR; PG8_SCHED;
;             PG8_LDB(B0, 1, 0); PG8_LDB(B1, 1, 1); PG8_SCHED; PG8_LDA(At, 1, 0); PG8_STAGE(PG8_SA(0, 1), a2 + hA, voffA);
;             PG8_WAIT_V(8); PG8_WAIT_L(0); PG8_BAR; PG8_MMA(0, 0, At, B0); PG8_MMA(0, 1, At, B1); PG8_BAR; PG8_SCHED;
;             PG8_LDA(At, 1, 1); PG8_STAGE(PG8_SB(1, 0), b3, voffB); PG8_STAGE(PG8_SB(1, 1), b3 + hB, voffB); PG8_STAGE(PG8_SA(1, 0), a3, voffA);
;             PG8_WAIT_V(8); PG8_WAIT_L(0); PG8_BAR; PG8_MMA(1, 0, At, B0); PG8_MMA(1, 1, At, B1); PG8_BAR; PG8_SCHED;
;     ...
;         if constexpr (ALIGN_EPI) { if (wr == 0) PG8_BAR; }
	s_waitcnt lgkmcnt(0)
	v_mfma_f32_16x16x32_bf16 v[126:129], v[148:151], v[196:199], v[126:129]
	v_mfma_f32_16x16x32_bf16 v[122:125], v[156:159], v[196:199], v[122:125]
	v_mfma_f32_16x16x32_bf16 v[110:113], v[148:151], v[204:207], v[110:113]
	v_mfma_f32_16x16x32_bf16 v[106:109], v[156:159], v[204:207], v[106:109]
	v_mfma_f32_16x16x32_bf16 v[94:97], v[148:151], v[212:215], v[94:97]
	v_mfma_f32_16x16x32_bf16 v[90:93], v[156:159], v[212:215], v[90:93]
	v_mfma_f32_16x16x32_bf16 v[78:81], v[148:151], v[224:227], v[78:81]
	v_mfma_f32_16x16x32_bf16 v[74:77], v[156:159], v[224:227], v[74:77]
	v_mfma_f32_16x16x32_bf16 v[126:129], v[152:155], v[200:203], v[126:129]
	v_mfma_f32_16x16x32_bf16 v[122:125], v[160:163], v[200:203], v[122:125]
	v_mfma_f32_16x16x32_bf16 v[110:113], v[152:155], v[208:211], v[110:113]
	v_mfma_f32_16x16x32_bf16 v[106:109], v[160:163], v[208:211], v[106:109]
	v_mfma_f32_16x16x32_bf16 v[94:97], v[152:155], v[216:219], v[94:97]
	v_mfma_f32_16x16x32_bf16 v[90:93], v[160:163], v[216:219], v[90:93]
	v_mfma_f32_16x16x32_bf16 v[78:81], v[152:155], v[228:231], v[78:81]
	v_mfma_f32_16x16x32_bf16 v[74:77], v[160:163], v[228:231], v[74:77]
	v_mfma_f32_16x16x32_bf16 v[118:121], v[180:183], v[196:199], v[118:121]
	v_mfma_f32_16x16x32_bf16 v[114:117], v[188:191], v[196:199], v[114:117]
	v_mfma_f32_16x16x32_bf16 v[102:105], v[180:183], v[204:207], v[102:105]
	v_mfma_f32_16x16x32_bf16 v[98:101], v[188:191], v[204:207], v[98:101]
	v_mfma_f32_16x16x32_bf16 v[86:89], v[180:183], v[212:215], v[86:89]
	v_mfma_f32_16x16x32_bf16 v[82:85], v[188:191], v[212:215], v[82:85]
	v_mfma_f32_16x16x32_bf16 v[70:73], v[180:183], v[224:227], v[70:73]
	v_mfma_f32_16x16x32_bf16 v[66:69], v[188:191], v[224:227], v[66:69]
	v_mfma_f32_16x16x32_bf16 v[118:121], v[184:187], v[200:203], v[118:121]
	v_mfma_f32_16x16x32_bf16 v[114:117], v[192:195], v[200:203], v[114:117]
	v_mfma_f32_16x16x32_bf16 v[102:105], v[184:187], v[208:211], v[102:105]
	v_mfma_f32_16x16x32_bf16 v[98:101], v[192:195], v[208:211], v[98:101]
	v_mfma_f32_16x16x32_bf16 v[86:89], v[184:187], v[216:219], v[86:89]
	v_mfma_f32_16x16x32_bf16 v[82:85], v[192:195], v[216:219], v[82:85]
	v_mfma_f32_16x16x32_bf16 v[70:73], v[184:187], v[228:231], v[70:73]
	v_mfma_f32_16x16x32_bf16 v[66:69], v[192:195], v[228:231], v[66:69]
	s_barrier
	s_add_i32 s18, s18, s49
	s_mov_b32 m0, s18
	ds_read_b128 v[196:199], v173 offset:49152
	ds_read_b128 v[200:203], v173 offset:50176
	ds_read_b128 v[204:207], v173 offset:51200
	ds_read_b128 v[208:211], v173 offset:52224
	ds_read_b128 v[212:215], v173 offset:53248
	ds_read_b128 v[216:219], v173 offset:54272
	ds_read_b128 v[224:227], v173 offset:55296
	ds_read_b128 v[228:231], v173 offset:56320
	global_load_lds_dwordx4 v134, s[76:77]
	s_add_i32 m0, s18, 0x2000
	s_add_u32 s42, s42, 0x80080
	s_addc_u32 s43, s43, 0
	s_add_i32 s18, s19, s49
	global_load_lds_dwordx4 v130, s[76:77]
	s_mov_b32 m0, s18
	s_nop 0
	global_load_lds_dwordx4 v134, s[42:43]
	s_add_i32 m0, s18, 0x2000
	s_nop 0
	global_load_lds_dwordx4 v130, s[42:43]
	s_mov_b32 m0, s60
	s_nop 0
	global_load_lds_dwordx4 v136, s[78:79]
	s_mov_b32 m0, s61
	s_nop 0
	global_load_lds_dwordx4 v132, s[78:79]
	global_load_dword v247, v[240:241], off
	v_lshl_add_u64 v[240:241], v[240:241], 0, s[80:81]
	s_waitcnt vmcnt(10)
	s_waitcnt lgkmcnt(0)
	s_barrier
	s_waitcnt lgkmcnt(0)
	v_mfma_f32_16x16x32_bf16 v[62:65], v[148:151], v[196:199], v[62:65]
	v_mfma_f32_16x16x32_bf16 v[58:61], v[156:159], v[196:199], v[58:61]
	v_mfma_f32_16x16x32_bf16 v[46:49], v[148:151], v[204:207], v[46:49]
	v_mfma_f32_16x16x32_bf16 v[42:45], v[156:159], v[204:207], v[42:45]
	v_mfma_f32_16x16x32_bf16 v[30:33], v[148:151], v[212:215], v[30:33]
	v_mfma_f32_16x16x32_bf16 v[26:29], v[156:159], v[212:215], v[26:29]
	v_mfma_f32_16x16x32_bf16 v[14:17], v[148:151], v[224:227], v[14:17]
	v_mfma_f32_16x16x32_bf16 v[10:13], v[156:159], v[224:227], v[10:13]
	v_mfma_f32_16x16x32_bf16 v[62:65], v[152:155], v[200:203], v[62:65]
	v_mfma_f32_16x16x32_bf16 v[58:61], v[160:163], v[200:203], v[58:61]
	v_mfma_f32_16x16x32_bf16 v[46:49], v[152:155], v[208:211], v[46:49]
	v_mfma_f32_16x16x32_bf16 v[42:45], v[160:163], v[208:211], v[42:45]
	v_mfma_f32_16x16x32_bf16 v[30:33], v[152:155], v[216:219], v[30:33]
	v_mfma_f32_16x16x32_bf16 v[26:29], v[160:163], v[216:219], v[26:29]
	v_mfma_f32_16x16x32_bf16 v[14:17], v[152:155], v[228:231], v[14:17]
	v_mfma_f32_16x16x32_bf16 v[10:13], v[160:163], v[228:231], v[10:13]
	v_mfma_f32_16x16x32_bf16 v[54:57], v[180:183], v[196:199], v[54:57]
	v_mfma_f32_16x16x32_bf16 v[50:53], v[188:191], v[196:199], v[50:53]
	v_mfma_f32_16x16x32_bf16 v[38:41], v[180:183], v[204:207], v[38:41]
	v_mfma_f32_16x16x32_bf16 v[34:37], v[188:191], v[204:207], v[34:37]
	v_mfma_f32_16x16x32_bf16 v[22:25], v[180:183], v[212:215], v[22:25]
	v_mfma_f32_16x16x32_bf16 v[18:21], v[188:191], v[212:215], v[18:21]
	v_mfma_f32_16x16x32_bf16 v[6:9], v[180:183], v[224:227], v[6:9]
	v_mfma_f32_16x16x32_bf16 v[2:5], v[188:191], v[224:227], v[2:5]
	v_mfma_f32_16x16x32_bf16 v[54:57], v[184:187], v[200:203], v[54:57]
	v_mfma_f32_16x16x32_bf16 v[50:53], v[192:195], v[200:203], v[50:53]
	v_mfma_f32_16x16x32_bf16 v[38:41], v[184:187], v[208:211], v[38:41]
	v_mfma_f32_16x16x32_bf16 v[34:37], v[192:195], v[208:211], v[34:37]
	v_mfma_f32_16x16x32_bf16 v[22:25], v[184:187], v[216:219], v[22:25]
	v_mfma_f32_16x16x32_bf16 v[18:21], v[192:195], v[216:219], v[18:21]
	v_mfma_f32_16x16x32_bf16 v[6:9], v[184:187], v[228:231], v[6:9]
	v_mfma_f32_16x16x32_bf16 v[2:5], v[192:195], v[228:231], v[2:5]
	s_barrier
	s_add_i32 s72, s72, 2
	s_add_u32 s8, s8, 0x100
	s_addc_u32 s9, s9, 0
	s_add_u32 s70, s70, 0x100
	s_addc_u32 s71, s71, 0
	s_cmp_gt_u32 s72, 29
	s_cbranch_scc0 .LBB0_1048
	s_and_b64 vcc, exec, s[22:23]
	s_cbranch_vccz .LBB0_1051
	s_barrier

; #define PG8_STAGE(bufoff, gbase, voff) do { _Pragma("unroll") for (int _i = 0; _i < 2; ++_i) \
;         __builtin_amdgcn_global_load_lds((const unsigned*)((const char*)(gbase) + (voff)[_i]), (PG8_LAS unsigned*)(lds + (bufoff) + ldsw + _i * 8192), 16, 0, 0); } while (0)
; #define PG8_LDA(dst, b, h) do { _Pragma("unroll") for (int m = 0; m < 4; ++m) _Pragma("unroll") for (int k = 0; k < 2; ++k) dst[m][k] = *(const PG8_LAS bf16x8*)(lds + PG8_SA(b, h) + aoff + m * 2048 + k * 1024); } while (0)
; #define PG8_LDB(dst, b, h) do { _Pragma("unroll") for (int n = 0; n < 2; ++n) _Pragma("unroll") for (int k = 0; k < 2; ++k) dst[n][k] = *(const PG8_LAS bf16x8*)(lds + PG8_SB(b, h) + boff + n * 2048 + k * 1024); } while (0)
; #define PG8_WAIT_V(n) asm volatile("s_waitcnt vmcnt(" #n ")" ::: "memory")
; #define PG8_WAIT_L(n) asm volatile("s_waitcnt lgkmcnt(" #n ")" ::: "memory")
; #define PG8_BAR __builtin_amdgcn_s_barrier()
; #define PG8_SCHED __builtin_amdgcn_sched_barrier(0)
; template <class Epi, class Sched, bool ALIGN_EPI = false, bool SP2 = false>
; __device__ __forceinline__ void gemm_phase(PG8_LAS unsigned char* lds, const Gemm g, const Sched& S, const Epi& E) {
;     ...
;     for (;;) {
;         const bool has_next = S.next(ui + 1, nxt);
;         const char* nA = has_next ? (const char*)g.A + (size_t)nxt.pm * tA + (size_t)nxt.pn * pnA : cA; const char* nB = has_next ? (const char*)g.Bt + (size_t)nxt.pn * tB : cB;
; #pragma nounroll
;         for (int t = 0; t < nt; t += 2) {
;             const bool last = (t == nt - 2);
;             const char* a1 = cA + (size_t)(t + 1) * kstep;
;             const char* a2 = last ? nA : cA + (size_t)(t + 2) * kstep; const char* b2 = last ? nB : cB + (size_t)(t + 2) * kstep;
;             const char* a3 = a2 + kstep; const char* b3 = b2 + kstep;
;             if (last && has_next) S.a_ready(nxt);
;             if constexpr (SP2) {
;             PG8_LDB(B0, 0, 0); PG8_LDB(B1, 0, 1); PG8_SCHED; PG8_LDA(At, 0, 0); PG8_STAGE(PG8_SA(1, 1), a1 + hA, voffA);
;             PG8_WAIT_V(8); PG8_WAIT_L(0); PG8_BAR; PG8_MMA(0, 0, At, B0); PG8_MMA(0, 1, At, B1); PG8_BAR; PG8_SCHED;
;             PG8_LDA(At, 0, 1); PG8_STAGE(PG8_SB(0, 0), b2, voffB); PG8_STAGE(PG8_SB(0, 1), b2 + hB, voffB); PG8_STAGE(PG8_SA(0, 0), a2, voffA);
;             PG8_WAIT_V(8); PG8_WAIT_L(0); PG8_BAR; PG8_MMA(1, 0, At, B0); PG8_MMA(1, 1, At, B1); PG8_BAR; PG8_SCHED;
.LBB0_1126:
	s_add_u32 s61, s36, 0x100
	v_mov_b32_e32 v2, 0
	s_addc_u32 s62, s37, 0
	s_mov_b32 s63, -2
	s_waitcnt lgkmcnt(0)
	v_mov_b32_e32 v3, v2
	s_add_u32 s80, s24, 0x200
	s_addc_u32 s81, s25, 0
	v_mov_b32_e32 v248, s80
	v_mov_b32_e32 v249, s81
	s_add_u32 s80, s61, 0x100
	s_addc_u32 s81, s62, 0
	v_mov_b32_e32 v250, s80
	v_mov_b32_e32 v251, s81
	s_mov_b64 s[80:81], 0xff0
	v_cndmask_b32_e64 v248, v248, v250, s[80:81]
	v_cndmask_b32_e64 v249, v249, v251, s[80:81]
	v_and_b32_e32 v247, 63, v0
	v_lshrrev_b32_e32 v250, 6, v0
	v_and_b32_e32 v251, 3, v247
	v_lshl_add_u32 v251, v250, 2, v251
	v_add_u32_e32 v247, 4, v247
	v_and_b32_e32 v247, 7, v247
	v_lshl_add_u32 v247, v250, 3, v247
	s_and_b32 s80, s2, 0xe0
	s_and_b32 s81, s2, 0x18
	s_lshl_b32 s81, s81, 3
	v_add_u32_e32 v251, s80, v251
	v_add_u32_e32 v247, s81, v247
	s_mov_b64 s[80:81], 0xff0
	v_cndmask_b32_e64 v247, v251, v247, s[80:81]
	v_mul_u32_u24_e32 v250, 0x2c00, v247
	v_mov_b32_e32 v251, 0
	s_nop 0
	v_lshl_add_u64 v[248:249], v[250:251], 0, v[248:249]
	s_mov_b32 s81, 0
	s_mov_b32 s80, 0x80
	ds_read_b128 v[130:133], v190
	ds_read_b128 v[134:137], v190 offset:1024
	ds_read_b128 v[138:141], v190 offset:2048
	ds_read_b128 v[142:145], v190 offset:3072
	ds_read_b128 v[146:149], v191
	ds_read_b128 v[150:153], v191 offset:1024
	ds_read_b128 v[170:173], v191 offset:2048
	ds_read_b128 v[174:177], v191 offset:3072
	s_add_u32 s36, s24, 0x100
	s_addc_u32 s37, s25, 0
	s_cmpk_eq_i32 s63, 0x54
	s_cselect_b32 s41, s9, s37
	s_cselect_b32 s40, s8, s36
	s_cselect_b32 s39, s23, s62
	s_cselect_b32 s38, s22, s61
	s_cmp_lt_i32 s63, 79
	s_cselect_b32 s80, 0x80, 0
	s_add_i32 m0, s46, 0xc000
	ds_read_b128 v[178:181], v192
	ds_read_b128 v[182:185], v192 offset:1024
	ds_read_b128 v[194:197], v192 offset:2048
	ds_read_b128 v[198:201], v192 offset:3072
	ds_read_b128 v[202:205], v192 offset:4096
	ds_read_b128 v[206:209], v192 offset:5120
	ds_read_b128 v[210:213], v192 offset:6144
	ds_read_b128 v[214:217], v192 offset:7168
	global_load_lds_dwordx4 v162, s[24:25]
	s_add_i32 m0, s46, 0xe000
	s_nop 0
	global_load_lds_dwordx4 v164, s[24:25]
	s_waitcnt vmcnt(9)
	s_waitcnt lgkmcnt(0)
	s_barrier
	s_waitcnt lgkmcnt(0)
	v_mfma_f32_16x16x32_bf16 v[126:129], v[130:133], v[178:181], 0
	v_mfma_f32_16x16x32_bf16 v[122:125], v[138:141], v[178:181], 0
	v_mfma_f32_16x16x32_bf16 v[110:113], v[130:133], v[194:197], 0
	v_mfma_f32_16x16x32_bf16 v[106:109], v[138:141], v[194:197], 0
	v_mfma_f32_16x16x32_bf16 v[94:97], v[130:133], v[202:205], 0
	v_mfma_f32_16x16x32_bf16 v[90:93], v[138:141], v[202:205], 0
	v_mfma_f32_16x16x32_bf16 v[78:81], v[130:133], v[210:213], 0
	v_mfma_f32_16x16x32_bf16 v[74:77], v[138:141], v[210:213], 0
	v_mfma_f32_16x16x32_bf16 v[126:129], v[134:137], v[182:185], v[126:129]
	v_mfma_f32_16x16x32_bf16 v[122:125], v[142:145], v[182:185], v[122:125]
	v_mfma_f32_16x16x32_bf16 v[110:113], v[134:137], v[198:201], v[110:113]
	v_mfma_f32_16x16x32_bf16 v[106:109], v[142:145], v[198:201], v[106:109]
	v_mfma_f32_16x16x32_bf16 v[94:97], v[134:137], v[206:209], v[94:97]
	v_mfma_f32_16x16x32_bf16 v[90:93], v[142:145], v[206:209], v[90:93]
	v_mfma_f32_16x16x32_bf16 v[78:81], v[134:137], v[214:217], v[78:81]
	v_mfma_f32_16x16x32_bf16 v[74:77], v[142:145], v[214:217], v[74:77]
	v_mfma_f32_16x16x32_bf16 v[118:121], v[146:149], v[178:181], 0
	v_mfma_f32_16x16x32_bf16 v[114:117], v[170:173], v[178:181], 0
	v_mfma_f32_16x16x32_bf16 v[102:105], v[146:149], v[194:197], 0
	v_mfma_f32_16x16x32_bf16 v[98:101], v[170:173], v[194:197], 0
	v_mfma_f32_16x16x32_bf16 v[86:89], v[146:149], v[202:205], 0
	v_mfma_f32_16x16x32_bf16 v[82:85], v[170:173], v[202:205], 0
	v_mfma_f32_16x16x32_bf16 v[70:73], v[146:149], v[210:213], 0
	v_mfma_f32_16x16x32_bf16 v[66:69], v[170:173], v[210:213], 0
	v_mfma_f32_16x16x32_bf16 v[118:121], v[150:153], v[182:185], v[118:121]
	v_mfma_f32_16x16x32_bf16 v[114:117], v[174:177], v[182:185], v[114:117]
	v_mfma_f32_16x16x32_bf16 v[102:105], v[150:153], v[198:201], v[102:105]
	v_mfma_f32_16x16x32_bf16 v[98:101], v[174:177], v[198:201], v[98:101]
	v_mfma_f32_16x16x32_bf16 v[86:89], v[150:153], v[206:209], v[86:89]
	v_mfma_f32_16x16x32_bf16 v[82:85], v[174:177], v[206:209], v[82:85]
	v_mfma_f32_16x16x32_bf16 v[70:73], v[150:153], v[214:217], v[70:73]
	v_mfma_f32_16x16x32_bf16 v[66:69], v[174:177], v[214:217], v[66:69]
	s_barrier
	s_add_i32 s18, s55, s45
	s_add_u32 s76, s38, s16
	s_addc_u32 s77, s39, s17
	s_mov_b32 m0, s18
	ds_read_b128 v[178:181], v192 offset:16384
	ds_read_b128 v[182:185], v192 offset:17408
	ds_read_b128 v[194:197], v192 offset:18432
	ds_read_b128 v[198:201], v192 offset:19456
	ds_read_b128 v[202:205], v192 offset:20480
	ds_read_b128 v[206:209], v192 offset:21504
	ds_read_b128 v[210:213], v192 offset:22528
	ds_read_b128 v[214:217], v192 offset:23552
	global_load_lds_dwordx4 v156, s[38:39]
	s_add_i32 m0, s18, 0x2000
	s_add_u32 s24, s38, 0x160000
	s_addc_u32 s25, s39, 0
	s_add_i32 s18, s56, s45
	global_load_lds_dwordx4 v160, s[38:39]
	s_mov_b32 m0, s18
	s_nop 0
	global_load_lds_dwordx4 v156, s[24:25]
	s_add_i32 m0, s18, 0x2000
	s_nop 0
	global_load_lds_dwordx4 v160, s[24:25]
	s_add_u32 s78, s40, s16
	s_addc_u32 s79, s41, s17
	s_mov_b32 m0, s46
	s_nop 0
	global_load_lds_dwordx4 v154, s[40:41]
	s_mov_b32 m0, s47
	s_nop 0
	global_load_lds_dwordx4 v158, s[40:41]
	global_load_dword v247, v[248:249], off
	v_lshl_add_u64 v[248:249], v[248:249], 0, s[80:81]
	s_waitcnt vmcnt(9)
	s_waitcnt lgkmcnt(0)
	s_barrier
; #define PG8_STAGE(bufoff, gbase, voff) do { _Pragma("unroll") for (int _i = 0; _i < 2; ++_i) \
;         __builtin_amdgcn_global_load_lds((const unsigned*)((const char*)(gbase) + (voff)[_i]), (PG8_LAS unsigned*)(lds + (bufoff) + ldsw + _i * 8192), 16, 0, 0); } while (0)
; #define PG8_LDA(dst, b, h) do { _Pragma("unroll") for (int m = 0; m < 4; ++m) _Pragma("unroll") for (int k = 0; k < 2; ++k) dst[m][k] = *(const PG8_LAS bf16x8*)(lds + PG8_SA(b, h) + aoff + m * 2048 + k * 1024); } while (0)
; #define PG8_LDB(dst, b, h) do { _Pragma("unroll") for (int n = 0; n < 2; ++n) _Pragma("unroll") for (int k = 0; k < 2; ++k) dst[n][k] = *(const PG8_LAS bf16x8*)(lds + PG8_SB(b, h) + boff + n * 2048 + k * 1024); } while (0)
; #define PG8_MMA(ai, bj, At, Bt) do { __builtin_amdgcn_s_setprio(1); _Pragma("unroll") for (int m = 0; m < 4; ++m) _Pragma("unroll") for (int n = 0; n < 2; ++n) _Pragma("unroll") for (int k = 0; k < 2; ++k) \
;         acc[ai][bj][m][n] = __builtin_amdgcn_mfma_f32_16x16x32_bf16(Bt[n][k], At[m][k], acc[ai][bj][m][n], 0, 0, 0); __builtin_amdgcn_s_setprio(0); } while (0)
; #define PG8_WAIT_V(n) asm volatile("s_waitcnt vmcnt(" #n ")" ::: "memory")
; #define PG8_WAIT_L(n) asm volatile("s_waitcnt lgkmcnt(" #n ")" ::: "memory")
; #define PG8_BAR __builtin_amdgcn_s_barrier()
; template <class Epi, class Sched, bool ALIGN_EPI = false, bool SP2 = false>
; __device__ __forceinline__ void gemm_phase(PG8_LAS unsigned char* lds, const Gemm g, const Sched& S, const Epi& E) {
;     ...
;             PG8_LDB(B0, 0, 0); PG8_LDB(B1, 0, 1); PG8_SCHED; PG8_LDA(At, 0, 0); PG8_STAGE(PG8_SA(1, 1), a1 + hA, voffA);
;             PG8_WAIT_V(8); PG8_WAIT_L(0); PG8_BAR; PG8_MMA(0, 0, At, B0); PG8_MMA(0, 1, At, B1); PG8_BAR; PG8_SCHED;
;             PG8_LDA(At, 0, 1); PG8_STAGE(PG8_SB(0, 0), b2, voffB); PG8_STAGE(PG8_SB(0, 1), b2 + hB, voffB); PG8_STAGE(PG8_SA(0, 0), a2, voffA);
;             PG8_WAIT_V(8); PG8_WAIT_L(0); PG8_BAR; PG8_MMA(1, 0, At, B0); PG8_MMA(1, 1, At, B1); PG8_BAR; PG8_SCHED;
;             PG8_LDB(B0, 1, 0); PG8_LDB(B1, 1, 1); PG8_SCHED; PG8_LDA(At, 1, 0); PG8_STAGE(PG8_SA(0, 1), a2 + hA, voffA);
;             PG8_WAIT_V(8); PG8_WAIT_L(0); PG8_BAR; PG8_MMA(0, 0, At, B0); PG8_MMA(0, 1, At, B1); PG8_BAR; PG8_SCHED;
;             PG8_LDA(At, 1, 1); PG8_STAGE(PG8_SB(1, 0), b3, voffB); PG8_STAGE(PG8_SB(1, 1), b3 + hB, voffB); PG8_STAGE(PG8_SA(1, 0), a3, voffA);
	s_waitcnt lgkmcnt(0)
	v_mfma_f32_16x16x32_bf16 v[62:65], v[130:133], v[178:181], 0
	v_mfma_f32_16x16x32_bf16 v[58:61], v[138:141], v[178:181], 0
	v_mfma_f32_16x16x32_bf16 v[46:49], v[130:133], v[194:197], 0
	v_mfma_f32_16x16x32_bf16 v[42:45], v[138:141], v[194:197], 0
	v_mfma_f32_16x16x32_bf16 v[30:33], v[130:133], v[202:205], 0
	v_mfma_f32_16x16x32_bf16 v[26:29], v[138:141], v[202:205], 0
	v_mfma_f32_16x16x32_bf16 v[14:17], v[130:133], v[210:213], 0
	v_mfma_f32_16x16x32_bf16 v[10:13], v[138:141], v[210:213], 0
	v_mfma_f32_16x16x32_bf16 v[62:65], v[134:137], v[182:185], v[62:65]
	v_mfma_f32_16x16x32_bf16 v[58:61], v[142:145], v[182:185], v[58:61]
	v_mfma_f32_16x16x32_bf16 v[46:49], v[134:137], v[198:201], v[46:49]
	v_mfma_f32_16x16x32_bf16 v[42:45], v[142:145], v[198:201], v[42:45]
	v_mfma_f32_16x16x32_bf16 v[30:33], v[134:137], v[206:209], v[30:33]
	v_mfma_f32_16x16x32_bf16 v[26:29], v[142:145], v[206:209], v[26:29]
	v_mfma_f32_16x16x32_bf16 v[14:17], v[134:137], v[214:217], v[14:17]
	v_mfma_f32_16x16x32_bf16 v[10:13], v[142:145], v[214:217], v[10:13]
	v_mfma_f32_16x16x32_bf16 v[54:57], v[146:149], v[178:181], 0
	v_mfma_f32_16x16x32_bf16 v[50:53], v[170:173], v[178:181], 0
	v_mfma_f32_16x16x32_bf16 v[38:41], v[146:149], v[194:197], 0
	v_mfma_f32_16x16x32_bf16 v[34:37], v[170:173], v[194:197], 0
	v_mfma_f32_16x16x32_bf16 v[22:25], v[146:149], v[202:205], 0
	v_mfma_f32_16x16x32_bf16 v[18:21], v[170:173], v[202:205], 0
	v_mfma_f32_16x16x32_bf16 v[6:9], v[146:149], v[210:213], 0
	v_mfma_f32_16x16x32_bf16 v[2:5], v[170:173], v[210:213], 0
	v_mfma_f32_16x16x32_bf16 v[54:57], v[150:153], v[182:185], v[54:57]
	v_mfma_f32_16x16x32_bf16 v[50:53], v[174:177], v[182:185], v[50:53]
	v_mfma_f32_16x16x32_bf16 v[38:41], v[150:153], v[198:201], v[38:41]
	v_mfma_f32_16x16x32_bf16 v[34:37], v[174:177], v[198:201], v[34:37]
	v_mfma_f32_16x16x32_bf16 v[22:25], v[150:153], v[206:209], v[22:25]
	v_mfma_f32_16x16x32_bf16 v[18:21], v[174:177], v[206:209], v[18:21]
	v_mfma_f32_16x16x32_bf16 v[6:9], v[150:153], v[214:217], v[6:9]
	v_mfma_f32_16x16x32_bf16 v[2:5], v[174:177], v[214:217], v[2:5]
	s_barrier
	s_add_i32 s18, 0, 0x18000
	s_add_i32 s19, 0, 0x1c000
	v_add_u32_e32 v142, s18, v188
	v_add_u32_e32 v174, s19, v188
	ds_read_b128 v[130:133], v142
	ds_read_b128 v[134:137], v142 offset:1024
	ds_read_b128 v[138:141], v142 offset:2048
	ds_read_b128 v[142:145], v142 offset:3072
	ds_read_b128 v[146:149], v174
	ds_read_b128 v[150:153], v174 offset:1024
	ds_read_b128 v[170:173], v174 offset:2048
	ds_read_b128 v[174:177], v174 offset:3072
	s_add_u32 s24, s40, 0x160000
	s_addc_u32 s25, s41, 0
	s_mov_b32 m0, s48
	ds_read_b128 v[178:181], v192 offset:32768
	ds_read_b128 v[182:185], v192 offset:33792
	ds_read_b128 v[194:197], v192 offset:34816
	ds_read_b128 v[198:201], v192 offset:35840
	ds_read_b128 v[202:205], v192 offset:36864
	ds_read_b128 v[206:209], v192 offset:37888
	ds_read_b128 v[210:213], v192 offset:38912
	ds_read_b128 v[214:217], v192 offset:39936
	global_load_lds_dwordx4 v154, s[24:25]
	s_mov_b32 m0, s49
	s_nop 0
	global_load_lds_dwordx4 v158, s[24:25]
	s_waitcnt vmcnt(9)
	s_waitcnt lgkmcnt(0)
	s_barrier
	s_waitcnt lgkmcnt(0)
	v_mfma_f32_16x16x32_bf16 v[126:129], v[130:133], v[178:181], v[126:129]
	v_mfma_f32_16x16x32_bf16 v[122:125], v[138:141], v[178:181], v[122:125]
	v_mfma_f32_16x16x32_bf16 v[110:113], v[130:133], v[194:197], v[110:113]
	v_mfma_f32_16x16x32_bf16 v[106:109], v[138:141], v[194:197], v[106:109]
	v_mfma_f32_16x16x32_bf16 v[94:97], v[130:133], v[202:205], v[94:97]
	v_mfma_f32_16x16x32_bf16 v[90:93], v[138:141], v[202:205], v[90:93]
	v_mfma_f32_16x16x32_bf16 v[78:81], v[130:133], v[210:213], v[78:81]
	v_mfma_f32_16x16x32_bf16 v[74:77], v[138:141], v[210:213], v[74:77]
	v_mfma_f32_16x16x32_bf16 v[126:129], v[134:137], v[182:185], v[126:129]
	v_mfma_f32_16x16x32_bf16 v[122:125], v[142:145], v[182:185], v[122:125]
	v_mfma_f32_16x16x32_bf16 v[110:113], v[134:137], v[198:201], v[110:113]
	v_mfma_f32_16x16x32_bf16 v[106:109], v[142:145], v[198:201], v[106:109]
	v_mfma_f32_16x16x32_bf16 v[94:97], v[134:137], v[206:209], v[94:97]
	v_mfma_f32_16x16x32_bf16 v[90:93], v[142:145], v[206:209], v[90:93]
	v_mfma_f32_16x16x32_bf16 v[78:81], v[134:137], v[214:217], v[78:81]
	v_mfma_f32_16x16x32_bf16 v[74:77], v[142:145], v[214:217], v[74:77]
	v_mfma_f32_16x16x32_bf16 v[118:121], v[146:149], v[178:181], v[118:121]
	v_mfma_f32_16x16x32_bf16 v[114:117], v[170:173], v[178:181], v[114:117]
	v_mfma_f32_16x16x32_bf16 v[102:105], v[146:149], v[194:197], v[102:105]
	v_mfma_f32_16x16x32_bf16 v[98:101], v[170:173], v[194:197], v[98:101]
	v_mfma_f32_16x16x32_bf16 v[86:89], v[146:149], v[202:205], v[86:89]
	v_mfma_f32_16x16x32_bf16 v[82:85], v[170:173], v[202:205], v[82:85]
	v_mfma_f32_16x16x32_bf16 v[70:73], v[146:149], v[210:213], v[70:73]
	v_mfma_f32_16x16x32_bf16 v[66:69], v[170:173], v[210:213], v[66:69]
	v_mfma_f32_16x16x32_bf16 v[118:121], v[150:153], v[182:185], v[118:121]
	v_mfma_f32_16x16x32_bf16 v[114:117], v[174:177], v[182:185], v[114:117]
	v_mfma_f32_16x16x32_bf16 v[102:105], v[150:153], v[198:201], v[102:105]
	v_mfma_f32_16x16x32_bf16 v[98:101], v[174:177], v[198:201], v[98:101]
	v_mfma_f32_16x16x32_bf16 v[86:89], v[150:153], v[206:209], v[86:89]
	v_mfma_f32_16x16x32_bf16 v[82:85], v[174:177], v[206:209], v[82:85]
	v_mfma_f32_16x16x32_bf16 v[70:73], v[150:153], v[214:217], v[70:73]
	v_mfma_f32_16x16x32_bf16 v[66:69], v[174:177], v[214:217], v[66:69]
	s_barrier
; #define PG8_STAGE(bufoff, gbase, voff) do { _Pragma("unroll") for (int _i = 0; _i < 2; ++_i) \
;         __builtin_amdgcn_global_load_lds((const unsigned*)((const char*)(gbase) + (voff)[_i]), (PG8_LAS unsigned*)(lds + (bufoff) + ldsw + _i * 8192), 16, 0, 0); } while (0)
; #define PG8_LDA(dst, b, h) do { _Pragma("unroll") for (int m = 0; m < 4; ++m) _Pragma("unroll") for (int k = 0; k < 2; ++k) dst[m][k] = *(const PG8_LAS bf16x8*)(lds + PG8_SA(b, h) + aoff + m * 2048 + k * 1024); } while (0)
; #define PG8_LDB(dst, b, h) do { _Pragma("unroll") for (int n = 0; n < 2; ++n) _Pragma("unroll") for (int k = 0; k < 2; ++k) dst[n][k] = *(const PG8_LAS bf16x8*)(lds + PG8_SB(b, h) + boff + n * 2048 + k * 1024); } while (0)
; template <class Epi, class Sched, bool ALIGN_EPI = false, bool SP2 = false>
; __device__ __forceinline__ void gemm_phase(PG8_LAS unsigned char* lds, const Gemm g, const Sched& S, const Epi& E) {
;     ...
;         for (int t = 0; t < nt; t += 2) {
;             const bool last = (t == nt - 2);
;             const char* a1 = cA + (size_t)(t + 1) * kstep;
;             const char* a2 = last ? nA : cA + (size_t)(t + 2) * kstep; const char* b2 = last ? nB : cB + (size_t)(t + 2) * kstep;
;             const char* a3 = a2 + kstep; const char* b3 = b2 + kstep;
;             if (last && has_next) S.a_ready(nxt);
;             if constexpr (SP2) {
;             PG8_LDB(B0, 0, 0); PG8_LDB(B1, 0, 1); PG8_SCHED; PG8_LDA(At, 0, 0); PG8_STAGE(PG8_SA(1, 1), a1 + hA, voffA);
;             PG8_WAIT_V(8); PG8_WAIT_L(0); PG8_BAR; PG8_MMA(0, 0, At, B0); PG8_MMA(0, 1, At, B1); PG8_BAR; PG8_SCHED;
;             PG8_LDA(At, 0, 1); PG8_STAGE(PG8_SB(0, 0), b2, voffB); PG8_STAGE(PG8_SB(0, 1), b2 + hB, voffB); PG8_STAGE(PG8_SA(0, 0), a2, voffA);
;             PG8_WAIT_V(8); PG8_WAIT_L(0); PG8_BAR; PG8_MMA(1, 0, At, B0); PG8_MMA(1, 1, At, B1); PG8_BAR; PG8_SCHED;
;             PG8_LDB(B0, 1, 0); PG8_LDB(B1, 1, 1); PG8_SCHED; PG8_LDA(At, 1, 0); PG8_STAGE(PG8_SA(0, 1), a2 + hA, voffA);
;             PG8_WAIT_V(8); PG8_WAIT_L(0); PG8_BAR; PG8_MMA(0, 0, At, B0); PG8_MMA(0, 1, At, B1); PG8_BAR; PG8_SCHED;
;             PG8_LDA(At, 1, 1); PG8_STAGE(PG8_SB(1, 0), b3, voffB); PG8_STAGE(PG8_SB(1, 1), b3 + hB, voffB); PG8_STAGE(PG8_SA(1, 0), a3, voffA);
;             PG8_WAIT_V(8); PG8_WAIT_L(0); PG8_BAR; PG8_MMA(1, 0, At, B0); PG8_MMA(1, 1, At, B1); PG8_BAR; PG8_SCHED;
	s_add_i32 s18, s18, s45
	s_mov_b32 m0, s18
	ds_read_b128 v[178:181], v192 offset:49152
	ds_read_b128 v[182:185], v192 offset:50176
	ds_read_b128 v[194:197], v192 offset:51200
	ds_read_b128 v[198:201], v192 offset:52224
	ds_read_b128 v[202:205], v192 offset:53248
	ds_read_b128 v[206:209], v192 offset:54272
	ds_read_b128 v[210:213], v192 offset:55296
	ds_read_b128 v[214:217], v192 offset:56320
	global_load_lds_dwordx4 v156, s[76:77]
	s_add_i32 m0, s18, 0x2000
	s_add_u32 s24, s38, 0x160080
	s_addc_u32 s25, s39, 0
	s_add_i32 s18, s19, s45
	global_load_lds_dwordx4 v160, s[76:77]
	s_mov_b32 m0, s18
	s_nop 0
	global_load_lds_dwordx4 v156, s[24:25]
	s_add_i32 m0, s18, 0x2000
	s_nop 0
	global_load_lds_dwordx4 v160, s[24:25]
	s_mov_b32 m0, s52
	s_nop 0
	global_load_lds_dwordx4 v154, s[78:79]
	s_mov_b32 m0, s53
	s_nop 0
	global_load_lds_dwordx4 v158, s[78:79]
	global_load_dword v247, v[248:249], off
	v_lshl_add_u64 v[248:249], v[248:249], 0, s[80:81]
	s_waitcnt vmcnt(10)
	s_waitcnt lgkmcnt(0)
	s_barrier
	s_waitcnt lgkmcnt(0)
	v_mfma_f32_16x16x32_bf16 v[62:65], v[130:133], v[178:181], v[62:65]
	v_mfma_f32_16x16x32_bf16 v[58:61], v[138:141], v[178:181], v[58:61]
	v_mfma_f32_16x16x32_bf16 v[46:49], v[130:133], v[194:197], v[46:49]
	v_mfma_f32_16x16x32_bf16 v[42:45], v[138:141], v[194:197], v[42:45]
	v_mfma_f32_16x16x32_bf16 v[30:33], v[130:133], v[202:205], v[30:33]
	v_mfma_f32_16x16x32_bf16 v[26:29], v[138:141], v[202:205], v[26:29]
	v_mfma_f32_16x16x32_bf16 v[14:17], v[130:133], v[210:213], v[14:17]
	v_mfma_f32_16x16x32_bf16 v[10:13], v[138:141], v[210:213], v[10:13]
	v_mfma_f32_16x16x32_bf16 v[62:65], v[134:137], v[182:185], v[62:65]
	v_mfma_f32_16x16x32_bf16 v[58:61], v[142:145], v[182:185], v[58:61]
	v_mfma_f32_16x16x32_bf16 v[46:49], v[134:137], v[198:201], v[46:49]
	v_mfma_f32_16x16x32_bf16 v[42:45], v[142:145], v[198:201], v[42:45]
	v_mfma_f32_16x16x32_bf16 v[30:33], v[134:137], v[206:209], v[30:33]
	v_mfma_f32_16x16x32_bf16 v[26:29], v[142:145], v[206:209], v[26:29]
	v_mfma_f32_16x16x32_bf16 v[14:17], v[134:137], v[214:217], v[14:17]
	v_mfma_f32_16x16x32_bf16 v[10:13], v[142:145], v[214:217], v[10:13]
	v_mfma_f32_16x16x32_bf16 v[54:57], v[146:149], v[178:181], v[54:57]
	v_mfma_f32_16x16x32_bf16 v[50:53], v[170:173], v[178:181], v[50:53]
	v_mfma_f32_16x16x32_bf16 v[38:41], v[146:149], v[194:197], v[38:41]
	v_mfma_f32_16x16x32_bf16 v[34:37], v[170:173], v[194:197], v[34:37]
	v_mfma_f32_16x16x32_bf16 v[22:25], v[146:149], v[202:205], v[22:25]
	v_mfma_f32_16x16x32_bf16 v[18:21], v[170:173], v[202:205], v[18:21]
	v_mfma_f32_16x16x32_bf16 v[6:9], v[146:149], v[210:213], v[6:9]
	v_mfma_f32_16x16x32_bf16 v[2:5], v[170:173], v[210:213], v[2:5]
	v_mfma_f32_16x16x32_bf16 v[54:57], v[150:153], v[182:185], v[54:57]
	v_mfma_f32_16x16x32_bf16 v[50:53], v[174:177], v[182:185], v[50:53]
	v_mfma_f32_16x16x32_bf16 v[38:41], v[150:153], v[198:201], v[38:41]
	v_mfma_f32_16x16x32_bf16 v[34:37], v[174:177], v[198:201], v[34:37]
	v_mfma_f32_16x16x32_bf16 v[22:25], v[150:153], v[206:209], v[22:25]
	v_mfma_f32_16x16x32_bf16 v[18:21], v[174:177], v[206:209], v[18:21]
	v_mfma_f32_16x16x32_bf16 v[6:9], v[150:153], v[214:217], v[6:9]
	v_mfma_f32_16x16x32_bf16 v[2:5], v[174:177], v[214:217], v[2:5]
	s_barrier
	s_add_i32 s63, s63, 2
	s_add_u32 s61, s61, 0x100
	s_addc_u32 s62, s62, 0
	s_cmpk_gt_u32 s63, 0x55
	s_mov_b64 s[24:25], s[36:37]
.LBB0_1127:
	ds_read_b128 v[130:133], v190
	ds_read_b128 v[134:137], v190 offset:1024
	ds_read_b128 v[138:141], v190 offset:2048
	ds_read_b128 v[142:145], v190 offset:3072
	ds_read_b128 v[146:149], v191
	ds_read_b128 v[150:153], v191 offset:1024
	ds_read_b128 v[170:173], v191 offset:2048
	ds_read_b128 v[174:177], v191 offset:3072
	s_add_u32 s36, s24, 0x100
	s_addc_u32 s37, s25, 0
	s_cmpk_eq_i32 s63, 0x54
	s_cselect_b32 s41, s9, s37
	s_cselect_b32 s40, s8, s36
	s_cselect_b32 s39, s23, s62
	s_cselect_b32 s38, s22, s61
	s_cmp_lt_i32 s63, 79
	s_cselect_b32 s80, 0x80, 0
	s_add_i32 m0, s46, 0xc000
	ds_read_b128 v[178:181], v192
	ds_read_b128 v[182:185], v192 offset:1024
	ds_read_b128 v[194:197], v192 offset:2048
	ds_read_b128 v[198:201], v192 offset:3072
	ds_read_b128 v[202:205], v192 offset:4096
	ds_read_b128 v[206:209], v192 offset:5120
	ds_read_b128 v[210:213], v192 offset:6144
	ds_read_b128 v[214:217], v192 offset:7168
	global_load_lds_dwordx4 v162, s[24:25]
	s_add_i32 m0, s46, 0xe000
	s_nop 0
	global_load_lds_dwordx4 v164, s[24:25]
	s_waitcnt vmcnt(9)
	s_waitcnt lgkmcnt(0)
	s_barrier
	s_waitcnt lgkmcnt(0)
	v_mfma_f32_16x16x32_bf16 v[126:129], v[130:133], v[178:181], v[126:129]
	v_mfma_f32_16x16x32_bf16 v[122:125], v[138:141], v[178:181], v[122:125]
	v_mfma_f32_16x16x32_bf16 v[110:113], v[130:133], v[194:197], v[110:113]
	v_mfma_f32_16x16x32_bf16 v[106:109], v[138:141], v[194:197], v[106:109]
	v_mfma_f32_16x16x32_bf16 v[94:97], v[130:133], v[202:205], v[94:97]
	v_mfma_f32_16x16x32_bf16 v[90:93], v[138:141], v[202:205], v[90:93]
	v_mfma_f32_16x16x32_bf16 v[78:81], v[130:133], v[210:213], v[78:81]
	v_mfma_f32_16x16x32_bf16 v[74:77], v[138:141], v[210:213], v[74:77]
	v_mfma_f32_16x16x32_bf16 v[126:129], v[134:137], v[182:185], v[126:129]
	v_mfma_f32_16x16x32_bf16 v[122:125], v[142:145], v[182:185], v[122:125]
	v_mfma_f32_16x16x32_bf16 v[110:113], v[134:137], v[198:201], v[110:113]
	v_mfma_f32_16x16x32_bf16 v[106:109], v[142:145], v[198:201], v[106:109]
	v_mfma_f32_16x16x32_bf16 v[94:97], v[134:137], v[206:209], v[94:97]
	v_mfma_f32_16x16x32_bf16 v[90:93], v[142:145], v[206:209], v[90:93]
	v_mfma_f32_16x16x32_bf16 v[78:81], v[134:137], v[214:217], v[78:81]
	v_mfma_f32_16x16x32_bf16 v[74:77], v[142:145], v[214:217], v[74:77]
	v_mfma_f32_16x16x32_bf16 v[118:121], v[146:149], v[178:181], v[118:121]
	v_mfma_f32_16x16x32_bf16 v[114:117], v[170:173], v[178:181], v[114:117]
	v_mfma_f32_16x16x32_bf16 v[102:105], v[146:149], v[194:197], v[102:105]
	v_mfma_f32_16x16x32_bf16 v[98:101], v[170:173], v[194:197], v[98:101]
	v_mfma_f32_16x16x32_bf16 v[86:89], v[146:149], v[202:205], v[86:89]
	v_mfma_f32_16x16x32_bf16 v[82:85], v[170:173], v[202:205], v[82:85]
	v_mfma_f32_16x16x32_bf16 v[70:73], v[146:149], v[210:213], v[70:73]
	v_mfma_f32_16x16x32_bf16 v[66:69], v[170:173], v[210:213], v[66:69]
	v_mfma_f32_16x16x32_bf16 v[118:121], v[150:153], v[182:185], v[118:121]
	v_mfma_f32_16x16x32_bf16 v[114:117], v[174:177], v[182:185], v[114:117]
	v_mfma_f32_16x16x32_bf16 v[102:105], v[150:153], v[198:201], v[102:105]
	v_mfma_f32_16x16x32_bf16 v[98:101], v[174:177], v[198:201], v[98:101]
	v_mfma_f32_16x16x32_bf16 v[86:89], v[150:153], v[206:209], v[86:89]
	v_mfma_f32_16x16x32_bf16 v[82:85], v[174:177], v[206:209], v[82:85]
	v_mfma_f32_16x16x32_bf16 v[70:73], v[150:153], v[214:217], v[70:73]
	v_mfma_f32_16x16x32_bf16 v[66:69], v[174:177], v[214:217], v[66:69]
	s_barrier
; #define PG8_STAGE(bufoff, gbase, voff) do { _Pragma("unroll") for (int _i = 0; _i < 2; ++_i) \
;         __builtin_amdgcn_global_load_lds((const unsigned*)((const char*)(gbase) + (voff)[_i]), (PG8_LAS unsigned*)(lds + (bufoff) + ldsw + _i * 8192), 16, 0, 0); } while (0)
; #define PG8_LDA(dst, b, h) do { _Pragma("unroll") for (int m = 0; m < 4; ++m) _Pragma("unroll") for (int k = 0; k < 2; ++k) dst[m][k] = *(const PG8_LAS bf16x8*)(lds + PG8_SA(b, h) + aoff + m * 2048 + k * 1024); } while (0)
; #define PG8_LDB(dst, b, h) do { _Pragma("unroll") for (int n = 0; n < 2; ++n) _Pragma("unroll") for (int k = 0; k < 2; ++k) dst[n][k] = *(const PG8_LAS bf16x8*)(lds + PG8_SB(b, h) + boff + n * 2048 + k * 1024); } while (0)
; #define PG8_MMA(ai, bj, At, Bt) do { __builtin_amdgcn_s_setprio(1); _Pragma("unroll") for (int m = 0; m < 4; ++m) _Pragma("unroll") for (int n = 0; n < 2; ++n) _Pragma("unroll") for (int k = 0; k < 2; ++k) \
;         acc[ai][bj][m][n] = __builtin_amdgcn_mfma_f32_16x16x32_bf16(Bt[n][k], At[m][k], acc[ai][bj][m][n], 0, 0, 0); __builtin_amdgcn_s_setprio(0); } while (0)
; #define PG8_WAIT_V(n) asm volatile("s_waitcnt vmcnt(" #n ")" ::: "memory")
; #define PG8_WAIT_L(n) asm volatile("s_waitcnt lgkmcnt(" #n ")" ::: "memory")
; #define PG8_BAR __builtin_amdgcn_s_barrier()
; template <class Epi, class Sched, bool ALIGN_EPI = false, bool SP2 = false>
; __device__ __forceinline__ void gemm_phase(PG8_LAS unsigned char* lds, const Gemm g, const Sched& S, const Epi& E) {
;     ...
;             PG8_LDB(B0, 0, 0); PG8_LDB(B1, 0, 1); PG8_SCHED; PG8_LDA(At, 0, 0); PG8_STAGE(PG8_SA(1, 1), a1 + hA, voffA);
;             PG8_WAIT_V(8); PG8_WAIT_L(0); PG8_BAR; PG8_MMA(0, 0, At, B0); PG8_MMA(0, 1, At, B1); PG8_BAR; PG8_SCHED;
;             PG8_LDA(At, 0, 1); PG8_STAGE(PG8_SB(0, 0), b2, voffB); PG8_STAGE(PG8_SB(0, 1), b2 + hB, voffB); PG8_STAGE(PG8_SA(0, 0), a2, voffA);
;             PG8_WAIT_V(8); PG8_WAIT_L(0); PG8_BAR; PG8_MMA(1, 0, At, B0); PG8_MMA(1, 1, At, B1); PG8_BAR; PG8_SCHED;
;             PG8_LDB(B0, 1, 0); PG8_LDB(B1, 1, 1); PG8_SCHED; PG8_LDA(At, 1, 0); PG8_STAGE(PG8_SA(0, 1), a2 + hA, voffA);
;             PG8_WAIT_V(8); PG8_WAIT_L(0); PG8_BAR; PG8_MMA(0, 0, At, B0); PG8_MMA(0, 1, At, B1); PG8_BAR; PG8_SCHED;
;             PG8_LDA(At, 1, 1); PG8_STAGE(PG8_SB(1, 0), b3, voffB); PG8_STAGE(PG8_SB(1, 1), b3 + hB, voffB); PG8_STAGE(PG8_SA(1, 0), a3, voffA);
	s_add_i32 s18, s55, s45
	s_add_u32 s76, s38, s16
	s_addc_u32 s77, s39, s17
	s_mov_b32 m0, s18
	ds_read_b128 v[178:181], v192 offset:16384
	ds_read_b128 v[182:185], v192 offset:17408
	ds_read_b128 v[194:197], v192 offset:18432
	ds_read_b128 v[198:201], v192 offset:19456
	ds_read_b128 v[202:205], v192 offset:20480
	ds_read_b128 v[206:209], v192 offset:21504
	ds_read_b128 v[210:213], v192 offset:22528
	ds_read_b128 v[214:217], v192 offset:23552
	global_load_lds_dwordx4 v156, s[38:39]
	s_add_i32 m0, s18, 0x2000
	s_add_u32 s24, s38, 0x160000
	s_addc_u32 s25, s39, 0
	s_add_i32 s18, s56, s45
	global_load_lds_dwordx4 v160, s[38:39]
	s_mov_b32 m0, s18
	s_nop 0
	global_load_lds_dwordx4 v156, s[24:25]
	s_add_i32 m0, s18, 0x2000
	s_nop 0
	global_load_lds_dwordx4 v160, s[24:25]
	s_add_u32 s78, s40, s16
	s_addc_u32 s79, s41, s17
	s_mov_b32 m0, s46
	s_nop 0
	global_load_lds_dwordx4 v154, s[40:41]
	s_mov_b32 m0, s47
	s_nop 0
	global_load_lds_dwordx4 v158, s[40:41]
	global_load_dword v247, v[248:249], off
	v_lshl_add_u64 v[248:249], v[248:249], 0, s[80:81]
	s_waitcnt vmcnt(10)
	s_waitcnt lgkmcnt(0)
	s_barrier
	s_waitcnt lgkmcnt(0)
	v_mfma_f32_16x16x32_bf16 v[62:65], v[130:133], v[178:181], v[62:65]
	v_mfma_f32_16x16x32_bf16 v[58:61], v[138:141], v[178:181], v[58:61]
	v_mfma_f32_16x16x32_bf16 v[46:49], v[130:133], v[194:197], v[46:49]
	v_mfma_f32_16x16x32_bf16 v[42:45], v[138:141], v[194:197], v[42:45]
	v_mfma_f32_16x16x32_bf16 v[30:33], v[130:133], v[202:205], v[30:33]
	v_mfma_f32_16x16x32_bf16 v[26:29], v[138:141], v[202:205], v[26:29]
	v_mfma_f32_16x16x32_bf16 v[14:17], v[130:133], v[210:213], v[14:17]
	v_mfma_f32_16x16x32_bf16 v[10:13], v[138:141], v[210:213], v[10:13]
	v_mfma_f32_16x16x32_bf16 v[62:65], v[134:137], v[182:185], v[62:65]
	v_mfma_f32_16x16x32_bf16 v[58:61], v[142:145], v[182:185], v[58:61]
	v_mfma_f32_16x16x32_bf16 v[46:49], v[134:137], v[198:201], v[46:49]
	v_mfma_f32_16x16x32_bf16 v[42:45], v[142:145], v[198:201], v[42:45]
	v_mfma_f32_16x16x32_bf16 v[30:33], v[134:137], v[206:209], v[30:33]
	v_mfma_f32_16x16x32_bf16 v[26:29], v[142:145], v[206:209], v[26:29]
	v_mfma_f32_16x16x32_bf16 v[14:17], v[134:137], v[214:217], v[14:17]
	v_mfma_f32_16x16x32_bf16 v[10:13], v[142:145], v[214:217], v[10:13]
	v_mfma_f32_16x16x32_bf16 v[54:57], v[146:149], v[178:181], v[54:57]
	v_mfma_f32_16x16x32_bf16 v[50:53], v[170:173], v[178:181], v[50:53]
	v_mfma_f32_16x16x32_bf16 v[38:41], v[146:149], v[194:197], v[38:41]
	v_mfma_f32_16x16x32_bf16 v[34:37], v[170:173], v[194:197], v[34:37]
	v_mfma_f32_16x16x32_bf16 v[22:25], v[146:149], v[202:205], v[22:25]
	v_mfma_f32_16x16x32_bf16 v[18:21], v[170:173], v[202:205], v[18:21]
	v_mfma_f32_16x16x32_bf16 v[6:9], v[146:149], v[210:213], v[6:9]
	v_mfma_f32_16x16x32_bf16 v[2:5], v[170:173], v[210:213], v[2:5]
	v_mfma_f32_16x16x32_bf16 v[54:57], v[150:153], v[182:185], v[54:57]
	v_mfma_f32_16x16x32_bf16 v[50:53], v[174:177], v[182:185], v[50:53]
	v_mfma_f32_16x16x32_bf16 v[38:41], v[150:153], v[198:201], v[38:41]
	v_mfma_f32_16x16x32_bf16 v[34:37], v[174:177], v[198:201], v[34:37]
	v_mfma_f32_16x16x32_bf16 v[22:25], v[150:153], v[206:209], v[22:25]
	v_mfma_f32_16x16x32_bf16 v[18:21], v[174:177], v[206:209], v[18:21]
	v_mfma_f32_16x16x32_bf16 v[6:9], v[150:153], v[214:217], v[6:9]
	v_mfma_f32_16x16x32_bf16 v[2:5], v[174:177], v[214:217], v[2:5]
	s_barrier
	s_add_i32 s18, 0, 0x18000
	s_add_i32 s19, 0, 0x1c000
	v_add_u32_e32 v142, s18, v188
	v_add_u32_e32 v174, s19, v188
	ds_read_b128 v[130:133], v142
	ds_read_b128 v[134:137], v142 offset:1024
	ds_read_b128 v[138:141], v142 offset:2048
	ds_read_b128 v[142:145], v142 offset:3072
	ds_read_b128 v[146:149], v174
	ds_read_b128 v[150:153], v174 offset:1024
	ds_read_b128 v[170:173], v174 offset:2048
	ds_read_b128 v[174:177], v174 offset:3072
	s_add_u32 s24, s40, 0x160000
	s_addc_u32 s25, s41, 0
	s_mov_b32 m0, s48
	ds_read_b128 v[178:181], v192 offset:32768
	ds_read_b128 v[182:185], v192 offset:33792
	ds_read_b128 v[194:197], v192 offset:34816
	ds_read_b128 v[198:201], v192 offset:35840
	ds_read_b128 v[202:205], v192 offset:36864
	ds_read_b128 v[206:209], v192 offset:37888
	ds_read_b128 v[210:213], v192 offset:38912
	ds_read_b128 v[214:217], v192 offset:39936
	global_load_lds_dwordx4 v154, s[24:25]
	s_mov_b32 m0, s49
	s_nop 0
	global_load_lds_dwordx4 v158, s[24:25]
	s_waitcnt vmcnt(9)
	s_waitcnt lgkmcnt(0)
	s_barrier
; #define PG8_STAGE(bufoff, gbase, voff) do { _Pragma("unroll") for (int _i = 0; _i < 2; ++_i) \
;         __builtin_amdgcn_global_load_lds((const unsigned*)((const char*)(gbase) + (voff)[_i]), (PG8_LAS unsigned*)(lds + (bufoff) + ldsw + _i * 8192), 16, 0, 0); } while (0)
; #define PG8_LDA(dst, b, h) do { _Pragma("unroll") for (int m = 0; m < 4; ++m) _Pragma("unroll") for (int k = 0; k < 2; ++k) dst[m][k] = *(const PG8_LAS bf16x8*)(lds + PG8_SA(b, h) + aoff + m * 2048 + k * 1024); } while (0)
; #define PG8_LDB(dst, b, h) do { _Pragma("unroll") for (int n = 0; n < 2; ++n) _Pragma("unroll") for (int k = 0; k < 2; ++k) dst[n][k] = *(const PG8_LAS bf16x8*)(lds + PG8_SB(b, h) + boff + n * 2048 + k * 1024); } while (0)
; #define PG8_MMA(ai, bj, At, Bt) do { __builtin_amdgcn_s_setprio(1); _Pragma("unroll") for (int m = 0; m < 4; ++m) _Pragma("unroll") for (int n = 0; n < 2; ++n) _Pragma("unroll") for (int k = 0; k < 2; ++k) \
;         acc[ai][bj][m][n] = __builtin_amdgcn_mfma_f32_16x16x32_bf16(Bt[n][k], At[m][k], acc[ai][bj][m][n], 0, 0, 0); __builtin_amdgcn_s_setprio(0); } while (0)
; template <class Epi, class Sched, bool ALIGN_EPI = false, bool SP2 = false>
; __device__ __forceinline__ void gemm_phase(PG8_LAS unsigned char* lds, const Gemm g, const Sched& S, const Epi& E) {
;     ...
;             PG8_LDB(B0, 0, 0); PG8_LDB(B1, 0, 1); PG8_SCHED; PG8_LDA(At, 0, 0); PG8_STAGE(PG8_SA(1, 1), a1 + hA, voffA);
;             PG8_WAIT_V(8); PG8_WAIT_L(0); PG8_BAR; PG8_MMA(0, 0, At, B0); PG8_MMA(0, 1, At, B1); PG8_BAR; PG8_SCHED;
;             PG8_LDA(At, 0, 1); PG8_STAGE(PG8_SB(0, 0), b2, voffB); PG8_STAGE(PG8_SB(0, 1), b2 + hB, voffB); PG8_STAGE(PG8_SA(0, 0), a2, voffA);
;             PG8_WAIT_V(8); PG8_WAIT_L(0); PG8_BAR; PG8_MMA(1, 0, At, B0); PG8_MMA(1, 1, At, B1); PG8_BAR; PG8_SCHED;
;             PG8_LDB(B0, 1, 0); PG8_LDB(B1, 1, 1); PG8_SCHED; PG8_LDA(At, 1, 0); PG8_STAGE(PG8_SA(0, 1), a2 + hA, voffA);
;             PG8_WAIT_V(8); PG8_WAIT_L(0); PG8_BAR; PG8_MMA(0, 0, At, B0); PG8_MMA(0, 1, At, B1); PG8_BAR; PG8_SCHED;
;             PG8_LDA(At, 1, 1); PG8_STAGE(PG8_SB(1, 0), b3, voffB); PG8_STAGE(PG8_SB(1, 1), b3 + hB, voffB); PG8_STAGE(PG8_SA(1, 0), a3, voffA);
;             PG8_WAIT_V(8); PG8_WAIT_L(0); PG8_BAR; PG8_MMA(1, 0, At, B0); PG8_MMA(1, 1, At, B1); PG8_BAR; PG8_SCHED;
;     ...
;         if constexpr (ALIGN_EPI) { if (wr == 0) PG8_BAR; }
	s_waitcnt lgkmcnt(0)
	v_mfma_f32_16x16x32_bf16 v[126:129], v[130:133], v[178:181], v[126:129]
	v_mfma_f32_16x16x32_bf16 v[122:125], v[138:141], v[178:181], v[122:125]
	v_mfma_f32_16x16x32_bf16 v[110:113], v[130:133], v[194:197], v[110:113]
	v_mfma_f32_16x16x32_bf16 v[106:109], v[138:141], v[194:197], v[106:109]
	v_mfma_f32_16x16x32_bf16 v[94:97], v[130:133], v[202:205], v[94:97]
	v_mfma_f32_16x16x32_bf16 v[90:93], v[138:141], v[202:205], v[90:93]
	v_mfma_f32_16x16x32_bf16 v[78:81], v[130:133], v[210:213], v[78:81]
	v_mfma_f32_16x16x32_bf16 v[74:77], v[138:141], v[210:213], v[74:77]
	v_mfma_f32_16x16x32_bf16 v[126:129], v[134:137], v[182:185], v[126:129]
	v_mfma_f32_16x16x32_bf16 v[122:125], v[142:145], v[182:185], v[122:125]
	v_mfma_f32_16x16x32_bf16 v[110:113], v[134:137], v[198:201], v[110:113]
	v_mfma_f32_16x16x32_bf16 v[106:109], v[142:145], v[198:201], v[106:109]
	v_mfma_f32_16x16x32_bf16 v[94:97], v[134:137], v[206:209], v[94:97]
	v_mfma_f32_16x16x32_bf16 v[90:93], v[142:145], v[206:209], v[90:93]
	v_mfma_f32_16x16x32_bf16 v[78:81], v[134:137], v[214:217], v[78:81]
	v_mfma_f32_16x16x32_bf16 v[74:77], v[142:145], v[214:217], v[74:77]
	v_mfma_f32_16x16x32_bf16 v[118:121], v[146:149], v[178:181], v[118:121]
	v_mfma_f32_16x16x32_bf16 v[114:117], v[170:173], v[178:181], v[114:117]
	v_mfma_f32_16x16x32_bf16 v[102:105], v[146:149], v[194:197], v[102:105]
	v_mfma_f32_16x16x32_bf16 v[98:101], v[170:173], v[194:197], v[98:101]
	v_mfma_f32_16x16x32_bf16 v[86:89], v[146:149], v[202:205], v[86:89]
	v_mfma_f32_16x16x32_bf16 v[82:85], v[170:173], v[202:205], v[82:85]
	v_mfma_f32_16x16x32_bf16 v[70:73], v[146:149], v[210:213], v[70:73]
	v_mfma_f32_16x16x32_bf16 v[66:69], v[170:173], v[210:213], v[66:69]
	v_mfma_f32_16x16x32_bf16 v[118:121], v[150:153], v[182:185], v[118:121]
	v_mfma_f32_16x16x32_bf16 v[114:117], v[174:177], v[182:185], v[114:117]
	v_mfma_f32_16x16x32_bf16 v[102:105], v[150:153], v[198:201], v[102:105]
	v_mfma_f32_16x16x32_bf16 v[98:101], v[174:177], v[198:201], v[98:101]
	v_mfma_f32_16x16x32_bf16 v[86:89], v[150:153], v[206:209], v[86:89]
	v_mfma_f32_16x16x32_bf16 v[82:85], v[174:177], v[206:209], v[82:85]
	v_mfma_f32_16x16x32_bf16 v[70:73], v[150:153], v[214:217], v[70:73]
	v_mfma_f32_16x16x32_bf16 v[66:69], v[174:177], v[214:217], v[66:69]
	s_barrier
	s_add_i32 s18, s18, s45
	s_mov_b32 m0, s18
	ds_read_b128 v[178:181], v192 offset:49152
	ds_read_b128 v[182:185], v192 offset:50176
	ds_read_b128 v[194:197], v192 offset:51200
	ds_read_b128 v[198:201], v192 offset:52224
	ds_read_b128 v[202:205], v192 offset:53248
	ds_read_b128 v[206:209], v192 offset:54272
	ds_read_b128 v[210:213], v192 offset:55296
	ds_read_b128 v[214:217], v192 offset:56320
	global_load_lds_dwordx4 v156, s[76:77]
	s_add_i32 m0, s18, 0x2000
	s_add_u32 s24, s38, 0x160080
	s_addc_u32 s25, s39, 0
	s_add_i32 s18, s19, s45
	global_load_lds_dwordx4 v160, s[76:77]
	s_mov_b32 m0, s18
	s_nop 0
	global_load_lds_dwordx4 v156, s[24:25]
	s_add_i32 m0, s18, 0x2000
	s_nop 0
	global_load_lds_dwordx4 v160, s[24:25]
	s_mov_b32 m0, s52
	s_nop 0
	global_load_lds_dwordx4 v154, s[78:79]
	s_mov_b32 m0, s53
	s_nop 0
	global_load_lds_dwordx4 v158, s[78:79]
	global_load_dword v247, v[248:249], off
	v_lshl_add_u64 v[248:249], v[248:249], 0, s[80:81]
	s_waitcnt vmcnt(10)
	s_waitcnt lgkmcnt(0)
	s_barrier
	s_waitcnt lgkmcnt(0)
	v_mfma_f32_16x16x32_bf16 v[62:65], v[130:133], v[178:181], v[62:65]
	v_mfma_f32_16x16x32_bf16 v[58:61], v[138:141], v[178:181], v[58:61]
	v_mfma_f32_16x16x32_bf16 v[46:49], v[130:133], v[194:197], v[46:49]
	v_mfma_f32_16x16x32_bf16 v[42:45], v[138:141], v[194:197], v[42:45]
	v_mfma_f32_16x16x32_bf16 v[30:33], v[130:133], v[202:205], v[30:33]
	v_mfma_f32_16x16x32_bf16 v[26:29], v[138:141], v[202:205], v[26:29]
	v_mfma_f32_16x16x32_bf16 v[14:17], v[130:133], v[210:213], v[14:17]
	v_mfma_f32_16x16x32_bf16 v[10:13], v[138:141], v[210:213], v[10:13]
	v_mfma_f32_16x16x32_bf16 v[62:65], v[134:137], v[182:185], v[62:65]
	v_mfma_f32_16x16x32_bf16 v[58:61], v[142:145], v[182:185], v[58:61]
	v_mfma_f32_16x16x32_bf16 v[46:49], v[134:137], v[198:201], v[46:49]
	v_mfma_f32_16x16x32_bf16 v[42:45], v[142:145], v[198:201], v[42:45]
	v_mfma_f32_16x16x32_bf16 v[30:33], v[134:137], v[206:209], v[30:33]
	v_mfma_f32_16x16x32_bf16 v[26:29], v[142:145], v[206:209], v[26:29]
	v_mfma_f32_16x16x32_bf16 v[14:17], v[134:137], v[214:217], v[14:17]
	v_mfma_f32_16x16x32_bf16 v[10:13], v[142:145], v[214:217], v[10:13]
	v_mfma_f32_16x16x32_bf16 v[54:57], v[146:149], v[178:181], v[54:57]
	v_mfma_f32_16x16x32_bf16 v[50:53], v[170:173], v[178:181], v[50:53]
	v_mfma_f32_16x16x32_bf16 v[38:41], v[146:149], v[194:197], v[38:41]
	v_mfma_f32_16x16x32_bf16 v[34:37], v[170:173], v[194:197], v[34:37]
	v_mfma_f32_16x16x32_bf16 v[22:25], v[146:149], v[202:205], v[22:25]
	v_mfma_f32_16x16x32_bf16 v[18:21], v[170:173], v[202:205], v[18:21]
	v_mfma_f32_16x16x32_bf16 v[6:9], v[146:149], v[210:213], v[6:9]
	v_mfma_f32_16x16x32_bf16 v[2:5], v[170:173], v[210:213], v[2:5]
	v_mfma_f32_16x16x32_bf16 v[54:57], v[150:153], v[182:185], v[54:57]
	v_mfma_f32_16x16x32_bf16 v[50:53], v[174:177], v[182:185], v[50:53]
	v_mfma_f32_16x16x32_bf16 v[38:41], v[150:153], v[198:201], v[38:41]
	v_mfma_f32_16x16x32_bf16 v[34:37], v[174:177], v[198:201], v[34:37]
	v_mfma_f32_16x16x32_bf16 v[22:25], v[150:153], v[206:209], v[22:25]
	v_mfma_f32_16x16x32_bf16 v[18:21], v[174:177], v[206:209], v[18:21]
	v_mfma_f32_16x16x32_bf16 v[6:9], v[150:153], v[214:217], v[6:9]
	v_mfma_f32_16x16x32_bf16 v[2:5], v[174:177], v[214:217], v[2:5]
	s_barrier
	s_add_i32 s63, s63, 2
	s_add_u32 s61, s61, 0x100
	s_addc_u32 s62, s62, 0
	s_cmpk_gt_u32 s63, 0x55
	s_mov_b64 s[24:25], s[36:37]
	s_cbranch_scc0 .LBB0_1127
	s_and_b64 vcc, exec, s[20:21]
	s_cbranch_vccz .LBB0_1130
	s_barrier
